# ResProb<false> epilogues (P10s,P12 + sample): 16 residual loads issued up front, global saddr, counted waits, batched SS atomics
# speedup vs baseline: 1.0019x; 1.0019x over previous
.LBB0_1483:
	ds_read_b128 v[146:149], v152
	ds_read_b128 v[156:159], v152 offset:1024
	ds_read_b128 v[160:163], v152 offset:2048
	ds_read_b128 v[164:167], v152 offset:3072
	ds_read_b128 v[168:171], v153
	ds_read_b128 v[172:175], v153 offset:1024
	ds_read_b128 v[176:179], v153 offset:2048
	ds_read_b128 v[180:183], v153 offset:3072
	s_add_u32 s38, s10, 0xfffc0080
	s_addc_u32 s39, s11, -1
	s_cmp_eq_u32 s66, 12
	s_cselect_b32 s41, s25, s39
	s_cselect_b32 s40, s27, s38
	s_cselect_b32 s39, s29, s65
	s_cselect_b32 s38, s28, s64
	v_lshl_add_u64 v[184:185], s[10:11], 0, v[140:141]
	s_add_i32 m0, s35, 0xc000
	ds_read_b128 v[188:191], v154
	ds_read_b128 v[192:195], v154 offset:1024
	ds_read_b128 v[196:199], v154 offset:2048
	ds_read_b128 v[200:203], v154 offset:3072
	ds_read_b128 v[204:207], v154 offset:4096
	ds_read_b128 v[208:211], v154 offset:5120
	ds_read_b128 v[212:215], v154 offset:6144
	ds_read_b128 v[216:219], v154 offset:7168
	global_load_lds_dwordx4 v[184:185], off
	v_lshl_add_u64 v[184:185], s[10:11], 0, v[138:139]
	s_add_i32 m0, s35, 0xe000
	s_nop 0
	global_load_lds_dwordx4 v[184:185], off
	s_waitcnt vmcnt(8)
	s_waitcnt lgkmcnt(0)
	s_barrier
	s_setprio 1
	s_waitcnt lgkmcnt(0)
	v_mfma_f32_16x16x32_bf16 v[126:129], v[146:149], v[188:191], v[126:129]
	v_mfma_f32_16x16x32_bf16 v[122:125], v[160:163], v[188:191], v[122:125]
	v_mfma_f32_16x16x32_bf16 v[110:113], v[146:149], v[196:199], v[110:113]
	v_mfma_f32_16x16x32_bf16 v[106:109], v[160:163], v[196:199], v[106:109]
	v_mfma_f32_16x16x32_bf16 v[94:97], v[146:149], v[204:207], v[94:97]
	v_mfma_f32_16x16x32_bf16 v[90:93], v[160:163], v[204:207], v[90:93]
	v_mfma_f32_16x16x32_bf16 v[78:81], v[146:149], v[212:215], v[78:81]
	v_mfma_f32_16x16x32_bf16 v[74:77], v[160:163], v[212:215], v[74:77]
	v_mfma_f32_16x16x32_bf16 v[126:129], v[156:159], v[192:195], v[126:129]
	v_mfma_f32_16x16x32_bf16 v[122:125], v[164:167], v[192:195], v[122:125]
	v_mfma_f32_16x16x32_bf16 v[110:113], v[156:159], v[200:203], v[110:113]
	v_mfma_f32_16x16x32_bf16 v[106:109], v[164:167], v[200:203], v[106:109]
	v_mfma_f32_16x16x32_bf16 v[94:97], v[156:159], v[208:211], v[94:97]
	v_mfma_f32_16x16x32_bf16 v[90:93], v[164:167], v[208:211], v[90:93]
	v_mfma_f32_16x16x32_bf16 v[78:81], v[156:159], v[216:219], v[78:81]
	v_mfma_f32_16x16x32_bf16 v[74:77], v[164:167], v[216:219], v[74:77]
	s_setprio 0
	s_setprio 1
	v_mfma_f32_16x16x32_bf16 v[118:121], v[168:171], v[188:191], v[118:121]
	v_mfma_f32_16x16x32_bf16 v[114:117], v[176:179], v[188:191], v[114:117]
	v_mfma_f32_16x16x32_bf16 v[102:105], v[168:171], v[196:199], v[102:105]
	v_mfma_f32_16x16x32_bf16 v[98:101], v[176:179], v[196:199], v[98:101]
	v_mfma_f32_16x16x32_bf16 v[86:89], v[168:171], v[204:207], v[86:89]
	v_mfma_f32_16x16x32_bf16 v[82:85], v[176:179], v[204:207], v[82:85]
	v_mfma_f32_16x16x32_bf16 v[70:73], v[168:171], v[212:215], v[70:73]
	v_mfma_f32_16x16x32_bf16 v[66:69], v[176:179], v[212:215], v[66:69]
	v_mfma_f32_16x16x32_bf16 v[118:121], v[172:175], v[192:195], v[118:121]
	v_mfma_f32_16x16x32_bf16 v[114:117], v[180:183], v[192:195], v[114:117]
	v_mfma_f32_16x16x32_bf16 v[102:105], v[172:175], v[200:203], v[102:105]
	v_mfma_f32_16x16x32_bf16 v[98:101], v[180:183], v[200:203], v[98:101]
	v_mfma_f32_16x16x32_bf16 v[86:89], v[172:175], v[208:211], v[86:89]
	v_mfma_f32_16x16x32_bf16 v[82:85], v[180:183], v[208:211], v[82:85]
	v_mfma_f32_16x16x32_bf16 v[70:73], v[172:175], v[216:219], v[70:73]
	v_mfma_f32_16x16x32_bf16 v[66:69], v[180:183], v[216:219], v[66:69]
	s_setprio 0
	s_barrier
	s_add_i32 s67, s62, s45
	v_lshl_add_u64 v[184:185], s[38:39], 0, v[132:133]
	s_mov_b32 m0, s67
	ds_read_b128 v[188:191], v154 offset:16384
	ds_read_b128 v[192:195], v154 offset:17408
	ds_read_b128 v[196:199], v154 offset:18432
	ds_read_b128 v[200:203], v154 offset:19456
	ds_read_b128 v[204:207], v154 offset:20480
	ds_read_b128 v[208:211], v154 offset:21504
	ds_read_b128 v[212:215], v154 offset:22528
	ds_read_b128 v[216:219], v154 offset:23552
	global_load_lds_dwordx4 v[184:185], off
	s_add_i32 m0, s67, 0x2000
	s_add_u32 s68, s38, 0x40000
	v_lshl_add_u64 v[220:221], s[38:39], 0, v[136:137]
	s_addc_u32 s69, s39, 0
	s_add_i32 s67, s63, s45
	global_load_lds_dwordx4 v[220:221], off
	v_lshl_add_u64 v[222:223], s[68:69], 0, v[132:133]
	s_mov_b32 m0, s67
	v_lshl_add_u64 v[224:225], s[40:41], 0, v[134:135]
	global_load_lds_dwordx4 v[222:223], off
	v_lshl_add_u64 v[222:223], s[68:69], 0, v[136:137]
	s_add_i32 m0, s67, 0x2000
	s_nop 0
	global_load_lds_dwordx4 v[222:223], off
	v_lshl_add_u64 v[222:223], s[40:41], 0, v[130:131]
	s_mov_b32 m0, s35
	s_nop 0
	global_load_lds_dwordx4 v[222:223], off
	s_mov_b32 m0, s37
	s_nop 0
	global_load_lds_dwordx4 v[224:225], off
	s_waitcnt vmcnt(8)
	s_waitcnt lgkmcnt(0)
	s_barrier
	s_setprio 1
	s_waitcnt lgkmcnt(0)
	v_mfma_f32_16x16x32_bf16 v[62:65], v[146:149], v[188:191], v[62:65]
	v_mfma_f32_16x16x32_bf16 v[58:61], v[160:163], v[188:191], v[58:61]
	v_mfma_f32_16x16x32_bf16 v[46:49], v[146:149], v[196:199], v[46:49]
	v_mfma_f32_16x16x32_bf16 v[42:45], v[160:163], v[196:199], v[42:45]
	v_mfma_f32_16x16x32_bf16 v[30:33], v[146:149], v[204:207], v[30:33]
	v_mfma_f32_16x16x32_bf16 v[26:29], v[160:163], v[204:207], v[26:29]
	v_mfma_f32_16x16x32_bf16 v[14:17], v[146:149], v[212:215], v[14:17]
	v_mfma_f32_16x16x32_bf16 v[10:13], v[160:163], v[212:215], v[10:13]
	v_mfma_f32_16x16x32_bf16 v[62:65], v[156:159], v[192:195], v[62:65]
	v_mfma_f32_16x16x32_bf16 v[58:61], v[164:167], v[192:195], v[58:61]
	v_mfma_f32_16x16x32_bf16 v[46:49], v[156:159], v[200:203], v[46:49]
	v_mfma_f32_16x16x32_bf16 v[42:45], v[164:167], v[200:203], v[42:45]
	v_mfma_f32_16x16x32_bf16 v[30:33], v[156:159], v[208:211], v[30:33]
	v_mfma_f32_16x16x32_bf16 v[26:29], v[164:167], v[208:211], v[26:29]
	v_mfma_f32_16x16x32_bf16 v[14:17], v[156:159], v[216:219], v[14:17]
	v_mfma_f32_16x16x32_bf16 v[10:13], v[164:167], v[216:219], v[10:13]
	s_setprio 0
	s_setprio 1
	v_mfma_f32_16x16x32_bf16 v[54:57], v[168:171], v[188:191], v[54:57]
	v_mfma_f32_16x16x32_bf16 v[50:53], v[176:179], v[188:191], v[50:53]
	v_mfma_f32_16x16x32_bf16 v[38:41], v[168:171], v[196:199], v[38:41]
	v_mfma_f32_16x16x32_bf16 v[34:37], v[176:179], v[196:199], v[34:37]
	v_mfma_f32_16x16x32_bf16 v[22:25], v[168:171], v[204:207], v[22:25]
	v_mfma_f32_16x16x32_bf16 v[18:21], v[176:179], v[204:207], v[18:21]
	v_mfma_f32_16x16x32_bf16 v[6:9], v[168:171], v[212:215], v[6:9]
	v_mfma_f32_16x16x32_bf16 v[2:5], v[176:179], v[212:215], v[2:5]
	v_mfma_f32_16x16x32_bf16 v[54:57], v[172:175], v[192:195], v[54:57]
	v_mfma_f32_16x16x32_bf16 v[50:53], v[180:183], v[192:195], v[50:53]
	v_mfma_f32_16x16x32_bf16 v[38:41], v[172:175], v[200:203], v[38:41]
	v_mfma_f32_16x16x32_bf16 v[34:37], v[180:183], v[200:203], v[34:37]
	v_mfma_f32_16x16x32_bf16 v[22:25], v[172:175], v[208:211], v[22:25]
	v_mfma_f32_16x16x32_bf16 v[18:21], v[180:183], v[208:211], v[18:21]
	v_mfma_f32_16x16x32_bf16 v[6:9], v[172:175], v[216:219], v[6:9]
	v_mfma_f32_16x16x32_bf16 v[2:5], v[180:183], v[216:219], v[2:5]
	s_setprio 0
	s_barrier
	s_add_i32 s67, 0, 0x18000
	s_add_i32 s68, 0, 0x1c000
	v_add_u32_e32 v164, s67, v150
	v_add_u32_e32 v180, s68, v150
	ds_read_b128 v[146:149], v164
	ds_read_b128 v[156:159], v164 offset:1024
	ds_read_b128 v[160:163], v164 offset:2048
	ds_read_b128 v[164:167], v164 offset:3072
	ds_read_b128 v[168:171], v180
	ds_read_b128 v[172:175], v180 offset:1024
	ds_read_b128 v[176:179], v180 offset:2048
	ds_read_b128 v[180:183], v180 offset:3072
	s_add_u32 s40, s40, 0x40000
	s_addc_u32 s41, s41, 0
	s_mov_b32 m0, s46
	v_lshl_add_u64 v[226:227], s[40:41], 0, v[130:131]
	ds_read_b128 v[188:191], v154 offset:32768
	ds_read_b128 v[192:195], v154 offset:33792
	ds_read_b128 v[196:199], v154 offset:34816
	ds_read_b128 v[200:203], v154 offset:35840
	ds_read_b128 v[204:207], v154 offset:36864
	ds_read_b128 v[208:211], v154 offset:37888
	ds_read_b128 v[212:215], v154 offset:38912
	ds_read_b128 v[216:219], v154 offset:39936
	global_load_lds_dwordx4 v[226:227], off
	v_lshl_add_u64 v[226:227], s[40:41], 0, v[134:135]
	s_mov_b32 m0, s47
	s_nop 0
	global_load_lds_dwordx4 v[226:227], off
	s_waitcnt vmcnt(8)
	s_waitcnt lgkmcnt(0)
	s_barrier
	s_setprio 1
	s_waitcnt lgkmcnt(0)
	v_mfma_f32_16x16x32_bf16 v[126:129], v[146:149], v[188:191], v[126:129]
	v_mfma_f32_16x16x32_bf16 v[122:125], v[160:163], v[188:191], v[122:125]
	v_mfma_f32_16x16x32_bf16 v[110:113], v[146:149], v[196:199], v[110:113]
	v_mfma_f32_16x16x32_bf16 v[106:109], v[160:163], v[196:199], v[106:109]
	v_mfma_f32_16x16x32_bf16 v[94:97], v[146:149], v[204:207], v[94:97]
	v_mfma_f32_16x16x32_bf16 v[90:93], v[160:163], v[204:207], v[90:93]
	v_mfma_f32_16x16x32_bf16 v[78:81], v[146:149], v[212:215], v[78:81]
	v_mfma_f32_16x16x32_bf16 v[74:77], v[160:163], v[212:215], v[74:77]
	v_mfma_f32_16x16x32_bf16 v[126:129], v[156:159], v[192:195], v[126:129]
	v_mfma_f32_16x16x32_bf16 v[122:125], v[164:167], v[192:195], v[122:125]
	v_mfma_f32_16x16x32_bf16 v[110:113], v[156:159], v[200:203], v[110:113]
	v_mfma_f32_16x16x32_bf16 v[106:109], v[164:167], v[200:203], v[106:109]
	v_mfma_f32_16x16x32_bf16 v[94:97], v[156:159], v[208:211], v[94:97]
	v_mfma_f32_16x16x32_bf16 v[90:93], v[164:167], v[208:211], v[90:93]
	v_mfma_f32_16x16x32_bf16 v[78:81], v[156:159], v[216:219], v[78:81]
	v_mfma_f32_16x16x32_bf16 v[74:77], v[164:167], v[216:219], v[74:77]
	s_setprio 0
	s_setprio 1
	v_mfma_f32_16x16x32_bf16 v[118:121], v[168:171], v[188:191], v[118:121]
	v_mfma_f32_16x16x32_bf16 v[114:117], v[176:179], v[188:191], v[114:117]
	v_mfma_f32_16x16x32_bf16 v[102:105], v[168:171], v[196:199], v[102:105]
	v_mfma_f32_16x16x32_bf16 v[98:101], v[176:179], v[196:199], v[98:101]
	v_mfma_f32_16x16x32_bf16 v[86:89], v[168:171], v[204:207], v[86:89]
	v_mfma_f32_16x16x32_bf16 v[82:85], v[176:179], v[204:207], v[82:85]
	v_mfma_f32_16x16x32_bf16 v[70:73], v[168:171], v[212:215], v[70:73]
	v_mfma_f32_16x16x32_bf16 v[66:69], v[176:179], v[212:215], v[66:69]
	v_mfma_f32_16x16x32_bf16 v[118:121], v[172:175], v[192:195], v[118:121]
	v_mfma_f32_16x16x32_bf16 v[114:117], v[180:183], v[192:195], v[114:117]
	v_mfma_f32_16x16x32_bf16 v[102:105], v[172:175], v[200:203], v[102:105]
	v_mfma_f32_16x16x32_bf16 v[98:101], v[180:183], v[200:203], v[98:101]
	v_mfma_f32_16x16x32_bf16 v[86:89], v[172:175], v[208:211], v[86:89]
	v_mfma_f32_16x16x32_bf16 v[82:85], v[180:183], v[208:211], v[82:85]
	v_mfma_f32_16x16x32_bf16 v[70:73], v[172:175], v[216:219], v[70:73]
	v_mfma_f32_16x16x32_bf16 v[66:69], v[180:183], v[216:219], v[66:69]
	s_setprio 0
	s_barrier
	s_add_i32 s40, s67, s45
	v_lshl_add_u64 v[184:185], v[184:185], 0, s[20:21]
	s_mov_b32 m0, s40
	ds_read_b128 v[188:191], v154 offset:49152
	ds_read_b128 v[192:195], v154 offset:50176
	ds_read_b128 v[196:199], v154 offset:51200
	ds_read_b128 v[200:203], v154 offset:52224
	ds_read_b128 v[204:207], v154 offset:53248
	ds_read_b128 v[208:211], v154 offset:54272
	ds_read_b128 v[212:215], v154 offset:55296
	ds_read_b128 v[216:219], v154 offset:56320
	global_load_lds_dwordx4 v[184:185], off
	s_add_i32 m0, s40, 0x2000
	s_add_u32 s38, s38, 0x40080
	v_lshl_add_u64 v[184:185], v[220:221], 0, s[20:21]
	s_addc_u32 s39, s39, 0
	s_add_i32 s40, s68, s45
	global_load_lds_dwordx4 v[184:185], off
	v_lshl_add_u64 v[184:185], s[38:39], 0, v[132:133]
	s_mov_b32 m0, s40
	s_nop 0
	global_load_lds_dwordx4 v[184:185], off
	v_lshl_add_u64 v[184:185], s[38:39], 0, v[136:137]
	s_add_i32 m0, s40, 0x2000
	s_nop 0
	global_load_lds_dwordx4 v[184:185], off
	v_lshl_add_u64 v[184:185], v[222:223], 0, s[20:21]
	s_mov_b32 m0, s57
	s_nop 0
	global_load_lds_dwordx4 v[184:185], off
	v_lshl_add_u64 v[184:185], v[224:225], 0, s[20:21]
	s_mov_b32 m0, s60
	s_nop 0
	global_load_lds_dwordx4 v[184:185], off
	s_waitcnt vmcnt(8)
	s_waitcnt lgkmcnt(0)
	s_barrier
	s_setprio 1
	s_waitcnt lgkmcnt(0)
	v_mfma_f32_16x16x32_bf16 v[62:65], v[146:149], v[188:191], v[62:65]
	v_mfma_f32_16x16x32_bf16 v[58:61], v[160:163], v[188:191], v[58:61]
	v_mfma_f32_16x16x32_bf16 v[46:49], v[146:149], v[196:199], v[46:49]
	v_mfma_f32_16x16x32_bf16 v[42:45], v[160:163], v[196:199], v[42:45]
	v_mfma_f32_16x16x32_bf16 v[30:33], v[146:149], v[204:207], v[30:33]
	v_mfma_f32_16x16x32_bf16 v[26:29], v[160:163], v[204:207], v[26:29]
	v_mfma_f32_16x16x32_bf16 v[14:17], v[146:149], v[212:215], v[14:17]
	v_mfma_f32_16x16x32_bf16 v[10:13], v[160:163], v[212:215], v[10:13]
	v_mfma_f32_16x16x32_bf16 v[62:65], v[156:159], v[192:195], v[62:65]
	v_mfma_f32_16x16x32_bf16 v[58:61], v[164:167], v[192:195], v[58:61]
	v_mfma_f32_16x16x32_bf16 v[46:49], v[156:159], v[200:203], v[46:49]
	v_mfma_f32_16x16x32_bf16 v[42:45], v[164:167], v[200:203], v[42:45]
	v_mfma_f32_16x16x32_bf16 v[30:33], v[156:159], v[208:211], v[30:33]
	v_mfma_f32_16x16x32_bf16 v[26:29], v[164:167], v[208:211], v[26:29]
	v_mfma_f32_16x16x32_bf16 v[14:17], v[156:159], v[216:219], v[14:17]
	v_mfma_f32_16x16x32_bf16 v[10:13], v[164:167], v[216:219], v[10:13]
	s_setprio 0
	s_setprio 1
	v_mfma_f32_16x16x32_bf16 v[54:57], v[168:171], v[188:191], v[54:57]
	v_mfma_f32_16x16x32_bf16 v[50:53], v[176:179], v[188:191], v[50:53]
	v_mfma_f32_16x16x32_bf16 v[38:41], v[168:171], v[196:199], v[38:41]
	v_mfma_f32_16x16x32_bf16 v[34:37], v[176:179], v[196:199], v[34:37]
	v_mfma_f32_16x16x32_bf16 v[22:25], v[168:171], v[204:207], v[22:25]
	v_mfma_f32_16x16x32_bf16 v[18:21], v[176:179], v[204:207], v[18:21]
	v_mfma_f32_16x16x32_bf16 v[6:9], v[168:171], v[212:215], v[6:9]
	v_mfma_f32_16x16x32_bf16 v[2:5], v[176:179], v[212:215], v[2:5]
	v_mfma_f32_16x16x32_bf16 v[54:57], v[172:175], v[192:195], v[54:57]
	v_mfma_f32_16x16x32_bf16 v[50:53], v[180:183], v[192:195], v[50:53]
	v_mfma_f32_16x16x32_bf16 v[38:41], v[172:175], v[200:203], v[38:41]
	v_mfma_f32_16x16x32_bf16 v[34:37], v[180:183], v[200:203], v[34:37]
	v_mfma_f32_16x16x32_bf16 v[22:25], v[172:175], v[208:211], v[22:25]
	v_mfma_f32_16x16x32_bf16 v[18:21], v[180:183], v[208:211], v[18:21]
	v_mfma_f32_16x16x32_bf16 v[6:9], v[172:175], v[216:219], v[6:9]
	v_mfma_f32_16x16x32_bf16 v[2:5], v[180:183], v[216:219], v[2:5]
	s_setprio 0
	s_barrier
	s_add_i32 s66, s66, 2
	s_add_u32 s64, s64, 0x100
	s_addc_u32 s65, s65, 0
	s_add_u32 s10, s10, 0x100
	s_addc_u32 s11, s11, 0
	s_cmp_gt_u32 s66, 13
	s_cbranch_scc0 .LBB0_1483
	v_lshl_add_u32 v245, s34, 8, v1
	v_lshl_or_b32 v246, s36, 8, v151
	v_lshlrev_b32_e32 v245, 13, v245
	v_lshl_add_u32 v245, v246, 1, v245
	global_load_dwordx4 v[146:149], v245, s[16:17]
	global_load_dwordx4 v[156:159], v245, s[16:17] offset:256
	s_add_u32 s10, s16, 0x20000
	s_addc_u32 s11, s17, 0
	global_load_dwordx4 v[160:163], v245, s[10:11]
	global_load_dwordx4 v[164:167], v245, s[10:11] offset:256
	s_add_u32 s10, s16, 0x40000
	s_addc_u32 s11, s17, 0
	global_load_dwordx4 v[168:171], v245, s[10:11]
	global_load_dwordx4 v[172:175], v245, s[10:11] offset:256
	s_add_u32 s10, s16, 0x60000
	s_addc_u32 s11, s17, 0
	global_load_dwordx4 v[176:179], v245, s[10:11]
	global_load_dwordx4 v[180:183], v245, s[10:11] offset:256
	s_add_u32 s10, s16, 0x100000
	s_addc_u32 s11, s17, 0
	global_load_dwordx4 v[188:191], v245, s[10:11]
	global_load_dwordx4 v[192:195], v245, s[10:11] offset:256
	s_add_u32 s10, s16, 0x120000
	s_addc_u32 s11, s17, 0
	global_load_dwordx4 v[196:199], v245, s[10:11]
	global_load_dwordx4 v[200:203], v245, s[10:11] offset:256
	s_add_u32 s10, s16, 0x140000
	s_addc_u32 s11, s17, 0
	global_load_dwordx4 v[204:207], v245, s[10:11]
	global_load_dwordx4 v[208:211], v245, s[10:11] offset:256
	s_add_u32 s10, s16, 0x160000
	s_addc_u32 s11, s17, 0
	global_load_dwordx4 v[212:215], v245, s[10:11]
	global_load_dwordx4 v[216:219], v245, s[10:11] offset:256
	s_and_b64 vcc, exec, s[22:23]
	s_cbranch_vccz .LBB0_1486
	s_barrier
.LBB0_1486:
	s_waitcnt vmcnt(15)
	v_lshlrev_b32_e32 v246, 16, v146
	v_and_b32_e32 v247, 0xffff0000, v146
	v_pk_add_f32 v[126:127], v[126:127], v[246:247]
	v_lshlrev_b32_e32 v246, 16, v147
	v_and_b32_e32 v247, 0xffff0000, v147
	v_pk_add_f32 v[128:129], v[128:129], v[246:247]
	v_lshlrev_b32_e32 v246, 16, v148
	v_and_b32_e32 v247, 0xffff0000, v148
	v_pk_add_f32 v[122:123], v[122:123], v[246:247]
	v_lshlrev_b32_e32 v246, 16, v149
	v_and_b32_e32 v247, 0xffff0000, v149
	v_pk_add_f32 v[124:125], v[124:125], v[246:247]
	v_cvt_pk_bf16_f32 v146, v126, v127
	v_cvt_pk_bf16_f32 v147, v128, v129
	v_cvt_pk_bf16_f32 v148, v122, v123
	v_cvt_pk_bf16_f32 v149, v124, v125
	global_store_dwordx4 v245, v[146:149], s[16:17]
	v_mul_f32_e32 v126, v126, v126
	v_fmac_f32_e32 v126, v127, v127
	v_fmac_f32_e32 v126, v128, v128
	v_fmac_f32_e32 v126, v129, v129
	v_fmac_f32_e32 v126, v122, v122
	v_fmac_f32_e32 v126, v123, v123
	v_fmac_f32_e32 v126, v124, v124
	v_fmac_f32_e32 v126, v125, v125
	s_waitcnt vmcnt(15)
	v_lshlrev_b32_e32 v246, 16, v156
	v_and_b32_e32 v247, 0xffff0000, v156
	v_pk_add_f32 v[118:119], v[118:119], v[246:247]
	v_lshlrev_b32_e32 v246, 16, v157
	v_and_b32_e32 v247, 0xffff0000, v157
	v_pk_add_f32 v[120:121], v[120:121], v[246:247]
	v_lshlrev_b32_e32 v246, 16, v158
	v_and_b32_e32 v247, 0xffff0000, v158
	v_pk_add_f32 v[114:115], v[114:115], v[246:247]
	v_lshlrev_b32_e32 v246, 16, v159
	v_and_b32_e32 v247, 0xffff0000, v159
	v_pk_add_f32 v[116:117], v[116:117], v[246:247]
	v_cvt_pk_bf16_f32 v156, v118, v119
	v_cvt_pk_bf16_f32 v157, v120, v121
	v_cvt_pk_bf16_f32 v158, v114, v115
	v_cvt_pk_bf16_f32 v159, v116, v117
	global_store_dwordx4 v245, v[156:159], s[16:17] offset:256
	v_fmac_f32_e32 v126, v118, v118
	v_fmac_f32_e32 v126, v119, v119
	v_fmac_f32_e32 v126, v120, v120
	v_fmac_f32_e32 v126, v121, v121
	v_fmac_f32_e32 v126, v114, v114
	v_fmac_f32_e32 v126, v115, v115
	v_fmac_f32_e32 v126, v116, v116
	v_fmac_f32_e32 v126, v117, v117
	s_add_u32 s10, s16, 0x20000
	s_addc_u32 s11, s17, 0
	s_waitcnt vmcnt(15)
	v_lshlrev_b32_e32 v246, 16, v160
	v_and_b32_e32 v247, 0xffff0000, v160
	v_pk_add_f32 v[110:111], v[110:111], v[246:247]
	v_lshlrev_b32_e32 v246, 16, v161
	v_and_b32_e32 v247, 0xffff0000, v161
	v_pk_add_f32 v[112:113], v[112:113], v[246:247]
	v_lshlrev_b32_e32 v246, 16, v162
	v_and_b32_e32 v247, 0xffff0000, v162
	v_pk_add_f32 v[106:107], v[106:107], v[246:247]
	v_lshlrev_b32_e32 v246, 16, v163
	v_and_b32_e32 v247, 0xffff0000, v163
	v_pk_add_f32 v[108:109], v[108:109], v[246:247]
	v_cvt_pk_bf16_f32 v160, v110, v111
	v_cvt_pk_bf16_f32 v161, v112, v113
	v_cvt_pk_bf16_f32 v162, v106, v107
	v_cvt_pk_bf16_f32 v163, v108, v109
	global_store_dwordx4 v245, v[160:163], s[10:11]
	v_mul_f32_e32 v110, v110, v110
	v_fmac_f32_e32 v110, v111, v111
	v_fmac_f32_e32 v110, v112, v112
	v_fmac_f32_e32 v110, v113, v113
	v_fmac_f32_e32 v110, v106, v106
	v_fmac_f32_e32 v110, v107, v107
	v_fmac_f32_e32 v110, v108, v108
	v_fmac_f32_e32 v110, v109, v109
	s_waitcnt vmcnt(15)
	v_lshlrev_b32_e32 v246, 16, v164
	v_and_b32_e32 v247, 0xffff0000, v164
	v_pk_add_f32 v[102:103], v[102:103], v[246:247]
	v_lshlrev_b32_e32 v246, 16, v165
	v_and_b32_e32 v247, 0xffff0000, v165
	v_pk_add_f32 v[104:105], v[104:105], v[246:247]
	v_lshlrev_b32_e32 v246, 16, v166
	v_and_b32_e32 v247, 0xffff0000, v166
	v_pk_add_f32 v[98:99], v[98:99], v[246:247]
	v_lshlrev_b32_e32 v246, 16, v167
	v_and_b32_e32 v247, 0xffff0000, v167
	v_pk_add_f32 v[100:101], v[100:101], v[246:247]
	v_cvt_pk_bf16_f32 v164, v102, v103
	v_cvt_pk_bf16_f32 v165, v104, v105
	v_cvt_pk_bf16_f32 v166, v98, v99
	v_cvt_pk_bf16_f32 v167, v100, v101
	global_store_dwordx4 v245, v[164:167], s[10:11] offset:256
	v_fmac_f32_e32 v110, v102, v102
	v_fmac_f32_e32 v110, v103, v103
	v_fmac_f32_e32 v110, v104, v104
	v_fmac_f32_e32 v110, v105, v105
	v_fmac_f32_e32 v110, v98, v98
	v_fmac_f32_e32 v110, v99, v99
	v_fmac_f32_e32 v110, v100, v100
	v_fmac_f32_e32 v110, v101, v101
	s_add_u32 s10, s16, 0x40000
	s_addc_u32 s11, s17, 0
	s_waitcnt vmcnt(15)
	v_lshlrev_b32_e32 v246, 16, v168
	v_and_b32_e32 v247, 0xffff0000, v168
	v_pk_add_f32 v[94:95], v[94:95], v[246:247]
	v_lshlrev_b32_e32 v246, 16, v169
	v_and_b32_e32 v247, 0xffff0000, v169
	v_pk_add_f32 v[96:97], v[96:97], v[246:247]
	v_lshlrev_b32_e32 v246, 16, v170
	v_and_b32_e32 v247, 0xffff0000, v170
	v_pk_add_f32 v[90:91], v[90:91], v[246:247]
	v_lshlrev_b32_e32 v246, 16, v171
	v_and_b32_e32 v247, 0xffff0000, v171
	v_pk_add_f32 v[92:93], v[92:93], v[246:247]
	v_cvt_pk_bf16_f32 v168, v94, v95
	v_cvt_pk_bf16_f32 v169, v96, v97
	v_cvt_pk_bf16_f32 v170, v90, v91
	v_cvt_pk_bf16_f32 v171, v92, v93
	global_store_dwordx4 v245, v[168:171], s[10:11]
	v_mul_f32_e32 v94, v94, v94
	v_fmac_f32_e32 v94, v95, v95
	v_fmac_f32_e32 v94, v96, v96
	v_fmac_f32_e32 v94, v97, v97
	v_fmac_f32_e32 v94, v90, v90
	v_fmac_f32_e32 v94, v91, v91
	v_fmac_f32_e32 v94, v92, v92
	v_fmac_f32_e32 v94, v93, v93
	s_waitcnt vmcnt(15)
	v_lshlrev_b32_e32 v246, 16, v172
	v_and_b32_e32 v247, 0xffff0000, v172
	v_pk_add_f32 v[86:87], v[86:87], v[246:247]
	v_lshlrev_b32_e32 v246, 16, v173
	v_and_b32_e32 v247, 0xffff0000, v173
	v_pk_add_f32 v[88:89], v[88:89], v[246:247]
	v_lshlrev_b32_e32 v246, 16, v174
	v_and_b32_e32 v247, 0xffff0000, v174
	v_pk_add_f32 v[82:83], v[82:83], v[246:247]
	v_lshlrev_b32_e32 v246, 16, v175
	v_and_b32_e32 v247, 0xffff0000, v175
	v_pk_add_f32 v[84:85], v[84:85], v[246:247]
	v_cvt_pk_bf16_f32 v172, v86, v87
	v_cvt_pk_bf16_f32 v173, v88, v89
	v_cvt_pk_bf16_f32 v174, v82, v83
	v_cvt_pk_bf16_f32 v175, v84, v85
	global_store_dwordx4 v245, v[172:175], s[10:11] offset:256
	v_fmac_f32_e32 v94, v86, v86
	v_fmac_f32_e32 v94, v87, v87
	v_fmac_f32_e32 v94, v88, v88
	v_fmac_f32_e32 v94, v89, v89
	v_fmac_f32_e32 v94, v82, v82
	v_fmac_f32_e32 v94, v83, v83
	v_fmac_f32_e32 v94, v84, v84
	v_fmac_f32_e32 v94, v85, v85
	s_add_u32 s10, s16, 0x60000
	s_addc_u32 s11, s17, 0
	s_waitcnt vmcnt(15)
	v_lshlrev_b32_e32 v246, 16, v176
	v_and_b32_e32 v247, 0xffff0000, v176
	v_pk_add_f32 v[78:79], v[78:79], v[246:247]
	v_lshlrev_b32_e32 v246, 16, v177
	v_and_b32_e32 v247, 0xffff0000, v177
	v_pk_add_f32 v[80:81], v[80:81], v[246:247]
	v_lshlrev_b32_e32 v246, 16, v178
	v_and_b32_e32 v247, 0xffff0000, v178
	v_pk_add_f32 v[74:75], v[74:75], v[246:247]
	v_lshlrev_b32_e32 v246, 16, v179
	v_and_b32_e32 v247, 0xffff0000, v179
	v_pk_add_f32 v[76:77], v[76:77], v[246:247]
	v_cvt_pk_bf16_f32 v176, v78, v79
	v_cvt_pk_bf16_f32 v177, v80, v81
	v_cvt_pk_bf16_f32 v178, v74, v75
	v_cvt_pk_bf16_f32 v179, v76, v77
	global_store_dwordx4 v245, v[176:179], s[10:11]
	v_mul_f32_e32 v78, v78, v78
	v_fmac_f32_e32 v78, v79, v79
	v_fmac_f32_e32 v78, v80, v80
	v_fmac_f32_e32 v78, v81, v81
	v_fmac_f32_e32 v78, v74, v74
	v_fmac_f32_e32 v78, v75, v75
	v_fmac_f32_e32 v78, v76, v76
	v_fmac_f32_e32 v78, v77, v77
	s_waitcnt vmcnt(15)
	v_lshlrev_b32_e32 v246, 16, v180
	v_and_b32_e32 v247, 0xffff0000, v180
	v_pk_add_f32 v[70:71], v[70:71], v[246:247]
	v_lshlrev_b32_e32 v246, 16, v181
	v_and_b32_e32 v247, 0xffff0000, v181
	v_pk_add_f32 v[72:73], v[72:73], v[246:247]
	v_lshlrev_b32_e32 v246, 16, v182
	v_and_b32_e32 v247, 0xffff0000, v182
	v_pk_add_f32 v[66:67], v[66:67], v[246:247]
	v_lshlrev_b32_e32 v246, 16, v183
	v_and_b32_e32 v247, 0xffff0000, v183
	v_pk_add_f32 v[68:69], v[68:69], v[246:247]
	v_cvt_pk_bf16_f32 v180, v70, v71
	v_cvt_pk_bf16_f32 v181, v72, v73
	v_cvt_pk_bf16_f32 v182, v66, v67
	v_cvt_pk_bf16_f32 v183, v68, v69
	global_store_dwordx4 v245, v[180:183], s[10:11] offset:256
	v_fmac_f32_e32 v78, v70, v70
	v_fmac_f32_e32 v78, v71, v71
	v_fmac_f32_e32 v78, v72, v72
	v_fmac_f32_e32 v78, v73, v73
	v_fmac_f32_e32 v78, v66, v66
	v_fmac_f32_e32 v78, v67, v67
	v_fmac_f32_e32 v78, v68, v68
	v_fmac_f32_e32 v78, v69, v69
	s_add_u32 s10, s16, 0x100000
	s_addc_u32 s11, s17, 0
	s_waitcnt vmcnt(15)
	v_lshlrev_b32_e32 v246, 16, v188
	v_and_b32_e32 v247, 0xffff0000, v188
	v_pk_add_f32 v[62:63], v[62:63], v[246:247]
	v_lshlrev_b32_e32 v246, 16, v189
	v_and_b32_e32 v247, 0xffff0000, v189
	v_pk_add_f32 v[64:65], v[64:65], v[246:247]
	v_lshlrev_b32_e32 v246, 16, v190
	v_and_b32_e32 v247, 0xffff0000, v190
	v_pk_add_f32 v[58:59], v[58:59], v[246:247]
	v_lshlrev_b32_e32 v246, 16, v191
	v_and_b32_e32 v247, 0xffff0000, v191
	v_pk_add_f32 v[60:61], v[60:61], v[246:247]
	v_cvt_pk_bf16_f32 v188, v62, v63
	v_cvt_pk_bf16_f32 v189, v64, v65
	v_cvt_pk_bf16_f32 v190, v58, v59
	v_cvt_pk_bf16_f32 v191, v60, v61
	global_store_dwordx4 v245, v[188:191], s[10:11]
	v_mul_f32_e32 v62, v62, v62
	v_fmac_f32_e32 v62, v63, v63
	v_fmac_f32_e32 v62, v64, v64
	v_fmac_f32_e32 v62, v65, v65
	v_fmac_f32_e32 v62, v58, v58
	v_fmac_f32_e32 v62, v59, v59
	v_fmac_f32_e32 v62, v60, v60
	v_fmac_f32_e32 v62, v61, v61
	s_waitcnt vmcnt(15)
	v_lshlrev_b32_e32 v246, 16, v192
	v_and_b32_e32 v247, 0xffff0000, v192
	v_pk_add_f32 v[54:55], v[54:55], v[246:247]
	v_lshlrev_b32_e32 v246, 16, v193
	v_and_b32_e32 v247, 0xffff0000, v193
	v_pk_add_f32 v[56:57], v[56:57], v[246:247]
	v_lshlrev_b32_e32 v246, 16, v194
	v_and_b32_e32 v247, 0xffff0000, v194
	v_pk_add_f32 v[50:51], v[50:51], v[246:247]
	v_lshlrev_b32_e32 v246, 16, v195
	v_and_b32_e32 v247, 0xffff0000, v195
	v_pk_add_f32 v[52:53], v[52:53], v[246:247]
	v_cvt_pk_bf16_f32 v192, v54, v55
	v_cvt_pk_bf16_f32 v193, v56, v57
	v_cvt_pk_bf16_f32 v194, v50, v51
	v_cvt_pk_bf16_f32 v195, v52, v53
	global_store_dwordx4 v245, v[192:195], s[10:11] offset:256
	v_fmac_f32_e32 v62, v54, v54
	v_fmac_f32_e32 v62, v55, v55
	v_fmac_f32_e32 v62, v56, v56
	v_fmac_f32_e32 v62, v57, v57
	v_fmac_f32_e32 v62, v50, v50
	v_fmac_f32_e32 v62, v51, v51
	v_fmac_f32_e32 v62, v52, v52
	v_fmac_f32_e32 v62, v53, v53
	s_add_u32 s10, s16, 0x120000
	s_addc_u32 s11, s17, 0
	s_waitcnt vmcnt(15)
	v_lshlrev_b32_e32 v246, 16, v196
	v_and_b32_e32 v247, 0xffff0000, v196
	v_pk_add_f32 v[46:47], v[46:47], v[246:247]
	v_lshlrev_b32_e32 v246, 16, v197
	v_and_b32_e32 v247, 0xffff0000, v197
	v_pk_add_f32 v[48:49], v[48:49], v[246:247]
	v_lshlrev_b32_e32 v246, 16, v198
	v_and_b32_e32 v247, 0xffff0000, v198
	v_pk_add_f32 v[42:43], v[42:43], v[246:247]
	v_lshlrev_b32_e32 v246, 16, v199
	v_and_b32_e32 v247, 0xffff0000, v199
	v_pk_add_f32 v[44:45], v[44:45], v[246:247]
	v_cvt_pk_bf16_f32 v196, v46, v47
	v_cvt_pk_bf16_f32 v197, v48, v49
	v_cvt_pk_bf16_f32 v198, v42, v43
	v_cvt_pk_bf16_f32 v199, v44, v45
	global_store_dwordx4 v245, v[196:199], s[10:11]
	v_mul_f32_e32 v46, v46, v46
	v_fmac_f32_e32 v46, v47, v47
	v_fmac_f32_e32 v46, v48, v48
	v_fmac_f32_e32 v46, v49, v49
	v_fmac_f32_e32 v46, v42, v42
	v_fmac_f32_e32 v46, v43, v43
	v_fmac_f32_e32 v46, v44, v44
	v_fmac_f32_e32 v46, v45, v45
	s_waitcnt vmcnt(15)
	v_lshlrev_b32_e32 v246, 16, v200
	v_and_b32_e32 v247, 0xffff0000, v200
	v_pk_add_f32 v[38:39], v[38:39], v[246:247]
	v_lshlrev_b32_e32 v246, 16, v201
	v_and_b32_e32 v247, 0xffff0000, v201
	v_pk_add_f32 v[40:41], v[40:41], v[246:247]
	v_lshlrev_b32_e32 v246, 16, v202
	v_and_b32_e32 v247, 0xffff0000, v202
	v_pk_add_f32 v[34:35], v[34:35], v[246:247]
	v_lshlrev_b32_e32 v246, 16, v203
	v_and_b32_e32 v247, 0xffff0000, v203
	v_pk_add_f32 v[36:37], v[36:37], v[246:247]
	v_cvt_pk_bf16_f32 v200, v38, v39
	v_cvt_pk_bf16_f32 v201, v40, v41
	v_cvt_pk_bf16_f32 v202, v34, v35
	v_cvt_pk_bf16_f32 v203, v36, v37
	global_store_dwordx4 v245, v[200:203], s[10:11] offset:256
	v_fmac_f32_e32 v46, v38, v38
	v_fmac_f32_e32 v46, v39, v39
	v_fmac_f32_e32 v46, v40, v40
	v_fmac_f32_e32 v46, v41, v41
	v_fmac_f32_e32 v46, v34, v34
	v_fmac_f32_e32 v46, v35, v35
	v_fmac_f32_e32 v46, v36, v36
	v_fmac_f32_e32 v46, v37, v37
	s_add_u32 s10, s16, 0x140000
	s_addc_u32 s11, s17, 0
	s_waitcnt vmcnt(15)
	v_lshlrev_b32_e32 v246, 16, v204
	v_and_b32_e32 v247, 0xffff0000, v204
	v_pk_add_f32 v[30:31], v[30:31], v[246:247]
	v_lshlrev_b32_e32 v246, 16, v205
	v_and_b32_e32 v247, 0xffff0000, v205
	v_pk_add_f32 v[32:33], v[32:33], v[246:247]
	v_lshlrev_b32_e32 v246, 16, v206
	v_and_b32_e32 v247, 0xffff0000, v206
	v_pk_add_f32 v[26:27], v[26:27], v[246:247]
	v_lshlrev_b32_e32 v246, 16, v207
	v_and_b32_e32 v247, 0xffff0000, v207
	v_pk_add_f32 v[28:29], v[28:29], v[246:247]
	v_cvt_pk_bf16_f32 v204, v30, v31
	v_cvt_pk_bf16_f32 v205, v32, v33
	v_cvt_pk_bf16_f32 v206, v26, v27
	v_cvt_pk_bf16_f32 v207, v28, v29
	global_store_dwordx4 v245, v[204:207], s[10:11]
	v_mul_f32_e32 v30, v30, v30
	v_fmac_f32_e32 v30, v31, v31
	v_fmac_f32_e32 v30, v32, v32
	v_fmac_f32_e32 v30, v33, v33
	v_fmac_f32_e32 v30, v26, v26
	v_fmac_f32_e32 v30, v27, v27
	v_fmac_f32_e32 v30, v28, v28
	v_fmac_f32_e32 v30, v29, v29
	s_waitcnt vmcnt(15)
	v_lshlrev_b32_e32 v246, 16, v208
	v_and_b32_e32 v247, 0xffff0000, v208
	v_pk_add_f32 v[22:23], v[22:23], v[246:247]
	v_lshlrev_b32_e32 v246, 16, v209
	v_and_b32_e32 v247, 0xffff0000, v209
	v_pk_add_f32 v[24:25], v[24:25], v[246:247]
	v_lshlrev_b32_e32 v246, 16, v210
	v_and_b32_e32 v247, 0xffff0000, v210
	v_pk_add_f32 v[18:19], v[18:19], v[246:247]
	v_lshlrev_b32_e32 v246, 16, v211
	v_and_b32_e32 v247, 0xffff0000, v211
	v_pk_add_f32 v[20:21], v[20:21], v[246:247]
	v_cvt_pk_bf16_f32 v208, v22, v23
	v_cvt_pk_bf16_f32 v209, v24, v25
	v_cvt_pk_bf16_f32 v210, v18, v19
	v_cvt_pk_bf16_f32 v211, v20, v21
	global_store_dwordx4 v245, v[208:211], s[10:11] offset:256
	v_fmac_f32_e32 v30, v22, v22
	v_fmac_f32_e32 v30, v23, v23
	v_fmac_f32_e32 v30, v24, v24
	v_fmac_f32_e32 v30, v25, v25
	v_fmac_f32_e32 v30, v18, v18
	v_fmac_f32_e32 v30, v19, v19
	v_fmac_f32_e32 v30, v20, v20
	v_fmac_f32_e32 v30, v21, v21
	s_add_u32 s10, s16, 0x160000
	s_addc_u32 s11, s17, 0
	s_waitcnt vmcnt(15)
	v_lshlrev_b32_e32 v246, 16, v212
	v_and_b32_e32 v247, 0xffff0000, v212
	v_pk_add_f32 v[14:15], v[14:15], v[246:247]
	v_lshlrev_b32_e32 v246, 16, v213
	v_and_b32_e32 v247, 0xffff0000, v213
	v_pk_add_f32 v[16:17], v[16:17], v[246:247]
	v_lshlrev_b32_e32 v246, 16, v214
	v_and_b32_e32 v247, 0xffff0000, v214
	v_pk_add_f32 v[10:11], v[10:11], v[246:247]
	v_lshlrev_b32_e32 v246, 16, v215
	v_and_b32_e32 v247, 0xffff0000, v215
	v_pk_add_f32 v[12:13], v[12:13], v[246:247]
	v_cvt_pk_bf16_f32 v212, v14, v15
	v_cvt_pk_bf16_f32 v213, v16, v17
	v_cvt_pk_bf16_f32 v214, v10, v11
	v_cvt_pk_bf16_f32 v215, v12, v13
	global_store_dwordx4 v245, v[212:215], s[10:11]
	v_mul_f32_e32 v14, v14, v14
	v_fmac_f32_e32 v14, v15, v15
	v_fmac_f32_e32 v14, v16, v16
	v_fmac_f32_e32 v14, v17, v17
	v_fmac_f32_e32 v14, v10, v10
	v_fmac_f32_e32 v14, v11, v11
	v_fmac_f32_e32 v14, v12, v12
	v_fmac_f32_e32 v14, v13, v13
	s_waitcnt vmcnt(15)
	v_lshlrev_b32_e32 v246, 16, v216
	v_and_b32_e32 v247, 0xffff0000, v216
	v_pk_add_f32 v[6:7], v[6:7], v[246:247]
	v_lshlrev_b32_e32 v246, 16, v217
	v_and_b32_e32 v247, 0xffff0000, v217
	v_pk_add_f32 v[8:9], v[8:9], v[246:247]
	v_lshlrev_b32_e32 v246, 16, v218
	v_and_b32_e32 v247, 0xffff0000, v218
	v_pk_add_f32 v[2:3], v[2:3], v[246:247]
	v_lshlrev_b32_e32 v246, 16, v219
	v_and_b32_e32 v247, 0xffff0000, v219
	v_pk_add_f32 v[4:5], v[4:5], v[246:247]
	v_cvt_pk_bf16_f32 v216, v6, v7
	v_cvt_pk_bf16_f32 v217, v8, v9
	v_cvt_pk_bf16_f32 v218, v2, v3
	v_cvt_pk_bf16_f32 v219, v4, v5
	global_store_dwordx4 v245, v[216:219], s[10:11] offset:256
	v_fmac_f32_e32 v14, v6, v6
	v_fmac_f32_e32 v14, v7, v7
	v_fmac_f32_e32 v14, v8, v8
	v_fmac_f32_e32 v14, v9, v9
	v_fmac_f32_e32 v14, v2, v2
	v_fmac_f32_e32 v14, v3, v3
	v_fmac_f32_e32 v14, v4, v4
	v_fmac_f32_e32 v14, v5, v5
	v_mbcnt_lo_u32_b32 v246, -1, 0
	v_mbcnt_hi_u32_b32 v246, -1, v246
	v_xor_b32_e32 v247, 32, v246
	v_xor_b32_e32 v246, 16, v246
	v_lshlrev_b32_e32 v246, 2, v246
	v_lshlrev_b32_e32 v247, 2, v247
	ds_bpermute_b32 v127, v246, v126
	ds_bpermute_b32 v111, v246, v110
	ds_bpermute_b32 v95, v246, v94
	ds_bpermute_b32 v79, v246, v78
	ds_bpermute_b32 v63, v246, v62
	ds_bpermute_b32 v47, v246, v46
	ds_bpermute_b32 v31, v246, v30
	ds_bpermute_b32 v15, v246, v14
	s_waitcnt lgkmcnt(0)
	v_add_f32_e32 v126, v126, v127
	v_add_f32_e32 v110, v110, v111
	v_add_f32_e32 v94, v94, v95
	v_add_f32_e32 v78, v78, v79
	v_add_f32_e32 v62, v62, v63
	v_add_f32_e32 v46, v46, v47
	v_add_f32_e32 v30, v30, v31
	v_add_f32_e32 v14, v14, v15
	ds_bpermute_b32 v127, v247, v126
	ds_bpermute_b32 v111, v247, v110
	ds_bpermute_b32 v95, v247, v94
	ds_bpermute_b32 v79, v247, v78
	ds_bpermute_b32 v63, v247, v62
	ds_bpermute_b32 v47, v247, v46
	ds_bpermute_b32 v31, v247, v30
	ds_bpermute_b32 v15, v247, v14
	s_waitcnt lgkmcnt(0)
	v_add_f32_e32 v126, v126, v127
	v_add_f32_e32 v110, v110, v111
	v_add_f32_e32 v94, v94, v95
	v_add_f32_e32 v78, v78, v79
	v_add_f32_e32 v62, v62, v63
	v_add_f32_e32 v46, v46, v47
	v_add_f32_e32 v30, v30, v31
	v_add_f32_e32 v14, v14, v15
	v_lshl_add_u32 v246, s34, 8, v1
	v_lshlrev_b32_e32 v246, 2, v246
	s_and_saveexec_b64 s[10:11], s[6:7]
	global_atomic_add_f32 v246, v126, s[18:19]
	global_atomic_add_f32 v246, v110, s[18:19] offset:64
	global_atomic_add_f32 v246, v94, s[18:19] offset:128
	global_atomic_add_f32 v246, v78, s[18:19] offset:192
	global_atomic_add_f32 v246, v62, s[18:19] offset:512
	global_atomic_add_f32 v246, v46, s[18:19] offset:576
	global_atomic_add_f32 v246, v30, s[18:19] offset:640
	global_atomic_add_f32 v246, v14, s[18:19] offset:704
	s_mov_b64 exec, s[10:11]
	s_and_b64 vcc, exec, s[8:9]
	s_mov_b64 s[8:9], -1
	s_cbranch_vccnz .LBB0_1473
	s_andn2_b64 vcc, exec, s[14:15]
	s_cbranch_vccnz .LBB0_1472
	s_barrier
	s_branch .LBB0_1472

.LBB0_1984:
	ds_read_b128 v[142:145], v149
	ds_read_b128 v[154:157], v149 offset:1024
	ds_read_b128 v[158:161], v149 offset:2048
	ds_read_b128 v[166:169], v149 offset:3072
	ds_read_b128 v[170:173], v150
	ds_read_b128 v[174:177], v150 offset:1024
	ds_read_b128 v[178:181], v150 offset:2048
	ds_read_b128 v[182:185], v150 offset:3072
	s_add_u32 s6, s72, 0xfff00080
	s_addc_u32 s7, s73, -1
	s_cmp_eq_u32 s83, 60
	s_cselect_b32 s77, s63, s7
	s_cselect_b32 s76, s69, s6
	s_cselect_b32 s75, s61, s82
	s_cselect_b32 s74, s80, s81
	v_lshl_add_u64 v[162:163], s[72:73], 0, v[140:141]
	s_add_i32 m0, s27, 0xc000
	ds_read_b128 v[188:191], v151
	ds_read_b128 v[192:195], v151 offset:1024
	ds_read_b128 v[196:199], v151 offset:2048
	ds_read_b128 v[200:203], v151 offset:3072
	ds_read_b128 v[204:207], v151 offset:4096
	ds_read_b128 v[208:211], v151 offset:5120
	ds_read_b128 v[212:215], v151 offset:6144
	ds_read_b128 v[216:219], v151 offset:7168
	global_load_lds_dwordx4 v[162:163], off
	v_lshl_add_u64 v[162:163], s[72:73], 0, v[138:139]
	s_add_i32 m0, s27, 0xe000
	s_nop 0
	global_load_lds_dwordx4 v[162:163], off
	s_waitcnt vmcnt(8)
	s_waitcnt lgkmcnt(0)
	s_barrier
	s_setprio 1
	s_waitcnt lgkmcnt(0)
	v_mfma_f32_16x16x32_bf16 v[126:129], v[142:145], v[188:191], v[126:129]
	v_mfma_f32_16x16x32_bf16 v[122:125], v[158:161], v[188:191], v[122:125]
	v_mfma_f32_16x16x32_bf16 v[110:113], v[142:145], v[196:199], v[110:113]
	v_mfma_f32_16x16x32_bf16 v[106:109], v[158:161], v[196:199], v[106:109]
	v_mfma_f32_16x16x32_bf16 v[94:97], v[142:145], v[204:207], v[94:97]
	v_mfma_f32_16x16x32_bf16 v[90:93], v[158:161], v[204:207], v[90:93]
	v_mfma_f32_16x16x32_bf16 v[78:81], v[142:145], v[212:215], v[78:81]
	v_mfma_f32_16x16x32_bf16 v[74:77], v[158:161], v[212:215], v[74:77]
	v_mfma_f32_16x16x32_bf16 v[126:129], v[154:157], v[192:195], v[126:129]
	v_mfma_f32_16x16x32_bf16 v[122:125], v[166:169], v[192:195], v[122:125]
	v_mfma_f32_16x16x32_bf16 v[110:113], v[154:157], v[200:203], v[110:113]
	v_mfma_f32_16x16x32_bf16 v[106:109], v[166:169], v[200:203], v[106:109]
	v_mfma_f32_16x16x32_bf16 v[94:97], v[154:157], v[208:211], v[94:97]
	v_mfma_f32_16x16x32_bf16 v[90:93], v[166:169], v[208:211], v[90:93]
	v_mfma_f32_16x16x32_bf16 v[78:81], v[154:157], v[216:219], v[78:81]
	v_mfma_f32_16x16x32_bf16 v[74:77], v[166:169], v[216:219], v[74:77]
	s_setprio 0
	s_setprio 1
	v_mfma_f32_16x16x32_bf16 v[118:121], v[170:173], v[188:191], v[118:121]
	v_mfma_f32_16x16x32_bf16 v[114:117], v[178:181], v[188:191], v[114:117]
	v_mfma_f32_16x16x32_bf16 v[102:105], v[170:173], v[196:199], v[102:105]
	v_mfma_f32_16x16x32_bf16 v[98:101], v[178:181], v[196:199], v[98:101]
	v_mfma_f32_16x16x32_bf16 v[86:89], v[170:173], v[204:207], v[86:89]
	v_mfma_f32_16x16x32_bf16 v[82:85], v[178:181], v[204:207], v[82:85]
	v_mfma_f32_16x16x32_bf16 v[70:73], v[170:173], v[212:215], v[70:73]
	v_mfma_f32_16x16x32_bf16 v[66:69], v[178:181], v[212:215], v[66:69]
	v_mfma_f32_16x16x32_bf16 v[118:121], v[174:177], v[192:195], v[118:121]
	v_mfma_f32_16x16x32_bf16 v[114:117], v[182:185], v[192:195], v[114:117]
	v_mfma_f32_16x16x32_bf16 v[102:105], v[174:177], v[200:203], v[102:105]
	v_mfma_f32_16x16x32_bf16 v[98:101], v[182:185], v[200:203], v[98:101]
	v_mfma_f32_16x16x32_bf16 v[86:89], v[174:177], v[208:211], v[86:89]
	v_mfma_f32_16x16x32_bf16 v[82:85], v[182:185], v[208:211], v[82:85]
	v_mfma_f32_16x16x32_bf16 v[70:73], v[174:177], v[216:219], v[70:73]
	v_mfma_f32_16x16x32_bf16 v[66:69], v[182:185], v[216:219], v[66:69]
	s_setprio 0
	s_barrier
	s_add_i32 s6, s78, s26
	v_lshl_add_u64 v[162:163], s[74:75], 0, v[132:133]
	s_mov_b32 m0, s6
	ds_read_b128 v[188:191], v151 offset:16384
	ds_read_b128 v[192:195], v151 offset:17408
	ds_read_b128 v[196:199], v151 offset:18432
	ds_read_b128 v[200:203], v151 offset:19456
	ds_read_b128 v[204:207], v151 offset:20480
	ds_read_b128 v[208:211], v151 offset:21504
	ds_read_b128 v[212:215], v151 offset:22528
	ds_read_b128 v[216:219], v151 offset:23552
	global_load_lds_dwordx4 v[162:163], off
	s_add_i32 m0, s6, 0x2000
	s_add_u32 s6, s74, 0x100000
	v_lshl_add_u64 v[220:221], s[74:75], 0, v[136:137]
	s_addc_u32 s7, s75, 0
	s_add_i32 s16, s79, s26
	global_load_lds_dwordx4 v[220:221], off
	v_lshl_add_u64 v[222:223], s[6:7], 0, v[132:133]
	s_mov_b32 m0, s16
	v_lshl_add_u64 v[224:225], s[76:77], 0, v[134:135]
	global_load_lds_dwordx4 v[222:223], off
	v_lshl_add_u64 v[222:223], s[6:7], 0, v[136:137]
	s_add_i32 m0, s16, 0x2000
	s_nop 0
	global_load_lds_dwordx4 v[222:223], off
	v_lshl_add_u64 v[222:223], s[76:77], 0, v[130:131]
	s_mov_b32 m0, s27
	s_nop 0
	global_load_lds_dwordx4 v[222:223], off
	s_mov_b32 m0, s28
	s_nop 0
	global_load_lds_dwordx4 v[224:225], off
	s_waitcnt vmcnt(8)
	s_waitcnt lgkmcnt(0)
	s_barrier
	s_setprio 1
	s_waitcnt lgkmcnt(0)
	v_mfma_f32_16x16x32_bf16 v[62:65], v[142:145], v[188:191], v[62:65]
	v_mfma_f32_16x16x32_bf16 v[58:61], v[158:161], v[188:191], v[58:61]
	v_mfma_f32_16x16x32_bf16 v[46:49], v[142:145], v[196:199], v[46:49]
	v_mfma_f32_16x16x32_bf16 v[42:45], v[158:161], v[196:199], v[42:45]
	v_mfma_f32_16x16x32_bf16 v[30:33], v[142:145], v[204:207], v[30:33]
	v_mfma_f32_16x16x32_bf16 v[26:29], v[158:161], v[204:207], v[26:29]
	v_mfma_f32_16x16x32_bf16 v[14:17], v[142:145], v[212:215], v[14:17]
	v_mfma_f32_16x16x32_bf16 v[10:13], v[158:161], v[212:215], v[10:13]
	v_mfma_f32_16x16x32_bf16 v[62:65], v[154:157], v[192:195], v[62:65]
	v_mfma_f32_16x16x32_bf16 v[58:61], v[166:169], v[192:195], v[58:61]
	v_mfma_f32_16x16x32_bf16 v[46:49], v[154:157], v[200:203], v[46:49]
	v_mfma_f32_16x16x32_bf16 v[42:45], v[166:169], v[200:203], v[42:45]
	v_mfma_f32_16x16x32_bf16 v[30:33], v[154:157], v[208:211], v[30:33]
	v_mfma_f32_16x16x32_bf16 v[26:29], v[166:169], v[208:211], v[26:29]
	v_mfma_f32_16x16x32_bf16 v[14:17], v[154:157], v[216:219], v[14:17]
	v_mfma_f32_16x16x32_bf16 v[10:13], v[166:169], v[216:219], v[10:13]
	s_setprio 0
	s_setprio 1
	v_mfma_f32_16x16x32_bf16 v[54:57], v[170:173], v[188:191], v[54:57]
	v_mfma_f32_16x16x32_bf16 v[50:53], v[178:181], v[188:191], v[50:53]
	v_mfma_f32_16x16x32_bf16 v[38:41], v[170:173], v[196:199], v[38:41]
	v_mfma_f32_16x16x32_bf16 v[34:37], v[178:181], v[196:199], v[34:37]
	v_mfma_f32_16x16x32_bf16 v[22:25], v[170:173], v[204:207], v[22:25]
	v_mfma_f32_16x16x32_bf16 v[18:21], v[178:181], v[204:207], v[18:21]
	v_mfma_f32_16x16x32_bf16 v[6:9], v[170:173], v[212:215], v[6:9]
	v_mfma_f32_16x16x32_bf16 v[2:5], v[178:181], v[212:215], v[2:5]
	v_mfma_f32_16x16x32_bf16 v[54:57], v[174:177], v[192:195], v[54:57]
	v_mfma_f32_16x16x32_bf16 v[50:53], v[182:185], v[192:195], v[50:53]
	v_mfma_f32_16x16x32_bf16 v[38:41], v[174:177], v[200:203], v[38:41]
	v_mfma_f32_16x16x32_bf16 v[34:37], v[182:185], v[200:203], v[34:37]
	v_mfma_f32_16x16x32_bf16 v[22:25], v[174:177], v[208:211], v[22:25]
	v_mfma_f32_16x16x32_bf16 v[18:21], v[182:185], v[208:211], v[18:21]
	v_mfma_f32_16x16x32_bf16 v[6:9], v[174:177], v[216:219], v[6:9]
	v_mfma_f32_16x16x32_bf16 v[2:5], v[182:185], v[216:219], v[2:5]
	s_setprio 0
	s_barrier
	s_add_i32 s16, 0, 0x18000
	v_add_u32_e32 v153, s16, v147
	s_add_i32 s17, 0, 0x1c000
	ds_read_b128 v[142:145], v153
	ds_read_b128 v[154:157], v153 offset:1024
	ds_read_b128 v[158:161], v153 offset:2048
	ds_read_b128 v[166:169], v153 offset:3072
	v_add_u32_e32 v153, s17, v147
	ds_read_b128 v[170:173], v153
	ds_read_b128 v[174:177], v153 offset:1024
	ds_read_b128 v[178:181], v153 offset:2048
	ds_read_b128 v[182:185], v153 offset:3072
	s_add_u32 s6, s76, 0x100000
	s_addc_u32 s7, s77, 0
	s_mov_b32 m0, s29
	v_lshl_add_u64 v[226:227], s[6:7], 0, v[130:131]
	ds_read_b128 v[188:191], v151 offset:32768
	ds_read_b128 v[192:195], v151 offset:33792
	ds_read_b128 v[196:199], v151 offset:34816
	ds_read_b128 v[200:203], v151 offset:35840
	ds_read_b128 v[204:207], v151 offset:36864
	ds_read_b128 v[208:211], v151 offset:37888
	ds_read_b128 v[212:215], v151 offset:38912
	ds_read_b128 v[216:219], v151 offset:39936
	global_load_lds_dwordx4 v[226:227], off
	v_lshl_add_u64 v[226:227], s[6:7], 0, v[134:135]
	s_mov_b32 m0, s40
	s_nop 0
	global_load_lds_dwordx4 v[226:227], off
	s_waitcnt vmcnt(8)
	s_waitcnt lgkmcnt(0)
	s_barrier
	s_setprio 1
	s_waitcnt lgkmcnt(0)
	v_mfma_f32_16x16x32_bf16 v[126:129], v[142:145], v[188:191], v[126:129]
	v_mfma_f32_16x16x32_bf16 v[122:125], v[158:161], v[188:191], v[122:125]
	v_mfma_f32_16x16x32_bf16 v[110:113], v[142:145], v[196:199], v[110:113]
	v_mfma_f32_16x16x32_bf16 v[106:109], v[158:161], v[196:199], v[106:109]
	v_mfma_f32_16x16x32_bf16 v[94:97], v[142:145], v[204:207], v[94:97]
	v_mfma_f32_16x16x32_bf16 v[90:93], v[158:161], v[204:207], v[90:93]
	v_mfma_f32_16x16x32_bf16 v[78:81], v[142:145], v[212:215], v[78:81]
	v_mfma_f32_16x16x32_bf16 v[74:77], v[158:161], v[212:215], v[74:77]
	v_mfma_f32_16x16x32_bf16 v[126:129], v[154:157], v[192:195], v[126:129]
	v_mfma_f32_16x16x32_bf16 v[122:125], v[166:169], v[192:195], v[122:125]
	v_mfma_f32_16x16x32_bf16 v[110:113], v[154:157], v[200:203], v[110:113]
	v_mfma_f32_16x16x32_bf16 v[106:109], v[166:169], v[200:203], v[106:109]
	v_mfma_f32_16x16x32_bf16 v[94:97], v[154:157], v[208:211], v[94:97]
	v_mfma_f32_16x16x32_bf16 v[90:93], v[166:169], v[208:211], v[90:93]
	v_mfma_f32_16x16x32_bf16 v[78:81], v[154:157], v[216:219], v[78:81]
	v_mfma_f32_16x16x32_bf16 v[74:77], v[166:169], v[216:219], v[74:77]
	s_setprio 0
	s_setprio 1
	v_mfma_f32_16x16x32_bf16 v[118:121], v[170:173], v[188:191], v[118:121]
	v_mfma_f32_16x16x32_bf16 v[114:117], v[178:181], v[188:191], v[114:117]
	v_mfma_f32_16x16x32_bf16 v[102:105], v[170:173], v[196:199], v[102:105]
	v_mfma_f32_16x16x32_bf16 v[98:101], v[178:181], v[196:199], v[98:101]
	v_mfma_f32_16x16x32_bf16 v[86:89], v[170:173], v[204:207], v[86:89]
	v_mfma_f32_16x16x32_bf16 v[82:85], v[178:181], v[204:207], v[82:85]
	v_mfma_f32_16x16x32_bf16 v[70:73], v[170:173], v[212:215], v[70:73]
	v_mfma_f32_16x16x32_bf16 v[66:69], v[178:181], v[212:215], v[66:69]
	v_mfma_f32_16x16x32_bf16 v[118:121], v[174:177], v[192:195], v[118:121]
	v_mfma_f32_16x16x32_bf16 v[114:117], v[182:185], v[192:195], v[114:117]
	v_mfma_f32_16x16x32_bf16 v[102:105], v[174:177], v[200:203], v[102:105]
	v_mfma_f32_16x16x32_bf16 v[98:101], v[182:185], v[200:203], v[98:101]
	v_mfma_f32_16x16x32_bf16 v[86:89], v[174:177], v[208:211], v[86:89]
	v_mfma_f32_16x16x32_bf16 v[82:85], v[182:185], v[208:211], v[82:85]
	v_mfma_f32_16x16x32_bf16 v[70:73], v[174:177], v[216:219], v[70:73]
	v_mfma_f32_16x16x32_bf16 v[66:69], v[182:185], v[216:219], v[66:69]
	s_setprio 0
	s_barrier
	s_add_i32 s6, s16, s26
	v_lshl_add_u64 v[162:163], v[162:163], 0, s[12:13]
	s_mov_b32 m0, s6
	ds_read_b128 v[188:191], v151 offset:49152
	ds_read_b128 v[192:195], v151 offset:50176
	ds_read_b128 v[196:199], v151 offset:51200
	ds_read_b128 v[200:203], v151 offset:52224
	ds_read_b128 v[204:207], v151 offset:53248
	ds_read_b128 v[208:211], v151 offset:54272
	ds_read_b128 v[212:215], v151 offset:55296
	ds_read_b128 v[216:219], v151 offset:56320
	global_load_lds_dwordx4 v[162:163], off
	s_add_i32 m0, s6, 0x2000
	s_add_u32 s6, s74, 0x100080
	v_lshl_add_u64 v[162:163], v[220:221], 0, s[12:13]
	s_addc_u32 s7, s75, 0
	s_add_i32 s16, s17, s26
	global_load_lds_dwordx4 v[162:163], off
	v_lshl_add_u64 v[162:163], s[6:7], 0, v[132:133]
	s_mov_b32 m0, s16
	s_nop 0
	global_load_lds_dwordx4 v[162:163], off
	v_lshl_add_u64 v[162:163], s[6:7], 0, v[136:137]
	s_add_i32 m0, s16, 0x2000
	s_nop 0
	global_load_lds_dwordx4 v[162:163], off
	v_lshl_add_u64 v[162:163], v[222:223], 0, s[12:13]
	s_mov_b32 m0, s56
	s_nop 0
	global_load_lds_dwordx4 v[162:163], off
	v_lshl_add_u64 v[162:163], v[224:225], 0, s[12:13]
	s_mov_b32 m0, s57
	s_nop 0
	global_load_lds_dwordx4 v[162:163], off
	s_waitcnt vmcnt(8)
	s_waitcnt lgkmcnt(0)
	s_barrier
	s_setprio 1
	s_waitcnt lgkmcnt(0)
	v_mfma_f32_16x16x32_bf16 v[62:65], v[142:145], v[188:191], v[62:65]
	v_mfma_f32_16x16x32_bf16 v[58:61], v[158:161], v[188:191], v[58:61]
	v_mfma_f32_16x16x32_bf16 v[46:49], v[142:145], v[196:199], v[46:49]
	v_mfma_f32_16x16x32_bf16 v[42:45], v[158:161], v[196:199], v[42:45]
	v_mfma_f32_16x16x32_bf16 v[30:33], v[142:145], v[204:207], v[30:33]
	v_mfma_f32_16x16x32_bf16 v[26:29], v[158:161], v[204:207], v[26:29]
	v_mfma_f32_16x16x32_bf16 v[14:17], v[142:145], v[212:215], v[14:17]
	v_mfma_f32_16x16x32_bf16 v[10:13], v[158:161], v[212:215], v[10:13]
	v_mfma_f32_16x16x32_bf16 v[62:65], v[154:157], v[192:195], v[62:65]
	v_mfma_f32_16x16x32_bf16 v[58:61], v[166:169], v[192:195], v[58:61]
	v_mfma_f32_16x16x32_bf16 v[46:49], v[154:157], v[200:203], v[46:49]
	v_mfma_f32_16x16x32_bf16 v[42:45], v[166:169], v[200:203], v[42:45]
	v_mfma_f32_16x16x32_bf16 v[30:33], v[154:157], v[208:211], v[30:33]
	v_mfma_f32_16x16x32_bf16 v[26:29], v[166:169], v[208:211], v[26:29]
	v_mfma_f32_16x16x32_bf16 v[14:17], v[154:157], v[216:219], v[14:17]
	v_mfma_f32_16x16x32_bf16 v[10:13], v[166:169], v[216:219], v[10:13]
	s_setprio 0
	s_setprio 1
	v_mfma_f32_16x16x32_bf16 v[54:57], v[170:173], v[188:191], v[54:57]
	v_mfma_f32_16x16x32_bf16 v[50:53], v[178:181], v[188:191], v[50:53]
	v_mfma_f32_16x16x32_bf16 v[38:41], v[170:173], v[196:199], v[38:41]
	v_mfma_f32_16x16x32_bf16 v[34:37], v[178:181], v[196:199], v[34:37]
	v_mfma_f32_16x16x32_bf16 v[22:25], v[170:173], v[204:207], v[22:25]
	v_mfma_f32_16x16x32_bf16 v[18:21], v[178:181], v[204:207], v[18:21]
	v_mfma_f32_16x16x32_bf16 v[6:9], v[170:173], v[212:215], v[6:9]
	v_mfma_f32_16x16x32_bf16 v[2:5], v[178:181], v[212:215], v[2:5]
	v_mfma_f32_16x16x32_bf16 v[54:57], v[174:177], v[192:195], v[54:57]
	v_mfma_f32_16x16x32_bf16 v[50:53], v[182:185], v[192:195], v[50:53]
	v_mfma_f32_16x16x32_bf16 v[38:41], v[174:177], v[200:203], v[38:41]
	v_mfma_f32_16x16x32_bf16 v[34:37], v[182:185], v[200:203], v[34:37]
	v_mfma_f32_16x16x32_bf16 v[22:25], v[174:177], v[208:211], v[22:25]
	v_mfma_f32_16x16x32_bf16 v[18:21], v[182:185], v[208:211], v[18:21]
	v_mfma_f32_16x16x32_bf16 v[6:9], v[174:177], v[216:219], v[6:9]
	v_mfma_f32_16x16x32_bf16 v[2:5], v[182:185], v[216:219], v[2:5]
	s_setprio 0
	s_barrier
	s_add_i32 s83, s83, 2
	s_add_u32 s81, s81, 0x100
	s_addc_u32 s82, s82, 0
	s_add_u32 s72, s72, 0x100
	s_addc_u32 s73, s73, 0
	s_cmp_gt_u32 s83, 61
	s_cbranch_scc0 .LBB0_1984
	v_lshl_add_u32 v245, s70, 8, v146
	v_lshl_or_b32 v246, s68, 8, v148
	v_lshlrev_b32_e32 v245, 13, v245
	v_lshl_add_u32 v245, v246, 1, v245
	global_load_dwordx4 v[142:145], v245, s[24:25]
	global_load_dwordx4 v[154:157], v245, s[24:25] offset:256
	s_add_u32 s68, s24, 0x20000
	s_addc_u32 s69, s25, 0
	global_load_dwordx4 v[158:161], v245, s[68:69]
	global_load_dwordx4 v[166:169], v245, s[68:69] offset:256
	s_add_u32 s68, s24, 0x40000
	s_addc_u32 s69, s25, 0
	global_load_dwordx4 v[170:173], v245, s[68:69]
	global_load_dwordx4 v[174:177], v245, s[68:69] offset:256
	s_add_u32 s68, s24, 0x60000
	s_addc_u32 s69, s25, 0
	global_load_dwordx4 v[178:181], v245, s[68:69]
	global_load_dwordx4 v[182:185], v245, s[68:69] offset:256
	s_add_u32 s68, s24, 0x100000
	s_addc_u32 s69, s25, 0
	global_load_dwordx4 v[188:191], v245, s[68:69]
	global_load_dwordx4 v[192:195], v245, s[68:69] offset:256
	s_add_u32 s68, s24, 0x120000
	s_addc_u32 s69, s25, 0
	global_load_dwordx4 v[196:199], v245, s[68:69]
	global_load_dwordx4 v[200:203], v245, s[68:69] offset:256
	s_add_u32 s68, s24, 0x140000
	s_addc_u32 s69, s25, 0
	global_load_dwordx4 v[204:207], v245, s[68:69]
	global_load_dwordx4 v[208:211], v245, s[68:69] offset:256
	s_add_u32 s68, s24, 0x160000
	s_addc_u32 s69, s25, 0
	global_load_dwordx4 v[212:215], v245, s[68:69]
	global_load_dwordx4 v[216:219], v245, s[68:69] offset:256
	s_and_b64 vcc, exec, s[44:45]
	s_cbranch_vccz .LBB0_1987
	s_barrier
.LBB0_1987:
	s_waitcnt vmcnt(15)
	v_lshlrev_b32_e32 v246, 16, v142
	v_and_b32_e32 v247, 0xffff0000, v142
	v_pk_add_f32 v[126:127], v[126:127], v[246:247]
	v_lshlrev_b32_e32 v246, 16, v143
	v_and_b32_e32 v247, 0xffff0000, v143
	v_pk_add_f32 v[128:129], v[128:129], v[246:247]
	v_lshlrev_b32_e32 v246, 16, v144
	v_and_b32_e32 v247, 0xffff0000, v144
	v_pk_add_f32 v[122:123], v[122:123], v[246:247]
	v_lshlrev_b32_e32 v246, 16, v145
	v_and_b32_e32 v247, 0xffff0000, v145
	v_pk_add_f32 v[124:125], v[124:125], v[246:247]
	v_cvt_pk_bf16_f32 v142, v126, v127
	v_cvt_pk_bf16_f32 v143, v128, v129
	v_cvt_pk_bf16_f32 v144, v122, v123
	v_cvt_pk_bf16_f32 v145, v124, v125
	global_store_dwordx4 v245, v[142:145], s[24:25]
	v_mul_f32_e32 v126, v126, v126
	v_fmac_f32_e32 v126, v127, v127
	v_fmac_f32_e32 v126, v128, v128
	v_fmac_f32_e32 v126, v129, v129
	v_fmac_f32_e32 v126, v122, v122
	v_fmac_f32_e32 v126, v123, v123
	v_fmac_f32_e32 v126, v124, v124
	v_fmac_f32_e32 v126, v125, v125
	s_waitcnt vmcnt(15)
	v_lshlrev_b32_e32 v246, 16, v154
	v_and_b32_e32 v247, 0xffff0000, v154
	v_pk_add_f32 v[118:119], v[118:119], v[246:247]
	v_lshlrev_b32_e32 v246, 16, v155
	v_and_b32_e32 v247, 0xffff0000, v155
	v_pk_add_f32 v[120:121], v[120:121], v[246:247]
	v_lshlrev_b32_e32 v246, 16, v156
	v_and_b32_e32 v247, 0xffff0000, v156
	v_pk_add_f32 v[114:115], v[114:115], v[246:247]
	v_lshlrev_b32_e32 v246, 16, v157
	v_and_b32_e32 v247, 0xffff0000, v157
	v_pk_add_f32 v[116:117], v[116:117], v[246:247]
	v_cvt_pk_bf16_f32 v154, v118, v119
	v_cvt_pk_bf16_f32 v155, v120, v121
	v_cvt_pk_bf16_f32 v156, v114, v115
	v_cvt_pk_bf16_f32 v157, v116, v117
	global_store_dwordx4 v245, v[154:157], s[24:25] offset:256
	v_fmac_f32_e32 v126, v118, v118
	v_fmac_f32_e32 v126, v119, v119
	v_fmac_f32_e32 v126, v120, v120
	v_fmac_f32_e32 v126, v121, v121
	v_fmac_f32_e32 v126, v114, v114
	v_fmac_f32_e32 v126, v115, v115
	v_fmac_f32_e32 v126, v116, v116
	v_fmac_f32_e32 v126, v117, v117
	s_add_u32 s68, s24, 0x20000
	s_addc_u32 s69, s25, 0
	s_waitcnt vmcnt(15)
	v_lshlrev_b32_e32 v246, 16, v158
	v_and_b32_e32 v247, 0xffff0000, v158
	v_pk_add_f32 v[110:111], v[110:111], v[246:247]
	v_lshlrev_b32_e32 v246, 16, v159
	v_and_b32_e32 v247, 0xffff0000, v159
	v_pk_add_f32 v[112:113], v[112:113], v[246:247]
	v_lshlrev_b32_e32 v246, 16, v160
	v_and_b32_e32 v247, 0xffff0000, v160
	v_pk_add_f32 v[106:107], v[106:107], v[246:247]
	v_lshlrev_b32_e32 v246, 16, v161
	v_and_b32_e32 v247, 0xffff0000, v161
	v_pk_add_f32 v[108:109], v[108:109], v[246:247]
	v_cvt_pk_bf16_f32 v158, v110, v111
	v_cvt_pk_bf16_f32 v159, v112, v113
	v_cvt_pk_bf16_f32 v160, v106, v107
	v_cvt_pk_bf16_f32 v161, v108, v109
	global_store_dwordx4 v245, v[158:161], s[68:69]
	v_mul_f32_e32 v110, v110, v110
	v_fmac_f32_e32 v110, v111, v111
	v_fmac_f32_e32 v110, v112, v112
	v_fmac_f32_e32 v110, v113, v113
	v_fmac_f32_e32 v110, v106, v106
	v_fmac_f32_e32 v110, v107, v107
	v_fmac_f32_e32 v110, v108, v108
	v_fmac_f32_e32 v110, v109, v109
	s_waitcnt vmcnt(15)
	v_lshlrev_b32_e32 v246, 16, v166
	v_and_b32_e32 v247, 0xffff0000, v166
	v_pk_add_f32 v[102:103], v[102:103], v[246:247]
	v_lshlrev_b32_e32 v246, 16, v167
	v_and_b32_e32 v247, 0xffff0000, v167
	v_pk_add_f32 v[104:105], v[104:105], v[246:247]
	v_lshlrev_b32_e32 v246, 16, v168
	v_and_b32_e32 v247, 0xffff0000, v168
	v_pk_add_f32 v[98:99], v[98:99], v[246:247]
	v_lshlrev_b32_e32 v246, 16, v169
	v_and_b32_e32 v247, 0xffff0000, v169
	v_pk_add_f32 v[100:101], v[100:101], v[246:247]
	v_cvt_pk_bf16_f32 v166, v102, v103
	v_cvt_pk_bf16_f32 v167, v104, v105
	v_cvt_pk_bf16_f32 v168, v98, v99
	v_cvt_pk_bf16_f32 v169, v100, v101
	global_store_dwordx4 v245, v[166:169], s[68:69] offset:256
	v_fmac_f32_e32 v110, v102, v102
	v_fmac_f32_e32 v110, v103, v103
	v_fmac_f32_e32 v110, v104, v104
	v_fmac_f32_e32 v110, v105, v105
	v_fmac_f32_e32 v110, v98, v98
	v_fmac_f32_e32 v110, v99, v99
	v_fmac_f32_e32 v110, v100, v100
	v_fmac_f32_e32 v110, v101, v101
	s_add_u32 s68, s24, 0x40000
	s_addc_u32 s69, s25, 0
	s_waitcnt vmcnt(15)
	v_lshlrev_b32_e32 v246, 16, v170
	v_and_b32_e32 v247, 0xffff0000, v170
	v_pk_add_f32 v[94:95], v[94:95], v[246:247]
	v_lshlrev_b32_e32 v246, 16, v171
	v_and_b32_e32 v247, 0xffff0000, v171
	v_pk_add_f32 v[96:97], v[96:97], v[246:247]
	v_lshlrev_b32_e32 v246, 16, v172
	v_and_b32_e32 v247, 0xffff0000, v172
	v_pk_add_f32 v[90:91], v[90:91], v[246:247]
	v_lshlrev_b32_e32 v246, 16, v173
	v_and_b32_e32 v247, 0xffff0000, v173
	v_pk_add_f32 v[92:93], v[92:93], v[246:247]
	v_cvt_pk_bf16_f32 v170, v94, v95
	v_cvt_pk_bf16_f32 v171, v96, v97
	v_cvt_pk_bf16_f32 v172, v90, v91
	v_cvt_pk_bf16_f32 v173, v92, v93
	global_store_dwordx4 v245, v[170:173], s[68:69]
	v_mul_f32_e32 v94, v94, v94
	v_fmac_f32_e32 v94, v95, v95
	v_fmac_f32_e32 v94, v96, v96
	v_fmac_f32_e32 v94, v97, v97
	v_fmac_f32_e32 v94, v90, v90
	v_fmac_f32_e32 v94, v91, v91
	v_fmac_f32_e32 v94, v92, v92
	v_fmac_f32_e32 v94, v93, v93
	s_waitcnt vmcnt(15)
	v_lshlrev_b32_e32 v246, 16, v174
	v_and_b32_e32 v247, 0xffff0000, v174
	v_pk_add_f32 v[86:87], v[86:87], v[246:247]
	v_lshlrev_b32_e32 v246, 16, v175
	v_and_b32_e32 v247, 0xffff0000, v175
	v_pk_add_f32 v[88:89], v[88:89], v[246:247]
	v_lshlrev_b32_e32 v246, 16, v176
	v_and_b32_e32 v247, 0xffff0000, v176
	v_pk_add_f32 v[82:83], v[82:83], v[246:247]
	v_lshlrev_b32_e32 v246, 16, v177
	v_and_b32_e32 v247, 0xffff0000, v177
	v_pk_add_f32 v[84:85], v[84:85], v[246:247]
	v_cvt_pk_bf16_f32 v174, v86, v87
	v_cvt_pk_bf16_f32 v175, v88, v89
	v_cvt_pk_bf16_f32 v176, v82, v83
	v_cvt_pk_bf16_f32 v177, v84, v85
	global_store_dwordx4 v245, v[174:177], s[68:69] offset:256
	v_fmac_f32_e32 v94, v86, v86
	v_fmac_f32_e32 v94, v87, v87
	v_fmac_f32_e32 v94, v88, v88
	v_fmac_f32_e32 v94, v89, v89
	v_fmac_f32_e32 v94, v82, v82
	v_fmac_f32_e32 v94, v83, v83
	v_fmac_f32_e32 v94, v84, v84
	v_fmac_f32_e32 v94, v85, v85
	s_add_u32 s68, s24, 0x60000
	s_addc_u32 s69, s25, 0
	s_waitcnt vmcnt(15)
	v_lshlrev_b32_e32 v246, 16, v178
	v_and_b32_e32 v247, 0xffff0000, v178
	v_pk_add_f32 v[78:79], v[78:79], v[246:247]
	v_lshlrev_b32_e32 v246, 16, v179
	v_and_b32_e32 v247, 0xffff0000, v179
	v_pk_add_f32 v[80:81], v[80:81], v[246:247]
	v_lshlrev_b32_e32 v246, 16, v180
	v_and_b32_e32 v247, 0xffff0000, v180
	v_pk_add_f32 v[74:75], v[74:75], v[246:247]
	v_lshlrev_b32_e32 v246, 16, v181
	v_and_b32_e32 v247, 0xffff0000, v181
	v_pk_add_f32 v[76:77], v[76:77], v[246:247]
	v_cvt_pk_bf16_f32 v178, v78, v79
	v_cvt_pk_bf16_f32 v179, v80, v81
	v_cvt_pk_bf16_f32 v180, v74, v75
	v_cvt_pk_bf16_f32 v181, v76, v77
	global_store_dwordx4 v245, v[178:181], s[68:69]
	v_mul_f32_e32 v78, v78, v78
	v_fmac_f32_e32 v78, v79, v79
	v_fmac_f32_e32 v78, v80, v80
	v_fmac_f32_e32 v78, v81, v81
	v_fmac_f32_e32 v78, v74, v74
	v_fmac_f32_e32 v78, v75, v75
	v_fmac_f32_e32 v78, v76, v76
	v_fmac_f32_e32 v78, v77, v77
	s_waitcnt vmcnt(15)
	v_lshlrev_b32_e32 v246, 16, v182
	v_and_b32_e32 v247, 0xffff0000, v182
	v_pk_add_f32 v[70:71], v[70:71], v[246:247]
	v_lshlrev_b32_e32 v246, 16, v183
	v_and_b32_e32 v247, 0xffff0000, v183
	v_pk_add_f32 v[72:73], v[72:73], v[246:247]
	v_lshlrev_b32_e32 v246, 16, v184
	v_and_b32_e32 v247, 0xffff0000, v184
	v_pk_add_f32 v[66:67], v[66:67], v[246:247]
	v_lshlrev_b32_e32 v246, 16, v185
	v_and_b32_e32 v247, 0xffff0000, v185
	v_pk_add_f32 v[68:69], v[68:69], v[246:247]
	v_cvt_pk_bf16_f32 v182, v70, v71
	v_cvt_pk_bf16_f32 v183, v72, v73
	v_cvt_pk_bf16_f32 v184, v66, v67
	v_cvt_pk_bf16_f32 v185, v68, v69
	global_store_dwordx4 v245, v[182:185], s[68:69] offset:256
	v_fmac_f32_e32 v78, v70, v70
	v_fmac_f32_e32 v78, v71, v71
	v_fmac_f32_e32 v78, v72, v72
	v_fmac_f32_e32 v78, v73, v73
	v_fmac_f32_e32 v78, v66, v66
	v_fmac_f32_e32 v78, v67, v67
	v_fmac_f32_e32 v78, v68, v68
	v_fmac_f32_e32 v78, v69, v69
	s_add_u32 s68, s24, 0x100000
	s_addc_u32 s69, s25, 0
	s_waitcnt vmcnt(15)
	v_lshlrev_b32_e32 v246, 16, v188
	v_and_b32_e32 v247, 0xffff0000, v188
	v_pk_add_f32 v[62:63], v[62:63], v[246:247]
	v_lshlrev_b32_e32 v246, 16, v189
	v_and_b32_e32 v247, 0xffff0000, v189
	v_pk_add_f32 v[64:65], v[64:65], v[246:247]
	v_lshlrev_b32_e32 v246, 16, v190
	v_and_b32_e32 v247, 0xffff0000, v190
	v_pk_add_f32 v[58:59], v[58:59], v[246:247]
	v_lshlrev_b32_e32 v246, 16, v191
	v_and_b32_e32 v247, 0xffff0000, v191
	v_pk_add_f32 v[60:61], v[60:61], v[246:247]
	v_cvt_pk_bf16_f32 v188, v62, v63
	v_cvt_pk_bf16_f32 v189, v64, v65
	v_cvt_pk_bf16_f32 v190, v58, v59
	v_cvt_pk_bf16_f32 v191, v60, v61
	global_store_dwordx4 v245, v[188:191], s[68:69]
	v_mul_f32_e32 v62, v62, v62
	v_fmac_f32_e32 v62, v63, v63
	v_fmac_f32_e32 v62, v64, v64
	v_fmac_f32_e32 v62, v65, v65
	v_fmac_f32_e32 v62, v58, v58
	v_fmac_f32_e32 v62, v59, v59
	v_fmac_f32_e32 v62, v60, v60
	v_fmac_f32_e32 v62, v61, v61
	s_waitcnt vmcnt(15)
	v_lshlrev_b32_e32 v246, 16, v192
	v_and_b32_e32 v247, 0xffff0000, v192
	v_pk_add_f32 v[54:55], v[54:55], v[246:247]
	v_lshlrev_b32_e32 v246, 16, v193
	v_and_b32_e32 v247, 0xffff0000, v193
	v_pk_add_f32 v[56:57], v[56:57], v[246:247]
	v_lshlrev_b32_e32 v246, 16, v194
	v_and_b32_e32 v247, 0xffff0000, v194
	v_pk_add_f32 v[50:51], v[50:51], v[246:247]
	v_lshlrev_b32_e32 v246, 16, v195
	v_and_b32_e32 v247, 0xffff0000, v195
	v_pk_add_f32 v[52:53], v[52:53], v[246:247]
	v_cvt_pk_bf16_f32 v192, v54, v55
	v_cvt_pk_bf16_f32 v193, v56, v57
	v_cvt_pk_bf16_f32 v194, v50, v51
	v_cvt_pk_bf16_f32 v195, v52, v53
	global_store_dwordx4 v245, v[192:195], s[68:69] offset:256
	v_fmac_f32_e32 v62, v54, v54
	v_fmac_f32_e32 v62, v55, v55
	v_fmac_f32_e32 v62, v56, v56
	v_fmac_f32_e32 v62, v57, v57
	v_fmac_f32_e32 v62, v50, v50
	v_fmac_f32_e32 v62, v51, v51
	v_fmac_f32_e32 v62, v52, v52
	v_fmac_f32_e32 v62, v53, v53
	s_add_u32 s68, s24, 0x120000
	s_addc_u32 s69, s25, 0
	s_waitcnt vmcnt(15)
	v_lshlrev_b32_e32 v246, 16, v196
	v_and_b32_e32 v247, 0xffff0000, v196
	v_pk_add_f32 v[46:47], v[46:47], v[246:247]
	v_lshlrev_b32_e32 v246, 16, v197
	v_and_b32_e32 v247, 0xffff0000, v197
	v_pk_add_f32 v[48:49], v[48:49], v[246:247]
	v_lshlrev_b32_e32 v246, 16, v198
	v_and_b32_e32 v247, 0xffff0000, v198
	v_pk_add_f32 v[42:43], v[42:43], v[246:247]
	v_lshlrev_b32_e32 v246, 16, v199
	v_and_b32_e32 v247, 0xffff0000, v199
	v_pk_add_f32 v[44:45], v[44:45], v[246:247]
	v_cvt_pk_bf16_f32 v196, v46, v47
	v_cvt_pk_bf16_f32 v197, v48, v49
	v_cvt_pk_bf16_f32 v198, v42, v43
	v_cvt_pk_bf16_f32 v199, v44, v45
	global_store_dwordx4 v245, v[196:199], s[68:69]
	v_mul_f32_e32 v46, v46, v46
	v_fmac_f32_e32 v46, v47, v47
	v_fmac_f32_e32 v46, v48, v48
	v_fmac_f32_e32 v46, v49, v49
	v_fmac_f32_e32 v46, v42, v42
	v_fmac_f32_e32 v46, v43, v43
	v_fmac_f32_e32 v46, v44, v44
	v_fmac_f32_e32 v46, v45, v45
	s_waitcnt vmcnt(15)
	v_lshlrev_b32_e32 v246, 16, v200
	v_and_b32_e32 v247, 0xffff0000, v200
	v_pk_add_f32 v[38:39], v[38:39], v[246:247]
	v_lshlrev_b32_e32 v246, 16, v201
	v_and_b32_e32 v247, 0xffff0000, v201
	v_pk_add_f32 v[40:41], v[40:41], v[246:247]
	v_lshlrev_b32_e32 v246, 16, v202
	v_and_b32_e32 v247, 0xffff0000, v202
	v_pk_add_f32 v[34:35], v[34:35], v[246:247]
	v_lshlrev_b32_e32 v246, 16, v203
	v_and_b32_e32 v247, 0xffff0000, v203
	v_pk_add_f32 v[36:37], v[36:37], v[246:247]
	v_cvt_pk_bf16_f32 v200, v38, v39
	v_cvt_pk_bf16_f32 v201, v40, v41
	v_cvt_pk_bf16_f32 v202, v34, v35
	v_cvt_pk_bf16_f32 v203, v36, v37
	global_store_dwordx4 v245, v[200:203], s[68:69] offset:256
	v_fmac_f32_e32 v46, v38, v38
	v_fmac_f32_e32 v46, v39, v39
	v_fmac_f32_e32 v46, v40, v40
	v_fmac_f32_e32 v46, v41, v41
	v_fmac_f32_e32 v46, v34, v34
	v_fmac_f32_e32 v46, v35, v35
	v_fmac_f32_e32 v46, v36, v36
	v_fmac_f32_e32 v46, v37, v37
	s_add_u32 s68, s24, 0x140000
	s_addc_u32 s69, s25, 0
	s_waitcnt vmcnt(15)
	v_lshlrev_b32_e32 v246, 16, v204
	v_and_b32_e32 v247, 0xffff0000, v204
	v_pk_add_f32 v[30:31], v[30:31], v[246:247]
	v_lshlrev_b32_e32 v246, 16, v205
	v_and_b32_e32 v247, 0xffff0000, v205
	v_pk_add_f32 v[32:33], v[32:33], v[246:247]
	v_lshlrev_b32_e32 v246, 16, v206
	v_and_b32_e32 v247, 0xffff0000, v206
	v_pk_add_f32 v[26:27], v[26:27], v[246:247]
	v_lshlrev_b32_e32 v246, 16, v207
	v_and_b32_e32 v247, 0xffff0000, v207
	v_pk_add_f32 v[28:29], v[28:29], v[246:247]
	v_cvt_pk_bf16_f32 v204, v30, v31
	v_cvt_pk_bf16_f32 v205, v32, v33
	v_cvt_pk_bf16_f32 v206, v26, v27
	v_cvt_pk_bf16_f32 v207, v28, v29
	global_store_dwordx4 v245, v[204:207], s[68:69]
	v_mul_f32_e32 v30, v30, v30
	v_fmac_f32_e32 v30, v31, v31
	v_fmac_f32_e32 v30, v32, v32
	v_fmac_f32_e32 v30, v33, v33
	v_fmac_f32_e32 v30, v26, v26
	v_fmac_f32_e32 v30, v27, v27
	v_fmac_f32_e32 v30, v28, v28
	v_fmac_f32_e32 v30, v29, v29
	s_waitcnt vmcnt(15)
	v_lshlrev_b32_e32 v246, 16, v208
	v_and_b32_e32 v247, 0xffff0000, v208
	v_pk_add_f32 v[22:23], v[22:23], v[246:247]
	v_lshlrev_b32_e32 v246, 16, v209
	v_and_b32_e32 v247, 0xffff0000, v209
	v_pk_add_f32 v[24:25], v[24:25], v[246:247]
	v_lshlrev_b32_e32 v246, 16, v210
	v_and_b32_e32 v247, 0xffff0000, v210
	v_pk_add_f32 v[18:19], v[18:19], v[246:247]
	v_lshlrev_b32_e32 v246, 16, v211
	v_and_b32_e32 v247, 0xffff0000, v211
	v_pk_add_f32 v[20:21], v[20:21], v[246:247]
	v_cvt_pk_bf16_f32 v208, v22, v23
	v_cvt_pk_bf16_f32 v209, v24, v25
	v_cvt_pk_bf16_f32 v210, v18, v19
	v_cvt_pk_bf16_f32 v211, v20, v21
	global_store_dwordx4 v245, v[208:211], s[68:69] offset:256
	v_fmac_f32_e32 v30, v22, v22
	v_fmac_f32_e32 v30, v23, v23
	v_fmac_f32_e32 v30, v24, v24
	v_fmac_f32_e32 v30, v25, v25
	v_fmac_f32_e32 v30, v18, v18
	v_fmac_f32_e32 v30, v19, v19
	v_fmac_f32_e32 v30, v20, v20
	v_fmac_f32_e32 v30, v21, v21
	s_add_u32 s68, s24, 0x160000
	s_addc_u32 s69, s25, 0
	s_waitcnt vmcnt(15)
	v_lshlrev_b32_e32 v246, 16, v212
	v_and_b32_e32 v247, 0xffff0000, v212
	v_pk_add_f32 v[14:15], v[14:15], v[246:247]
	v_lshlrev_b32_e32 v246, 16, v213
	v_and_b32_e32 v247, 0xffff0000, v213
	v_pk_add_f32 v[16:17], v[16:17], v[246:247]
	v_lshlrev_b32_e32 v246, 16, v214
	v_and_b32_e32 v247, 0xffff0000, v214
	v_pk_add_f32 v[10:11], v[10:11], v[246:247]
	v_lshlrev_b32_e32 v246, 16, v215
	v_and_b32_e32 v247, 0xffff0000, v215
	v_pk_add_f32 v[12:13], v[12:13], v[246:247]
	v_cvt_pk_bf16_f32 v212, v14, v15
	v_cvt_pk_bf16_f32 v213, v16, v17
	v_cvt_pk_bf16_f32 v214, v10, v11
	v_cvt_pk_bf16_f32 v215, v12, v13
	global_store_dwordx4 v245, v[212:215], s[68:69]
	v_mul_f32_e32 v14, v14, v14
	v_fmac_f32_e32 v14, v15, v15
	v_fmac_f32_e32 v14, v16, v16
	v_fmac_f32_e32 v14, v17, v17
	v_fmac_f32_e32 v14, v10, v10
	v_fmac_f32_e32 v14, v11, v11
	v_fmac_f32_e32 v14, v12, v12
	v_fmac_f32_e32 v14, v13, v13
	s_waitcnt vmcnt(15)
	v_lshlrev_b32_e32 v246, 16, v216
	v_and_b32_e32 v247, 0xffff0000, v216
	v_pk_add_f32 v[6:7], v[6:7], v[246:247]
	v_lshlrev_b32_e32 v246, 16, v217
	v_and_b32_e32 v247, 0xffff0000, v217
	v_pk_add_f32 v[8:9], v[8:9], v[246:247]
	v_lshlrev_b32_e32 v246, 16, v218
	v_and_b32_e32 v247, 0xffff0000, v218
	v_pk_add_f32 v[2:3], v[2:3], v[246:247]
	v_lshlrev_b32_e32 v246, 16, v219
	v_and_b32_e32 v247, 0xffff0000, v219
	v_pk_add_f32 v[4:5], v[4:5], v[246:247]
	v_cvt_pk_bf16_f32 v216, v6, v7
	v_cvt_pk_bf16_f32 v217, v8, v9
	v_cvt_pk_bf16_f32 v218, v2, v3
	v_cvt_pk_bf16_f32 v219, v4, v5
	global_store_dwordx4 v245, v[216:219], s[68:69] offset:256
	v_fmac_f32_e32 v14, v6, v6
	v_fmac_f32_e32 v14, v7, v7
	v_fmac_f32_e32 v14, v8, v8
	v_fmac_f32_e32 v14, v9, v9
	v_fmac_f32_e32 v14, v2, v2
	v_fmac_f32_e32 v14, v3, v3
	v_fmac_f32_e32 v14, v4, v4
	v_fmac_f32_e32 v14, v5, v5
	v_mbcnt_lo_u32_b32 v246, -1, 0
	v_mbcnt_hi_u32_b32 v246, -1, v246
	v_xor_b32_e32 v247, 32, v246
	v_xor_b32_e32 v246, 16, v246
	v_lshlrev_b32_e32 v246, 2, v246
	v_lshlrev_b32_e32 v247, 2, v247
	ds_bpermute_b32 v127, v246, v126
	ds_bpermute_b32 v111, v246, v110
	ds_bpermute_b32 v95, v246, v94
	ds_bpermute_b32 v79, v246, v78
	ds_bpermute_b32 v63, v246, v62
	ds_bpermute_b32 v47, v246, v46
	ds_bpermute_b32 v31, v246, v30
	ds_bpermute_b32 v15, v246, v14
	s_waitcnt lgkmcnt(0)
	v_add_f32_e32 v126, v126, v127
	v_add_f32_e32 v110, v110, v111
	v_add_f32_e32 v94, v94, v95
	v_add_f32_e32 v78, v78, v79
	v_add_f32_e32 v62, v62, v63
	v_add_f32_e32 v46, v46, v47
	v_add_f32_e32 v30, v30, v31
	v_add_f32_e32 v14, v14, v15
	ds_bpermute_b32 v127, v247, v126
	ds_bpermute_b32 v111, v247, v110
	ds_bpermute_b32 v95, v247, v94
	ds_bpermute_b32 v79, v247, v78
	ds_bpermute_b32 v63, v247, v62
	ds_bpermute_b32 v47, v247, v46
	ds_bpermute_b32 v31, v247, v30
	ds_bpermute_b32 v15, v247, v14
	s_waitcnt lgkmcnt(0)
	v_add_f32_e32 v126, v126, v127
	v_add_f32_e32 v110, v110, v111
	v_add_f32_e32 v94, v94, v95
	v_add_f32_e32 v78, v78, v79
	v_add_f32_e32 v62, v62, v63
	v_add_f32_e32 v46, v46, v47
	v_add_f32_e32 v30, v30, v31
	v_add_f32_e32 v14, v14, v15
	v_lshl_add_u32 v246, s70, 8, v146
	v_lshlrev_b32_e32 v246, 2, v246
	s_and_saveexec_b64 s[68:69], s[8:9]
	global_atomic_add_f32 v246, v126, s[42:43]
	global_atomic_add_f32 v246, v110, s[42:43] offset:64
	global_atomic_add_f32 v246, v94, s[42:43] offset:128
	global_atomic_add_f32 v246, v78, s[42:43] offset:192
	global_atomic_add_f32 v246, v62, s[42:43] offset:512
	global_atomic_add_f32 v246, v46, s[42:43] offset:576
	global_atomic_add_f32 v246, v30, s[42:43] offset:640
	global_atomic_add_f32 v246, v14, s[42:43] offset:704
	s_mov_b64 exec, s[68:69]
	s_andn2_b64 vcc, exec, s[46:47]
	s_mov_b64 s[46:47], -1
	s_cbranch_vccnz .LBB0_1976
	s_andn2_b64 vcc, exec, s[10:11]
	s_cbranch_vccnz .LBB0_1975
	s_barrier
	s_branch .LBB0_1975

.LBB0_2118:
	ds_read_b128 v[142:145], v149
	ds_read_b128 v[154:157], v149 offset:1024
	ds_read_b128 v[158:161], v149 offset:2048
	ds_read_b128 v[162:165], v149 offset:3072
	ds_read_b128 v[166:169], v150
	ds_read_b128 v[170:173], v150 offset:1024
	ds_read_b128 v[174:177], v150 offset:2048
	ds_read_b128 v[178:181], v150 offset:3072
	s_add_u32 s16, s40, 0xffd50080
	s_addc_u32 s17, s41, -1
	s_cmpk_eq_i32 s71, 0xa8
	s_cselect_b32 s45, s37, s17
	s_cselect_b32 s44, s36, s16
	s_cselect_b32 s43, s39, s70
	s_cselect_b32 s42, s38, s69
	v_lshl_add_u64 v[214:215], s[40:41], 0, v[140:141]
	s_add_i32 m0, s27, 0xc000
	ds_read_b128 v[182:185], v151
	ds_read_b128 v[186:189], v151 offset:1024
	ds_read_b128 v[190:193], v151 offset:2048
	ds_read_b128 v[194:197], v151 offset:3072
	ds_read_b128 v[198:201], v151 offset:4096
	ds_read_b128 v[202:205], v151 offset:5120
	ds_read_b128 v[206:209], v151 offset:6144
	ds_read_b128 v[210:213], v151 offset:7168
	global_load_lds_dwordx4 v[214:215], off
	v_lshl_add_u64 v[214:215], s[40:41], 0, v[138:139]
	s_add_i32 m0, s27, 0xe000
	s_nop 0
	global_load_lds_dwordx4 v[214:215], off
	s_waitcnt vmcnt(8)
	s_waitcnt lgkmcnt(0)
	s_barrier
	s_setprio 1
	s_waitcnt lgkmcnt(0)
	v_mfma_f32_16x16x32_bf16 v[126:129], v[142:145], v[182:185], v[126:129]
	v_mfma_f32_16x16x32_bf16 v[122:125], v[158:161], v[182:185], v[122:125]
	v_mfma_f32_16x16x32_bf16 v[110:113], v[142:145], v[190:193], v[110:113]
	v_mfma_f32_16x16x32_bf16 v[106:109], v[158:161], v[190:193], v[106:109]
	v_mfma_f32_16x16x32_bf16 v[94:97], v[142:145], v[198:201], v[94:97]
	v_mfma_f32_16x16x32_bf16 v[90:93], v[158:161], v[198:201], v[90:93]
	v_mfma_f32_16x16x32_bf16 v[78:81], v[142:145], v[206:209], v[78:81]
	v_mfma_f32_16x16x32_bf16 v[74:77], v[158:161], v[206:209], v[74:77]
	v_mfma_f32_16x16x32_bf16 v[126:129], v[154:157], v[186:189], v[126:129]
	v_mfma_f32_16x16x32_bf16 v[122:125], v[162:165], v[186:189], v[122:125]
	v_mfma_f32_16x16x32_bf16 v[110:113], v[154:157], v[194:197], v[110:113]
	v_mfma_f32_16x16x32_bf16 v[106:109], v[162:165], v[194:197], v[106:109]
	v_mfma_f32_16x16x32_bf16 v[94:97], v[154:157], v[202:205], v[94:97]
	v_mfma_f32_16x16x32_bf16 v[90:93], v[162:165], v[202:205], v[90:93]
	v_mfma_f32_16x16x32_bf16 v[78:81], v[154:157], v[210:213], v[78:81]
	v_mfma_f32_16x16x32_bf16 v[74:77], v[162:165], v[210:213], v[74:77]
	s_setprio 0
	s_setprio 1
	v_mfma_f32_16x16x32_bf16 v[118:121], v[166:169], v[182:185], v[118:121]
	v_mfma_f32_16x16x32_bf16 v[114:117], v[174:177], v[182:185], v[114:117]
	v_mfma_f32_16x16x32_bf16 v[102:105], v[166:169], v[190:193], v[102:105]
	v_mfma_f32_16x16x32_bf16 v[98:101], v[174:177], v[190:193], v[98:101]
	v_mfma_f32_16x16x32_bf16 v[86:89], v[166:169], v[198:201], v[86:89]
	v_mfma_f32_16x16x32_bf16 v[82:85], v[174:177], v[198:201], v[82:85]
	v_mfma_f32_16x16x32_bf16 v[70:73], v[166:169], v[206:209], v[70:73]
	v_mfma_f32_16x16x32_bf16 v[66:69], v[174:177], v[206:209], v[66:69]
	v_mfma_f32_16x16x32_bf16 v[118:121], v[170:173], v[186:189], v[118:121]
	v_mfma_f32_16x16x32_bf16 v[114:117], v[178:181], v[186:189], v[114:117]
	v_mfma_f32_16x16x32_bf16 v[102:105], v[170:173], v[194:197], v[102:105]
	v_mfma_f32_16x16x32_bf16 v[98:101], v[178:181], v[194:197], v[98:101]
	v_mfma_f32_16x16x32_bf16 v[86:89], v[170:173], v[202:205], v[86:89]
	v_mfma_f32_16x16x32_bf16 v[82:85], v[178:181], v[202:205], v[82:85]
	v_mfma_f32_16x16x32_bf16 v[70:73], v[170:173], v[210:213], v[70:73]
	v_mfma_f32_16x16x32_bf16 v[66:69], v[178:181], v[210:213], v[66:69]
	s_setprio 0
	s_barrier
	s_add_i32 s16, s63, s26
	v_lshl_add_u64 v[214:215], s[42:43], 0, v[132:133]
	s_mov_b32 m0, s16
	ds_read_b128 v[182:185], v151 offset:16384
	ds_read_b128 v[186:189], v151 offset:17408
	ds_read_b128 v[190:193], v151 offset:18432
	ds_read_b128 v[194:197], v151 offset:19456
	ds_read_b128 v[198:201], v151 offset:20480
	ds_read_b128 v[202:205], v151 offset:21504
	ds_read_b128 v[206:209], v151 offset:22528
	ds_read_b128 v[210:213], v151 offset:23552
	global_load_lds_dwordx4 v[214:215], off
	s_add_i32 m0, s16, 0x2000
	s_add_u32 s16, s42, 0x2b0000
	v_lshl_add_u64 v[216:217], s[42:43], 0, v[136:137]
	s_addc_u32 s17, s43, 0
	s_add_i32 s72, s64, s26
	global_load_lds_dwordx4 v[216:217], off
	v_lshl_add_u64 v[218:219], s[16:17], 0, v[132:133]
	s_mov_b32 m0, s72
	v_lshl_add_u64 v[220:221], s[44:45], 0, v[134:135]
	global_load_lds_dwordx4 v[218:219], off
	v_lshl_add_u64 v[218:219], s[16:17], 0, v[136:137]
	s_add_i32 m0, s72, 0x2000
	s_nop 0
	global_load_lds_dwordx4 v[218:219], off
	v_lshl_add_u64 v[218:219], s[44:45], 0, v[130:131]
	s_mov_b32 m0, s27
	s_nop 0
	global_load_lds_dwordx4 v[218:219], off
	s_mov_b32 m0, s28
	s_nop 0
	global_load_lds_dwordx4 v[220:221], off
	s_waitcnt vmcnt(8)
	s_waitcnt lgkmcnt(0)
	s_barrier
	s_setprio 1
	s_waitcnt lgkmcnt(0)
	v_mfma_f32_16x16x32_bf16 v[62:65], v[142:145], v[182:185], v[62:65]
	v_mfma_f32_16x16x32_bf16 v[58:61], v[158:161], v[182:185], v[58:61]
	v_mfma_f32_16x16x32_bf16 v[46:49], v[142:145], v[190:193], v[46:49]
	v_mfma_f32_16x16x32_bf16 v[42:45], v[158:161], v[190:193], v[42:45]
	v_mfma_f32_16x16x32_bf16 v[30:33], v[142:145], v[198:201], v[30:33]
	v_mfma_f32_16x16x32_bf16 v[26:29], v[158:161], v[198:201], v[26:29]
	v_mfma_f32_16x16x32_bf16 v[14:17], v[142:145], v[206:209], v[14:17]
	v_mfma_f32_16x16x32_bf16 v[10:13], v[158:161], v[206:209], v[10:13]
	v_mfma_f32_16x16x32_bf16 v[62:65], v[154:157], v[186:189], v[62:65]
	v_mfma_f32_16x16x32_bf16 v[58:61], v[162:165], v[186:189], v[58:61]
	v_mfma_f32_16x16x32_bf16 v[46:49], v[154:157], v[194:197], v[46:49]
	v_mfma_f32_16x16x32_bf16 v[42:45], v[162:165], v[194:197], v[42:45]
	v_mfma_f32_16x16x32_bf16 v[30:33], v[154:157], v[202:205], v[30:33]
	v_mfma_f32_16x16x32_bf16 v[26:29], v[162:165], v[202:205], v[26:29]
	v_mfma_f32_16x16x32_bf16 v[14:17], v[154:157], v[210:213], v[14:17]
	v_mfma_f32_16x16x32_bf16 v[10:13], v[162:165], v[210:213], v[10:13]
	s_setprio 0
	s_setprio 1
	v_mfma_f32_16x16x32_bf16 v[54:57], v[166:169], v[182:185], v[54:57]
	v_mfma_f32_16x16x32_bf16 v[50:53], v[174:177], v[182:185], v[50:53]
	v_mfma_f32_16x16x32_bf16 v[38:41], v[166:169], v[190:193], v[38:41]
	v_mfma_f32_16x16x32_bf16 v[34:37], v[174:177], v[190:193], v[34:37]
	v_mfma_f32_16x16x32_bf16 v[22:25], v[166:169], v[198:201], v[22:25]
	v_mfma_f32_16x16x32_bf16 v[18:21], v[174:177], v[198:201], v[18:21]
	v_mfma_f32_16x16x32_bf16 v[6:9], v[166:169], v[206:209], v[6:9]
	v_mfma_f32_16x16x32_bf16 v[2:5], v[174:177], v[206:209], v[2:5]
	v_mfma_f32_16x16x32_bf16 v[54:57], v[170:173], v[186:189], v[54:57]
	v_mfma_f32_16x16x32_bf16 v[50:53], v[178:181], v[186:189], v[50:53]
	v_mfma_f32_16x16x32_bf16 v[38:41], v[170:173], v[194:197], v[38:41]
	v_mfma_f32_16x16x32_bf16 v[34:37], v[178:181], v[194:197], v[34:37]
	v_mfma_f32_16x16x32_bf16 v[22:25], v[170:173], v[202:205], v[22:25]
	v_mfma_f32_16x16x32_bf16 v[18:21], v[178:181], v[202:205], v[18:21]
	v_mfma_f32_16x16x32_bf16 v[6:9], v[170:173], v[210:213], v[6:9]
	v_mfma_f32_16x16x32_bf16 v[2:5], v[178:181], v[210:213], v[2:5]
	s_setprio 0
	s_barrier
	s_add_i32 s72, 0, 0x18000
	v_add_u32_e32 v153, s72, v147
	s_add_i32 s73, 0, 0x1c000
	ds_read_b128 v[142:145], v153
	ds_read_b128 v[154:157], v153 offset:1024
	ds_read_b128 v[158:161], v153 offset:2048
	ds_read_b128 v[162:165], v153 offset:3072
	v_add_u32_e32 v153, s73, v147
	ds_read_b128 v[166:169], v153
	ds_read_b128 v[170:173], v153 offset:1024
	ds_read_b128 v[174:177], v153 offset:2048
	ds_read_b128 v[178:181], v153 offset:3072
	s_add_u32 s16, s44, 0x2b0000
	s_addc_u32 s17, s45, 0
	s_mov_b32 m0, s29
	v_lshl_add_u64 v[222:223], s[16:17], 0, v[130:131]
	ds_read_b128 v[182:185], v151 offset:32768
	ds_read_b128 v[186:189], v151 offset:33792
	ds_read_b128 v[190:193], v151 offset:34816
	ds_read_b128 v[194:197], v151 offset:35840
	ds_read_b128 v[198:201], v151 offset:36864
	ds_read_b128 v[202:205], v151 offset:37888
	ds_read_b128 v[206:209], v151 offset:38912
	ds_read_b128 v[210:213], v151 offset:39936
	global_load_lds_dwordx4 v[222:223], off
	v_lshl_add_u64 v[222:223], s[16:17], 0, v[134:135]
	s_mov_b32 m0, s56
	s_nop 0
	global_load_lds_dwordx4 v[222:223], off
	s_waitcnt vmcnt(8)
	s_waitcnt lgkmcnt(0)
	s_barrier
	s_setprio 1
	s_waitcnt lgkmcnt(0)
	v_mfma_f32_16x16x32_bf16 v[126:129], v[142:145], v[182:185], v[126:129]
	v_mfma_f32_16x16x32_bf16 v[122:125], v[158:161], v[182:185], v[122:125]
	v_mfma_f32_16x16x32_bf16 v[110:113], v[142:145], v[190:193], v[110:113]
	v_mfma_f32_16x16x32_bf16 v[106:109], v[158:161], v[190:193], v[106:109]
	v_mfma_f32_16x16x32_bf16 v[94:97], v[142:145], v[198:201], v[94:97]
	v_mfma_f32_16x16x32_bf16 v[90:93], v[158:161], v[198:201], v[90:93]
	v_mfma_f32_16x16x32_bf16 v[78:81], v[142:145], v[206:209], v[78:81]
	v_mfma_f32_16x16x32_bf16 v[74:77], v[158:161], v[206:209], v[74:77]
	v_mfma_f32_16x16x32_bf16 v[126:129], v[154:157], v[186:189], v[126:129]
	v_mfma_f32_16x16x32_bf16 v[122:125], v[162:165], v[186:189], v[122:125]
	v_mfma_f32_16x16x32_bf16 v[110:113], v[154:157], v[194:197], v[110:113]
	v_mfma_f32_16x16x32_bf16 v[106:109], v[162:165], v[194:197], v[106:109]
	v_mfma_f32_16x16x32_bf16 v[94:97], v[154:157], v[202:205], v[94:97]
	v_mfma_f32_16x16x32_bf16 v[90:93], v[162:165], v[202:205], v[90:93]
	v_mfma_f32_16x16x32_bf16 v[78:81], v[154:157], v[210:213], v[78:81]
	v_mfma_f32_16x16x32_bf16 v[74:77], v[162:165], v[210:213], v[74:77]
	s_setprio 0
	s_setprio 1
	v_mfma_f32_16x16x32_bf16 v[118:121], v[166:169], v[182:185], v[118:121]
	v_mfma_f32_16x16x32_bf16 v[114:117], v[174:177], v[182:185], v[114:117]
	v_mfma_f32_16x16x32_bf16 v[102:105], v[166:169], v[190:193], v[102:105]
	v_mfma_f32_16x16x32_bf16 v[98:101], v[174:177], v[190:193], v[98:101]
	v_mfma_f32_16x16x32_bf16 v[86:89], v[166:169], v[198:201], v[86:89]
	v_mfma_f32_16x16x32_bf16 v[82:85], v[174:177], v[198:201], v[82:85]
	v_mfma_f32_16x16x32_bf16 v[70:73], v[166:169], v[206:209], v[70:73]
	v_mfma_f32_16x16x32_bf16 v[66:69], v[174:177], v[206:209], v[66:69]
	v_mfma_f32_16x16x32_bf16 v[118:121], v[170:173], v[186:189], v[118:121]
	v_mfma_f32_16x16x32_bf16 v[114:117], v[178:181], v[186:189], v[114:117]
	v_mfma_f32_16x16x32_bf16 v[102:105], v[170:173], v[194:197], v[102:105]
	v_mfma_f32_16x16x32_bf16 v[98:101], v[178:181], v[194:197], v[98:101]
	v_mfma_f32_16x16x32_bf16 v[86:89], v[170:173], v[202:205], v[86:89]
	v_mfma_f32_16x16x32_bf16 v[82:85], v[178:181], v[202:205], v[82:85]
	v_mfma_f32_16x16x32_bf16 v[70:73], v[170:173], v[210:213], v[70:73]
	v_mfma_f32_16x16x32_bf16 v[66:69], v[178:181], v[210:213], v[66:69]
	s_setprio 0
	s_barrier
	s_add_i32 s16, s72, s26
	v_lshl_add_u64 v[214:215], v[214:215], 0, s[14:15]
	s_mov_b32 m0, s16
	ds_read_b128 v[182:185], v151 offset:49152
	ds_read_b128 v[186:189], v151 offset:50176
	ds_read_b128 v[190:193], v151 offset:51200
	ds_read_b128 v[194:197], v151 offset:52224
	ds_read_b128 v[198:201], v151 offset:53248
	ds_read_b128 v[202:205], v151 offset:54272
	ds_read_b128 v[206:209], v151 offset:55296
	ds_read_b128 v[210:213], v151 offset:56320
	global_load_lds_dwordx4 v[214:215], off
	s_add_i32 m0, s16, 0x2000
	s_add_u32 s16, s42, 0x2b0080
	v_lshl_add_u64 v[214:215], v[216:217], 0, s[14:15]
	s_addc_u32 s17, s43, 0
	s_add_i32 s42, s73, s26
	global_load_lds_dwordx4 v[214:215], off
	v_lshl_add_u64 v[214:215], s[16:17], 0, v[132:133]
	s_mov_b32 m0, s42
	s_nop 0
	global_load_lds_dwordx4 v[214:215], off
	v_lshl_add_u64 v[214:215], s[16:17], 0, v[136:137]
	s_add_i32 m0, s42, 0x2000
	s_nop 0
	global_load_lds_dwordx4 v[214:215], off
	v_lshl_add_u64 v[214:215], v[218:219], 0, s[14:15]
	s_mov_b32 m0, s60
	s_nop 0
	global_load_lds_dwordx4 v[214:215], off
	v_lshl_add_u64 v[214:215], v[220:221], 0, s[14:15]
	s_mov_b32 m0, s61
	s_nop 0
	global_load_lds_dwordx4 v[214:215], off
	s_waitcnt vmcnt(8)
	s_waitcnt lgkmcnt(0)
	s_barrier
	s_setprio 1
	s_waitcnt lgkmcnt(0)
	v_mfma_f32_16x16x32_bf16 v[62:65], v[142:145], v[182:185], v[62:65]
	v_mfma_f32_16x16x32_bf16 v[58:61], v[158:161], v[182:185], v[58:61]
	v_mfma_f32_16x16x32_bf16 v[46:49], v[142:145], v[190:193], v[46:49]
	v_mfma_f32_16x16x32_bf16 v[42:45], v[158:161], v[190:193], v[42:45]
	v_mfma_f32_16x16x32_bf16 v[30:33], v[142:145], v[198:201], v[30:33]
	v_mfma_f32_16x16x32_bf16 v[26:29], v[158:161], v[198:201], v[26:29]
	v_mfma_f32_16x16x32_bf16 v[14:17], v[142:145], v[206:209], v[14:17]
	v_mfma_f32_16x16x32_bf16 v[10:13], v[158:161], v[206:209], v[10:13]
	v_mfma_f32_16x16x32_bf16 v[62:65], v[154:157], v[186:189], v[62:65]
	v_mfma_f32_16x16x32_bf16 v[58:61], v[162:165], v[186:189], v[58:61]
	v_mfma_f32_16x16x32_bf16 v[46:49], v[154:157], v[194:197], v[46:49]
	v_mfma_f32_16x16x32_bf16 v[42:45], v[162:165], v[194:197], v[42:45]
	v_mfma_f32_16x16x32_bf16 v[30:33], v[154:157], v[202:205], v[30:33]
	v_mfma_f32_16x16x32_bf16 v[26:29], v[162:165], v[202:205], v[26:29]
	v_mfma_f32_16x16x32_bf16 v[14:17], v[154:157], v[210:213], v[14:17]
	v_mfma_f32_16x16x32_bf16 v[10:13], v[162:165], v[210:213], v[10:13]
	s_setprio 0
	s_setprio 1
	v_mfma_f32_16x16x32_bf16 v[54:57], v[166:169], v[182:185], v[54:57]
	v_mfma_f32_16x16x32_bf16 v[50:53], v[174:177], v[182:185], v[50:53]
	v_mfma_f32_16x16x32_bf16 v[38:41], v[166:169], v[190:193], v[38:41]
	v_mfma_f32_16x16x32_bf16 v[34:37], v[174:177], v[190:193], v[34:37]
	v_mfma_f32_16x16x32_bf16 v[22:25], v[166:169], v[198:201], v[22:25]
	v_mfma_f32_16x16x32_bf16 v[18:21], v[174:177], v[198:201], v[18:21]
	v_mfma_f32_16x16x32_bf16 v[6:9], v[166:169], v[206:209], v[6:9]
	v_mfma_f32_16x16x32_bf16 v[2:5], v[174:177], v[206:209], v[2:5]
	v_mfma_f32_16x16x32_bf16 v[54:57], v[170:173], v[186:189], v[54:57]
	v_mfma_f32_16x16x32_bf16 v[50:53], v[178:181], v[186:189], v[50:53]
	v_mfma_f32_16x16x32_bf16 v[38:41], v[170:173], v[194:197], v[38:41]
	v_mfma_f32_16x16x32_bf16 v[34:37], v[178:181], v[194:197], v[34:37]
	v_mfma_f32_16x16x32_bf16 v[22:25], v[170:173], v[202:205], v[22:25]
	v_mfma_f32_16x16x32_bf16 v[18:21], v[178:181], v[202:205], v[18:21]
	v_mfma_f32_16x16x32_bf16 v[6:9], v[170:173], v[210:213], v[6:9]
	v_mfma_f32_16x16x32_bf16 v[2:5], v[178:181], v[210:213], v[2:5]
	s_setprio 0
	s_barrier
	s_add_i32 s71, s71, 2
	s_add_u32 s69, s69, 0x100
	s_addc_u32 s70, s70, 0
	s_add_u32 s40, s40, 0x100
	s_addc_u32 s41, s41, 0
	s_cmpk_gt_u32 s71, 0xa9
	s_cbranch_scc0 .LBB0_2118
	v_lshl_add_u32 v245, s68, 8, v146
	v_lshl_or_b32 v246, s67, 8, v148
	v_lshlrev_b32_e32 v245, 13, v245
	v_lshl_add_u32 v245, v246, 1, v245
	global_load_dwordx4 v[142:145], v245, s[24:25]
	global_load_dwordx4 v[154:157], v245, s[24:25] offset:256
	s_add_u32 s40, s24, 0x20000
	s_addc_u32 s41, s25, 0
	global_load_dwordx4 v[158:161], v245, s[40:41]
	global_load_dwordx4 v[162:165], v245, s[40:41] offset:256
	s_add_u32 s40, s24, 0x40000
	s_addc_u32 s41, s25, 0
	global_load_dwordx4 v[166:169], v245, s[40:41]
	global_load_dwordx4 v[170:173], v245, s[40:41] offset:256
	s_add_u32 s40, s24, 0x60000
	s_addc_u32 s41, s25, 0
	global_load_dwordx4 v[174:177], v245, s[40:41]
	global_load_dwordx4 v[178:181], v245, s[40:41] offset:256
	s_add_u32 s40, s24, 0x100000
	s_addc_u32 s41, s25, 0
	global_load_dwordx4 v[182:185], v245, s[40:41]
	global_load_dwordx4 v[186:189], v245, s[40:41] offset:256
	s_add_u32 s40, s24, 0x120000
	s_addc_u32 s41, s25, 0
	global_load_dwordx4 v[190:193], v245, s[40:41]
	global_load_dwordx4 v[194:197], v245, s[40:41] offset:256
	s_add_u32 s40, s24, 0x140000
	s_addc_u32 s41, s25, 0
	global_load_dwordx4 v[198:201], v245, s[40:41]
	global_load_dwordx4 v[202:205], v245, s[40:41] offset:256
	s_add_u32 s40, s24, 0x160000
	s_addc_u32 s41, s25, 0
	global_load_dwordx4 v[206:209], v245, s[40:41]
	global_load_dwordx4 v[210:213], v245, s[40:41] offset:256
	s_and_b64 vcc, exec, s[34:35]
	s_cbranch_vccz .LBB0_2121
	s_barrier
.LBB0_2121:
	s_waitcnt vmcnt(15)
	v_lshlrev_b32_e32 v246, 16, v142
	v_and_b32_e32 v247, 0xffff0000, v142
	v_pk_add_f32 v[126:127], v[126:127], v[246:247]
	v_lshlrev_b32_e32 v246, 16, v143
	v_and_b32_e32 v247, 0xffff0000, v143
	v_pk_add_f32 v[128:129], v[128:129], v[246:247]
	v_lshlrev_b32_e32 v246, 16, v144
	v_and_b32_e32 v247, 0xffff0000, v144
	v_pk_add_f32 v[122:123], v[122:123], v[246:247]
	v_lshlrev_b32_e32 v246, 16, v145
	v_and_b32_e32 v247, 0xffff0000, v145
	v_pk_add_f32 v[124:125], v[124:125], v[246:247]
	v_cvt_pk_bf16_f32 v142, v126, v127
	v_cvt_pk_bf16_f32 v143, v128, v129
	v_cvt_pk_bf16_f32 v144, v122, v123
	v_cvt_pk_bf16_f32 v145, v124, v125
	global_store_dwordx4 v245, v[142:145], s[24:25]
	v_mul_f32_e32 v126, v126, v126
	v_fmac_f32_e32 v126, v127, v127
	v_fmac_f32_e32 v126, v128, v128
	v_fmac_f32_e32 v126, v129, v129
	v_fmac_f32_e32 v126, v122, v122
	v_fmac_f32_e32 v126, v123, v123
	v_fmac_f32_e32 v126, v124, v124
	v_fmac_f32_e32 v126, v125, v125
	s_waitcnt vmcnt(15)
	v_lshlrev_b32_e32 v246, 16, v154
	v_and_b32_e32 v247, 0xffff0000, v154
	v_pk_add_f32 v[118:119], v[118:119], v[246:247]
	v_lshlrev_b32_e32 v246, 16, v155
	v_and_b32_e32 v247, 0xffff0000, v155
	v_pk_add_f32 v[120:121], v[120:121], v[246:247]
	v_lshlrev_b32_e32 v246, 16, v156
	v_and_b32_e32 v247, 0xffff0000, v156
	v_pk_add_f32 v[114:115], v[114:115], v[246:247]
	v_lshlrev_b32_e32 v246, 16, v157
	v_and_b32_e32 v247, 0xffff0000, v157
	v_pk_add_f32 v[116:117], v[116:117], v[246:247]
	v_cvt_pk_bf16_f32 v154, v118, v119
	v_cvt_pk_bf16_f32 v155, v120, v121
	v_cvt_pk_bf16_f32 v156, v114, v115
	v_cvt_pk_bf16_f32 v157, v116, v117
	global_store_dwordx4 v245, v[154:157], s[24:25] offset:256
	v_fmac_f32_e32 v126, v118, v118
	v_fmac_f32_e32 v126, v119, v119
	v_fmac_f32_e32 v126, v120, v120
	v_fmac_f32_e32 v126, v121, v121
	v_fmac_f32_e32 v126, v114, v114
	v_fmac_f32_e32 v126, v115, v115
	v_fmac_f32_e32 v126, v116, v116
	v_fmac_f32_e32 v126, v117, v117
	s_add_u32 s40, s24, 0x20000
	s_addc_u32 s41, s25, 0
	s_waitcnt vmcnt(15)
	v_lshlrev_b32_e32 v246, 16, v158
	v_and_b32_e32 v247, 0xffff0000, v158
	v_pk_add_f32 v[110:111], v[110:111], v[246:247]
	v_lshlrev_b32_e32 v246, 16, v159
	v_and_b32_e32 v247, 0xffff0000, v159
	v_pk_add_f32 v[112:113], v[112:113], v[246:247]
	v_lshlrev_b32_e32 v246, 16, v160
	v_and_b32_e32 v247, 0xffff0000, v160
	v_pk_add_f32 v[106:107], v[106:107], v[246:247]
	v_lshlrev_b32_e32 v246, 16, v161
	v_and_b32_e32 v247, 0xffff0000, v161
	v_pk_add_f32 v[108:109], v[108:109], v[246:247]
	v_cvt_pk_bf16_f32 v158, v110, v111
	v_cvt_pk_bf16_f32 v159, v112, v113
	v_cvt_pk_bf16_f32 v160, v106, v107
	v_cvt_pk_bf16_f32 v161, v108, v109
	global_store_dwordx4 v245, v[158:161], s[40:41]
	v_mul_f32_e32 v110, v110, v110
	v_fmac_f32_e32 v110, v111, v111
	v_fmac_f32_e32 v110, v112, v112
	v_fmac_f32_e32 v110, v113, v113
	v_fmac_f32_e32 v110, v106, v106
	v_fmac_f32_e32 v110, v107, v107
	v_fmac_f32_e32 v110, v108, v108
	v_fmac_f32_e32 v110, v109, v109
	s_waitcnt vmcnt(15)
	v_lshlrev_b32_e32 v246, 16, v162
	v_and_b32_e32 v247, 0xffff0000, v162
	v_pk_add_f32 v[102:103], v[102:103], v[246:247]
	v_lshlrev_b32_e32 v246, 16, v163
	v_and_b32_e32 v247, 0xffff0000, v163
	v_pk_add_f32 v[104:105], v[104:105], v[246:247]
	v_lshlrev_b32_e32 v246, 16, v164
	v_and_b32_e32 v247, 0xffff0000, v164
	v_pk_add_f32 v[98:99], v[98:99], v[246:247]
	v_lshlrev_b32_e32 v246, 16, v165
	v_and_b32_e32 v247, 0xffff0000, v165
	v_pk_add_f32 v[100:101], v[100:101], v[246:247]
	v_cvt_pk_bf16_f32 v162, v102, v103
	v_cvt_pk_bf16_f32 v163, v104, v105
	v_cvt_pk_bf16_f32 v164, v98, v99
	v_cvt_pk_bf16_f32 v165, v100, v101
	global_store_dwordx4 v245, v[162:165], s[40:41] offset:256
	v_fmac_f32_e32 v110, v102, v102
	v_fmac_f32_e32 v110, v103, v103
	v_fmac_f32_e32 v110, v104, v104
	v_fmac_f32_e32 v110, v105, v105
	v_fmac_f32_e32 v110, v98, v98
	v_fmac_f32_e32 v110, v99, v99
	v_fmac_f32_e32 v110, v100, v100
	v_fmac_f32_e32 v110, v101, v101
	s_add_u32 s40, s24, 0x40000
	s_addc_u32 s41, s25, 0
	s_waitcnt vmcnt(15)
	v_lshlrev_b32_e32 v246, 16, v166
	v_and_b32_e32 v247, 0xffff0000, v166
	v_pk_add_f32 v[94:95], v[94:95], v[246:247]
	v_lshlrev_b32_e32 v246, 16, v167
	v_and_b32_e32 v247, 0xffff0000, v167
	v_pk_add_f32 v[96:97], v[96:97], v[246:247]
	v_lshlrev_b32_e32 v246, 16, v168
	v_and_b32_e32 v247, 0xffff0000, v168
	v_pk_add_f32 v[90:91], v[90:91], v[246:247]
	v_lshlrev_b32_e32 v246, 16, v169
	v_and_b32_e32 v247, 0xffff0000, v169
	v_pk_add_f32 v[92:93], v[92:93], v[246:247]
	v_cvt_pk_bf16_f32 v166, v94, v95
	v_cvt_pk_bf16_f32 v167, v96, v97
	v_cvt_pk_bf16_f32 v168, v90, v91
	v_cvt_pk_bf16_f32 v169, v92, v93
	global_store_dwordx4 v245, v[166:169], s[40:41]
	v_mul_f32_e32 v94, v94, v94
	v_fmac_f32_e32 v94, v95, v95
	v_fmac_f32_e32 v94, v96, v96
	v_fmac_f32_e32 v94, v97, v97
	v_fmac_f32_e32 v94, v90, v90
	v_fmac_f32_e32 v94, v91, v91
	v_fmac_f32_e32 v94, v92, v92
	v_fmac_f32_e32 v94, v93, v93
	s_waitcnt vmcnt(15)
	v_lshlrev_b32_e32 v246, 16, v170
	v_and_b32_e32 v247, 0xffff0000, v170
	v_pk_add_f32 v[86:87], v[86:87], v[246:247]
	v_lshlrev_b32_e32 v246, 16, v171
	v_and_b32_e32 v247, 0xffff0000, v171
	v_pk_add_f32 v[88:89], v[88:89], v[246:247]
	v_lshlrev_b32_e32 v246, 16, v172
	v_and_b32_e32 v247, 0xffff0000, v172
	v_pk_add_f32 v[82:83], v[82:83], v[246:247]
	v_lshlrev_b32_e32 v246, 16, v173
	v_and_b32_e32 v247, 0xffff0000, v173
	v_pk_add_f32 v[84:85], v[84:85], v[246:247]
	v_cvt_pk_bf16_f32 v170, v86, v87
	v_cvt_pk_bf16_f32 v171, v88, v89
	v_cvt_pk_bf16_f32 v172, v82, v83
	v_cvt_pk_bf16_f32 v173, v84, v85
	global_store_dwordx4 v245, v[170:173], s[40:41] offset:256
	v_fmac_f32_e32 v94, v86, v86
	v_fmac_f32_e32 v94, v87, v87
	v_fmac_f32_e32 v94, v88, v88
	v_fmac_f32_e32 v94, v89, v89
	v_fmac_f32_e32 v94, v82, v82
	v_fmac_f32_e32 v94, v83, v83
	v_fmac_f32_e32 v94, v84, v84
	v_fmac_f32_e32 v94, v85, v85
	s_add_u32 s40, s24, 0x60000
	s_addc_u32 s41, s25, 0
	s_waitcnt vmcnt(15)
	v_lshlrev_b32_e32 v246, 16, v174
	v_and_b32_e32 v247, 0xffff0000, v174
	v_pk_add_f32 v[78:79], v[78:79], v[246:247]
	v_lshlrev_b32_e32 v246, 16, v175
	v_and_b32_e32 v247, 0xffff0000, v175
	v_pk_add_f32 v[80:81], v[80:81], v[246:247]
	v_lshlrev_b32_e32 v246, 16, v176
	v_and_b32_e32 v247, 0xffff0000, v176
	v_pk_add_f32 v[74:75], v[74:75], v[246:247]
	v_lshlrev_b32_e32 v246, 16, v177
	v_and_b32_e32 v247, 0xffff0000, v177
	v_pk_add_f32 v[76:77], v[76:77], v[246:247]
	v_cvt_pk_bf16_f32 v174, v78, v79
	v_cvt_pk_bf16_f32 v175, v80, v81
	v_cvt_pk_bf16_f32 v176, v74, v75
	v_cvt_pk_bf16_f32 v177, v76, v77
	global_store_dwordx4 v245, v[174:177], s[40:41]
	v_mul_f32_e32 v78, v78, v78
	v_fmac_f32_e32 v78, v79, v79
	v_fmac_f32_e32 v78, v80, v80
	v_fmac_f32_e32 v78, v81, v81
	v_fmac_f32_e32 v78, v74, v74
	v_fmac_f32_e32 v78, v75, v75
	v_fmac_f32_e32 v78, v76, v76
	v_fmac_f32_e32 v78, v77, v77
	s_waitcnt vmcnt(15)
	v_lshlrev_b32_e32 v246, 16, v178
	v_and_b32_e32 v247, 0xffff0000, v178
	v_pk_add_f32 v[70:71], v[70:71], v[246:247]
	v_lshlrev_b32_e32 v246, 16, v179
	v_and_b32_e32 v247, 0xffff0000, v179
	v_pk_add_f32 v[72:73], v[72:73], v[246:247]
	v_lshlrev_b32_e32 v246, 16, v180
	v_and_b32_e32 v247, 0xffff0000, v180
	v_pk_add_f32 v[66:67], v[66:67], v[246:247]
	v_lshlrev_b32_e32 v246, 16, v181
	v_and_b32_e32 v247, 0xffff0000, v181
	v_pk_add_f32 v[68:69], v[68:69], v[246:247]
	v_cvt_pk_bf16_f32 v178, v70, v71
	v_cvt_pk_bf16_f32 v179, v72, v73
	v_cvt_pk_bf16_f32 v180, v66, v67
	v_cvt_pk_bf16_f32 v181, v68, v69
	global_store_dwordx4 v245, v[178:181], s[40:41] offset:256
	v_fmac_f32_e32 v78, v70, v70
	v_fmac_f32_e32 v78, v71, v71
	v_fmac_f32_e32 v78, v72, v72
	v_fmac_f32_e32 v78, v73, v73
	v_fmac_f32_e32 v78, v66, v66
	v_fmac_f32_e32 v78, v67, v67
	v_fmac_f32_e32 v78, v68, v68
	v_fmac_f32_e32 v78, v69, v69
	s_add_u32 s40, s24, 0x100000
	s_addc_u32 s41, s25, 0
	s_waitcnt vmcnt(15)
	v_lshlrev_b32_e32 v246, 16, v182
	v_and_b32_e32 v247, 0xffff0000, v182
	v_pk_add_f32 v[62:63], v[62:63], v[246:247]
	v_lshlrev_b32_e32 v246, 16, v183
	v_and_b32_e32 v247, 0xffff0000, v183
	v_pk_add_f32 v[64:65], v[64:65], v[246:247]
	v_lshlrev_b32_e32 v246, 16, v184
	v_and_b32_e32 v247, 0xffff0000, v184
	v_pk_add_f32 v[58:59], v[58:59], v[246:247]
	v_lshlrev_b32_e32 v246, 16, v185
	v_and_b32_e32 v247, 0xffff0000, v185
	v_pk_add_f32 v[60:61], v[60:61], v[246:247]
	v_cvt_pk_bf16_f32 v182, v62, v63
	v_cvt_pk_bf16_f32 v183, v64, v65
	v_cvt_pk_bf16_f32 v184, v58, v59
	v_cvt_pk_bf16_f32 v185, v60, v61
	global_store_dwordx4 v245, v[182:185], s[40:41]
	v_mul_f32_e32 v62, v62, v62
	v_fmac_f32_e32 v62, v63, v63
	v_fmac_f32_e32 v62, v64, v64
	v_fmac_f32_e32 v62, v65, v65
	v_fmac_f32_e32 v62, v58, v58
	v_fmac_f32_e32 v62, v59, v59
	v_fmac_f32_e32 v62, v60, v60
	v_fmac_f32_e32 v62, v61, v61
	s_waitcnt vmcnt(15)
	v_lshlrev_b32_e32 v246, 16, v186
	v_and_b32_e32 v247, 0xffff0000, v186
	v_pk_add_f32 v[54:55], v[54:55], v[246:247]
	v_lshlrev_b32_e32 v246, 16, v187
	v_and_b32_e32 v247, 0xffff0000, v187
	v_pk_add_f32 v[56:57], v[56:57], v[246:247]
	v_lshlrev_b32_e32 v246, 16, v188
	v_and_b32_e32 v247, 0xffff0000, v188
	v_pk_add_f32 v[50:51], v[50:51], v[246:247]
	v_lshlrev_b32_e32 v246, 16, v189
	v_and_b32_e32 v247, 0xffff0000, v189
	v_pk_add_f32 v[52:53], v[52:53], v[246:247]
	v_cvt_pk_bf16_f32 v186, v54, v55
	v_cvt_pk_bf16_f32 v187, v56, v57
	v_cvt_pk_bf16_f32 v188, v50, v51
	v_cvt_pk_bf16_f32 v189, v52, v53
	global_store_dwordx4 v245, v[186:189], s[40:41] offset:256
	v_fmac_f32_e32 v62, v54, v54
	v_fmac_f32_e32 v62, v55, v55
	v_fmac_f32_e32 v62, v56, v56
	v_fmac_f32_e32 v62, v57, v57
	v_fmac_f32_e32 v62, v50, v50
	v_fmac_f32_e32 v62, v51, v51
	v_fmac_f32_e32 v62, v52, v52
	v_fmac_f32_e32 v62, v53, v53
	s_add_u32 s40, s24, 0x120000
	s_addc_u32 s41, s25, 0
	s_waitcnt vmcnt(15)
	v_lshlrev_b32_e32 v246, 16, v190
	v_and_b32_e32 v247, 0xffff0000, v190
	v_pk_add_f32 v[46:47], v[46:47], v[246:247]
	v_lshlrev_b32_e32 v246, 16, v191
	v_and_b32_e32 v247, 0xffff0000, v191
	v_pk_add_f32 v[48:49], v[48:49], v[246:247]
	v_lshlrev_b32_e32 v246, 16, v192
	v_and_b32_e32 v247, 0xffff0000, v192
	v_pk_add_f32 v[42:43], v[42:43], v[246:247]
	v_lshlrev_b32_e32 v246, 16, v193
	v_and_b32_e32 v247, 0xffff0000, v193
	v_pk_add_f32 v[44:45], v[44:45], v[246:247]
	v_cvt_pk_bf16_f32 v190, v46, v47
	v_cvt_pk_bf16_f32 v191, v48, v49
	v_cvt_pk_bf16_f32 v192, v42, v43
	v_cvt_pk_bf16_f32 v193, v44, v45
	global_store_dwordx4 v245, v[190:193], s[40:41]
	v_mul_f32_e32 v46, v46, v46
	v_fmac_f32_e32 v46, v47, v47
	v_fmac_f32_e32 v46, v48, v48
	v_fmac_f32_e32 v46, v49, v49
	v_fmac_f32_e32 v46, v42, v42
	v_fmac_f32_e32 v46, v43, v43
	v_fmac_f32_e32 v46, v44, v44
	v_fmac_f32_e32 v46, v45, v45
	s_waitcnt vmcnt(15)
	v_lshlrev_b32_e32 v246, 16, v194
	v_and_b32_e32 v247, 0xffff0000, v194
	v_pk_add_f32 v[38:39], v[38:39], v[246:247]
	v_lshlrev_b32_e32 v246, 16, v195
	v_and_b32_e32 v247, 0xffff0000, v195
	v_pk_add_f32 v[40:41], v[40:41], v[246:247]
	v_lshlrev_b32_e32 v246, 16, v196
	v_and_b32_e32 v247, 0xffff0000, v196
	v_pk_add_f32 v[34:35], v[34:35], v[246:247]
	v_lshlrev_b32_e32 v246, 16, v197
	v_and_b32_e32 v247, 0xffff0000, v197
	v_pk_add_f32 v[36:37], v[36:37], v[246:247]
	v_cvt_pk_bf16_f32 v194, v38, v39
	v_cvt_pk_bf16_f32 v195, v40, v41
	v_cvt_pk_bf16_f32 v196, v34, v35
	v_cvt_pk_bf16_f32 v197, v36, v37
	global_store_dwordx4 v245, v[194:197], s[40:41] offset:256
	v_fmac_f32_e32 v46, v38, v38
	v_fmac_f32_e32 v46, v39, v39
	v_fmac_f32_e32 v46, v40, v40
	v_fmac_f32_e32 v46, v41, v41
	v_fmac_f32_e32 v46, v34, v34
	v_fmac_f32_e32 v46, v35, v35
	v_fmac_f32_e32 v46, v36, v36
	v_fmac_f32_e32 v46, v37, v37
	s_add_u32 s40, s24, 0x140000
	s_addc_u32 s41, s25, 0
	s_waitcnt vmcnt(15)
	v_lshlrev_b32_e32 v246, 16, v198
	v_and_b32_e32 v247, 0xffff0000, v198
	v_pk_add_f32 v[30:31], v[30:31], v[246:247]
	v_lshlrev_b32_e32 v246, 16, v199
	v_and_b32_e32 v247, 0xffff0000, v199
	v_pk_add_f32 v[32:33], v[32:33], v[246:247]
	v_lshlrev_b32_e32 v246, 16, v200
	v_and_b32_e32 v247, 0xffff0000, v200
	v_pk_add_f32 v[26:27], v[26:27], v[246:247]
	v_lshlrev_b32_e32 v246, 16, v201
	v_and_b32_e32 v247, 0xffff0000, v201
	v_pk_add_f32 v[28:29], v[28:29], v[246:247]
	v_cvt_pk_bf16_f32 v198, v30, v31
	v_cvt_pk_bf16_f32 v199, v32, v33
	v_cvt_pk_bf16_f32 v200, v26, v27
	v_cvt_pk_bf16_f32 v201, v28, v29
	global_store_dwordx4 v245, v[198:201], s[40:41]
	v_mul_f32_e32 v30, v30, v30
	v_fmac_f32_e32 v30, v31, v31
	v_fmac_f32_e32 v30, v32, v32
	v_fmac_f32_e32 v30, v33, v33
	v_fmac_f32_e32 v30, v26, v26
	v_fmac_f32_e32 v30, v27, v27
	v_fmac_f32_e32 v30, v28, v28
	v_fmac_f32_e32 v30, v29, v29
	s_waitcnt vmcnt(15)
	v_lshlrev_b32_e32 v246, 16, v202
	v_and_b32_e32 v247, 0xffff0000, v202
	v_pk_add_f32 v[22:23], v[22:23], v[246:247]
	v_lshlrev_b32_e32 v246, 16, v203
	v_and_b32_e32 v247, 0xffff0000, v203
	v_pk_add_f32 v[24:25], v[24:25], v[246:247]
	v_lshlrev_b32_e32 v246, 16, v204
	v_and_b32_e32 v247, 0xffff0000, v204
	v_pk_add_f32 v[18:19], v[18:19], v[246:247]
	v_lshlrev_b32_e32 v246, 16, v205
	v_and_b32_e32 v247, 0xffff0000, v205
	v_pk_add_f32 v[20:21], v[20:21], v[246:247]
	v_cvt_pk_bf16_f32 v202, v22, v23
	v_cvt_pk_bf16_f32 v203, v24, v25
	v_cvt_pk_bf16_f32 v204, v18, v19
	v_cvt_pk_bf16_f32 v205, v20, v21
	global_store_dwordx4 v245, v[202:205], s[40:41] offset:256
	v_fmac_f32_e32 v30, v22, v22
	v_fmac_f32_e32 v30, v23, v23
	v_fmac_f32_e32 v30, v24, v24
	v_fmac_f32_e32 v30, v25, v25
	v_fmac_f32_e32 v30, v18, v18
	v_fmac_f32_e32 v30, v19, v19
	v_fmac_f32_e32 v30, v20, v20
	v_fmac_f32_e32 v30, v21, v21
	s_add_u32 s40, s24, 0x160000
	s_addc_u32 s41, s25, 0
	s_waitcnt vmcnt(15)
	v_lshlrev_b32_e32 v246, 16, v206
	v_and_b32_e32 v247, 0xffff0000, v206
	v_pk_add_f32 v[14:15], v[14:15], v[246:247]
	v_lshlrev_b32_e32 v246, 16, v207
	v_and_b32_e32 v247, 0xffff0000, v207
	v_pk_add_f32 v[16:17], v[16:17], v[246:247]
	v_lshlrev_b32_e32 v246, 16, v208
	v_and_b32_e32 v247, 0xffff0000, v208
	v_pk_add_f32 v[10:11], v[10:11], v[246:247]
	v_lshlrev_b32_e32 v246, 16, v209
	v_and_b32_e32 v247, 0xffff0000, v209
	v_pk_add_f32 v[12:13], v[12:13], v[246:247]
	v_cvt_pk_bf16_f32 v206, v14, v15
	v_cvt_pk_bf16_f32 v207, v16, v17
	v_cvt_pk_bf16_f32 v208, v10, v11
	v_cvt_pk_bf16_f32 v209, v12, v13
	global_store_dwordx4 v245, v[206:209], s[40:41]
	v_mul_f32_e32 v14, v14, v14
	v_fmac_f32_e32 v14, v15, v15
	v_fmac_f32_e32 v14, v16, v16
	v_fmac_f32_e32 v14, v17, v17
	v_fmac_f32_e32 v14, v10, v10
	v_fmac_f32_e32 v14, v11, v11
	v_fmac_f32_e32 v14, v12, v12
	v_fmac_f32_e32 v14, v13, v13
	s_waitcnt vmcnt(15)
	v_lshlrev_b32_e32 v246, 16, v210
	v_and_b32_e32 v247, 0xffff0000, v210
	v_pk_add_f32 v[6:7], v[6:7], v[246:247]
	v_lshlrev_b32_e32 v246, 16, v211
	v_and_b32_e32 v247, 0xffff0000, v211
	v_pk_add_f32 v[8:9], v[8:9], v[246:247]
	v_lshlrev_b32_e32 v246, 16, v212
	v_and_b32_e32 v247, 0xffff0000, v212
	v_pk_add_f32 v[2:3], v[2:3], v[246:247]
	v_lshlrev_b32_e32 v246, 16, v213
	v_and_b32_e32 v247, 0xffff0000, v213
	v_pk_add_f32 v[4:5], v[4:5], v[246:247]
	v_cvt_pk_bf16_f32 v210, v6, v7
	v_cvt_pk_bf16_f32 v211, v8, v9
	v_cvt_pk_bf16_f32 v212, v2, v3
	v_cvt_pk_bf16_f32 v213, v4, v5
	global_store_dwordx4 v245, v[210:213], s[40:41] offset:256
	v_fmac_f32_e32 v14, v6, v6
	v_fmac_f32_e32 v14, v7, v7
	v_fmac_f32_e32 v14, v8, v8
	v_fmac_f32_e32 v14, v9, v9
	v_fmac_f32_e32 v14, v2, v2
	v_fmac_f32_e32 v14, v3, v3
	v_fmac_f32_e32 v14, v4, v4
	v_fmac_f32_e32 v14, v5, v5
	v_mbcnt_lo_u32_b32 v246, -1, 0
	v_mbcnt_hi_u32_b32 v246, -1, v246
	v_xor_b32_e32 v247, 32, v246
	v_xor_b32_e32 v246, 16, v246
	v_lshlrev_b32_e32 v246, 2, v246
	v_lshlrev_b32_e32 v247, 2, v247
	ds_bpermute_b32 v127, v246, v126
	ds_bpermute_b32 v111, v246, v110
	ds_bpermute_b32 v95, v246, v94
	ds_bpermute_b32 v79, v246, v78
	ds_bpermute_b32 v63, v246, v62
	ds_bpermute_b32 v47, v246, v46
	ds_bpermute_b32 v31, v246, v30
	ds_bpermute_b32 v15, v246, v14
	s_waitcnt lgkmcnt(0)
	v_add_f32_e32 v126, v126, v127
	v_add_f32_e32 v110, v110, v111
	v_add_f32_e32 v94, v94, v95
	v_add_f32_e32 v78, v78, v79
	v_add_f32_e32 v62, v62, v63
	v_add_f32_e32 v46, v46, v47
	v_add_f32_e32 v30, v30, v31
	v_add_f32_e32 v14, v14, v15
	ds_bpermute_b32 v127, v247, v126
	ds_bpermute_b32 v111, v247, v110
	ds_bpermute_b32 v95, v247, v94
	ds_bpermute_b32 v79, v247, v78
	ds_bpermute_b32 v63, v247, v62
	ds_bpermute_b32 v47, v247, v46
	ds_bpermute_b32 v31, v247, v30
	ds_bpermute_b32 v15, v247, v14
	s_waitcnt lgkmcnt(0)
	v_add_f32_e32 v126, v126, v127
	v_add_f32_e32 v110, v110, v111
	v_add_f32_e32 v94, v94, v95
	v_add_f32_e32 v78, v78, v79
	v_add_f32_e32 v62, v62, v63
	v_add_f32_e32 v46, v46, v47
	v_add_f32_e32 v30, v30, v31
	v_add_f32_e32 v14, v14, v15
	v_lshl_add_u32 v246, s68, 8, v146
	v_lshlrev_b32_e32 v246, 2, v246
	s_and_saveexec_b64 s[40:41], s[6:7]
	global_atomic_add_f32 v246, v126, s[12:13]
	global_atomic_add_f32 v246, v110, s[12:13] offset:64
	global_atomic_add_f32 v246, v94, s[12:13] offset:128
	global_atomic_add_f32 v246, v78, s[12:13] offset:192
	global_atomic_add_f32 v246, v62, s[12:13] offset:512
	global_atomic_add_f32 v246, v46, s[12:13] offset:576
	global_atomic_add_f32 v246, v30, s[12:13] offset:640
	global_atomic_add_f32 v246, v14, s[12:13] offset:704
	s_mov_b64 exec, s[40:41]
	s_and_b64 vcc, exec, s[8:9]
	s_mov_b64 s[8:9], -1
	s_cbranch_vccnz .LBB0_2106
	s_andn2_b64 vcc, exec, s[10:11]
	s_cbranch_vccnz .LBB0_2105
	s_barrier
	s_branch .LBB0_2105

.LBB0_2248:
	ds_read_b128 v[146:149], v152
	ds_read_b128 v[156:159], v152 offset:1024
	ds_read_b128 v[160:163], v152 offset:2048
	ds_read_b128 v[164:167], v152 offset:3072
	ds_read_b128 v[168:171], v153
	ds_read_b128 v[172:175], v153 offset:1024
	ds_read_b128 v[176:179], v153 offset:2048
	ds_read_b128 v[180:183], v153 offset:3072
	s_add_u32 s28, s26, 0xffd50080
	s_addc_u32 s29, s27, -1
	s_cmpk_eq_i32 s64, 0xa8
	s_cselect_b32 s31, s11, s29
	s_cselect_b32 s30, s10, s28
	s_cselect_b32 s29, s25, s63
	s_cselect_b32 s28, s24, s62
	v_lshl_add_u64 v[216:217], s[26:27], 0, v[140:141]
	s_add_i32 m0, s38, 0xc000
	ds_read_b128 v[184:187], v154
	ds_read_b128 v[188:191], v154 offset:1024
	ds_read_b128 v[192:195], v154 offset:2048
	ds_read_b128 v[196:199], v154 offset:3072
	ds_read_b128 v[200:203], v154 offset:4096
	ds_read_b128 v[204:207], v154 offset:5120
	ds_read_b128 v[208:211], v154 offset:6144
	ds_read_b128 v[212:215], v154 offset:7168
	global_load_lds_dwordx4 v[216:217], off
	v_lshl_add_u64 v[216:217], s[26:27], 0, v[138:139]
	s_add_i32 m0, s38, 0xe000
	s_nop 0
	global_load_lds_dwordx4 v[216:217], off
	s_waitcnt vmcnt(8)
	s_waitcnt lgkmcnt(0)
	s_barrier
	s_setprio 1
	s_waitcnt lgkmcnt(0)
	v_mfma_f32_16x16x32_bf16 v[126:129], v[146:149], v[184:187], v[126:129]
	v_mfma_f32_16x16x32_bf16 v[122:125], v[160:163], v[184:187], v[122:125]
	v_mfma_f32_16x16x32_bf16 v[110:113], v[146:149], v[192:195], v[110:113]
	v_mfma_f32_16x16x32_bf16 v[106:109], v[160:163], v[192:195], v[106:109]
	v_mfma_f32_16x16x32_bf16 v[94:97], v[146:149], v[200:203], v[94:97]
	v_mfma_f32_16x16x32_bf16 v[90:93], v[160:163], v[200:203], v[90:93]
	v_mfma_f32_16x16x32_bf16 v[78:81], v[146:149], v[208:211], v[78:81]
	v_mfma_f32_16x16x32_bf16 v[74:77], v[160:163], v[208:211], v[74:77]
	v_mfma_f32_16x16x32_bf16 v[126:129], v[156:159], v[188:191], v[126:129]
	v_mfma_f32_16x16x32_bf16 v[122:125], v[164:167], v[188:191], v[122:125]
	v_mfma_f32_16x16x32_bf16 v[110:113], v[156:159], v[196:199], v[110:113]
	v_mfma_f32_16x16x32_bf16 v[106:109], v[164:167], v[196:199], v[106:109]
	v_mfma_f32_16x16x32_bf16 v[94:97], v[156:159], v[204:207], v[94:97]
	v_mfma_f32_16x16x32_bf16 v[90:93], v[164:167], v[204:207], v[90:93]
	v_mfma_f32_16x16x32_bf16 v[78:81], v[156:159], v[212:215], v[78:81]
	v_mfma_f32_16x16x32_bf16 v[74:77], v[164:167], v[212:215], v[74:77]
	s_setprio 0
	s_setprio 1
	v_mfma_f32_16x16x32_bf16 v[118:121], v[168:171], v[184:187], v[118:121]
	v_mfma_f32_16x16x32_bf16 v[114:117], v[176:179], v[184:187], v[114:117]
	v_mfma_f32_16x16x32_bf16 v[102:105], v[168:171], v[192:195], v[102:105]
	v_mfma_f32_16x16x32_bf16 v[98:101], v[176:179], v[192:195], v[98:101]
	v_mfma_f32_16x16x32_bf16 v[86:89], v[168:171], v[200:203], v[86:89]
	v_mfma_f32_16x16x32_bf16 v[82:85], v[176:179], v[200:203], v[82:85]
	v_mfma_f32_16x16x32_bf16 v[70:73], v[168:171], v[208:211], v[70:73]
	v_mfma_f32_16x16x32_bf16 v[66:69], v[176:179], v[208:211], v[66:69]
	v_mfma_f32_16x16x32_bf16 v[118:121], v[172:175], v[188:191], v[118:121]
	v_mfma_f32_16x16x32_bf16 v[114:117], v[180:183], v[188:191], v[114:117]
	v_mfma_f32_16x16x32_bf16 v[102:105], v[172:175], v[196:199], v[102:105]
	v_mfma_f32_16x16x32_bf16 v[98:101], v[180:183], v[196:199], v[98:101]
	v_mfma_f32_16x16x32_bf16 v[86:89], v[172:175], v[204:207], v[86:89]
	v_mfma_f32_16x16x32_bf16 v[82:85], v[180:183], v[204:207], v[82:85]
	v_mfma_f32_16x16x32_bf16 v[70:73], v[172:175], v[212:215], v[70:73]
	v_mfma_f32_16x16x32_bf16 v[66:69], v[180:183], v[212:215], v[66:69]
	s_setprio 0
	s_barrier
	s_add_i32 s65, s47, s37
	v_lshl_add_u64 v[216:217], s[28:29], 0, v[132:133]
	s_mov_b32 m0, s65
	ds_read_b128 v[184:187], v154 offset:16384
	ds_read_b128 v[188:191], v154 offset:17408
	ds_read_b128 v[192:195], v154 offset:18432
	ds_read_b128 v[196:199], v154 offset:19456
	ds_read_b128 v[200:203], v154 offset:20480
	ds_read_b128 v[204:207], v154 offset:21504
	ds_read_b128 v[208:211], v154 offset:22528
	ds_read_b128 v[212:215], v154 offset:23552
	global_load_lds_dwordx4 v[216:217], off
	s_add_i32 m0, s65, 0x2000
	s_add_u32 s66, s28, 0x2b0000
	v_lshl_add_u64 v[218:219], s[28:29], 0, v[136:137]
	s_addc_u32 s67, s29, 0
	s_add_i32 s65, s49, s37
	global_load_lds_dwordx4 v[218:219], off
	v_lshl_add_u64 v[220:221], s[66:67], 0, v[132:133]
	s_mov_b32 m0, s65
	v_lshl_add_u64 v[222:223], s[30:31], 0, v[134:135]
	global_load_lds_dwordx4 v[220:221], off
	v_lshl_add_u64 v[220:221], s[66:67], 0, v[136:137]
	s_add_i32 m0, s65, 0x2000
	s_nop 0
	global_load_lds_dwordx4 v[220:221], off
	v_lshl_add_u64 v[220:221], s[30:31], 0, v[130:131]
	s_mov_b32 m0, s38
	s_nop 0
	global_load_lds_dwordx4 v[220:221], off
	s_mov_b32 m0, s39
	s_nop 0
	global_load_lds_dwordx4 v[222:223], off
	s_waitcnt vmcnt(8)
	s_waitcnt lgkmcnt(0)
	s_barrier
	s_setprio 1
	s_waitcnt lgkmcnt(0)
	v_mfma_f32_16x16x32_bf16 v[62:65], v[146:149], v[184:187], v[62:65]
	v_mfma_f32_16x16x32_bf16 v[58:61], v[160:163], v[184:187], v[58:61]
	v_mfma_f32_16x16x32_bf16 v[46:49], v[146:149], v[192:195], v[46:49]
	v_mfma_f32_16x16x32_bf16 v[42:45], v[160:163], v[192:195], v[42:45]
	v_mfma_f32_16x16x32_bf16 v[30:33], v[146:149], v[200:203], v[30:33]
	v_mfma_f32_16x16x32_bf16 v[26:29], v[160:163], v[200:203], v[26:29]
	v_mfma_f32_16x16x32_bf16 v[14:17], v[146:149], v[208:211], v[14:17]
	v_mfma_f32_16x16x32_bf16 v[10:13], v[160:163], v[208:211], v[10:13]
	v_mfma_f32_16x16x32_bf16 v[62:65], v[156:159], v[188:191], v[62:65]
	v_mfma_f32_16x16x32_bf16 v[58:61], v[164:167], v[188:191], v[58:61]
	v_mfma_f32_16x16x32_bf16 v[46:49], v[156:159], v[196:199], v[46:49]
	v_mfma_f32_16x16x32_bf16 v[42:45], v[164:167], v[196:199], v[42:45]
	v_mfma_f32_16x16x32_bf16 v[30:33], v[156:159], v[204:207], v[30:33]
	v_mfma_f32_16x16x32_bf16 v[26:29], v[164:167], v[204:207], v[26:29]
	v_mfma_f32_16x16x32_bf16 v[14:17], v[156:159], v[212:215], v[14:17]
	v_mfma_f32_16x16x32_bf16 v[10:13], v[164:167], v[212:215], v[10:13]
	s_setprio 0
	s_setprio 1
	v_mfma_f32_16x16x32_bf16 v[54:57], v[168:171], v[184:187], v[54:57]
	v_mfma_f32_16x16x32_bf16 v[50:53], v[176:179], v[184:187], v[50:53]
	v_mfma_f32_16x16x32_bf16 v[38:41], v[168:171], v[192:195], v[38:41]
	v_mfma_f32_16x16x32_bf16 v[34:37], v[176:179], v[192:195], v[34:37]
	v_mfma_f32_16x16x32_bf16 v[22:25], v[168:171], v[200:203], v[22:25]
	v_mfma_f32_16x16x32_bf16 v[18:21], v[176:179], v[200:203], v[18:21]
	v_mfma_f32_16x16x32_bf16 v[6:9], v[168:171], v[208:211], v[6:9]
	v_mfma_f32_16x16x32_bf16 v[2:5], v[176:179], v[208:211], v[2:5]
	v_mfma_f32_16x16x32_bf16 v[54:57], v[172:175], v[188:191], v[54:57]
	v_mfma_f32_16x16x32_bf16 v[50:53], v[180:183], v[188:191], v[50:53]
	v_mfma_f32_16x16x32_bf16 v[38:41], v[172:175], v[196:199], v[38:41]
	v_mfma_f32_16x16x32_bf16 v[34:37], v[180:183], v[196:199], v[34:37]
	v_mfma_f32_16x16x32_bf16 v[22:25], v[172:175], v[204:207], v[22:25]
	v_mfma_f32_16x16x32_bf16 v[18:21], v[180:183], v[204:207], v[18:21]
	v_mfma_f32_16x16x32_bf16 v[6:9], v[172:175], v[212:215], v[6:9]
	v_mfma_f32_16x16x32_bf16 v[2:5], v[180:183], v[212:215], v[2:5]
	s_setprio 0
	s_barrier
	s_add_i32 s65, 0, 0x18000
	s_add_i32 s66, 0, 0x1c000
	v_add_u32_e32 v164, s65, v150
	v_add_u32_e32 v180, s66, v150
	ds_read_b128 v[146:149], v164
	ds_read_b128 v[156:159], v164 offset:1024
	ds_read_b128 v[160:163], v164 offset:2048
	ds_read_b128 v[164:167], v164 offset:3072
	ds_read_b128 v[168:171], v180
	ds_read_b128 v[172:175], v180 offset:1024
	ds_read_b128 v[176:179], v180 offset:2048
	ds_read_b128 v[180:183], v180 offset:3072
	s_add_u32 s30, s30, 0x2b0000
	s_addc_u32 s31, s31, 0
	s_mov_b32 m0, s40
	v_lshl_add_u64 v[224:225], s[30:31], 0, v[130:131]
	ds_read_b128 v[184:187], v154 offset:32768
	ds_read_b128 v[188:191], v154 offset:33792
	ds_read_b128 v[192:195], v154 offset:34816
	ds_read_b128 v[196:199], v154 offset:35840
	ds_read_b128 v[200:203], v154 offset:36864
	ds_read_b128 v[204:207], v154 offset:37888
	ds_read_b128 v[208:211], v154 offset:38912
	ds_read_b128 v[212:215], v154 offset:39936
	global_load_lds_dwordx4 v[224:225], off
	v_lshl_add_u64 v[224:225], s[30:31], 0, v[134:135]
	s_mov_b32 m0, s41
	s_nop 0
	global_load_lds_dwordx4 v[224:225], off
	s_waitcnt vmcnt(8)
	s_waitcnt lgkmcnt(0)
	s_barrier
	s_setprio 1
	s_waitcnt lgkmcnt(0)
	v_mfma_f32_16x16x32_bf16 v[126:129], v[146:149], v[184:187], v[126:129]
	v_mfma_f32_16x16x32_bf16 v[122:125], v[160:163], v[184:187], v[122:125]
	v_mfma_f32_16x16x32_bf16 v[110:113], v[146:149], v[192:195], v[110:113]
	v_mfma_f32_16x16x32_bf16 v[106:109], v[160:163], v[192:195], v[106:109]
	v_mfma_f32_16x16x32_bf16 v[94:97], v[146:149], v[200:203], v[94:97]
	v_mfma_f32_16x16x32_bf16 v[90:93], v[160:163], v[200:203], v[90:93]
	v_mfma_f32_16x16x32_bf16 v[78:81], v[146:149], v[208:211], v[78:81]
	v_mfma_f32_16x16x32_bf16 v[74:77], v[160:163], v[208:211], v[74:77]
	v_mfma_f32_16x16x32_bf16 v[126:129], v[156:159], v[188:191], v[126:129]
	v_mfma_f32_16x16x32_bf16 v[122:125], v[164:167], v[188:191], v[122:125]
	v_mfma_f32_16x16x32_bf16 v[110:113], v[156:159], v[196:199], v[110:113]
	v_mfma_f32_16x16x32_bf16 v[106:109], v[164:167], v[196:199], v[106:109]
	v_mfma_f32_16x16x32_bf16 v[94:97], v[156:159], v[204:207], v[94:97]
	v_mfma_f32_16x16x32_bf16 v[90:93], v[164:167], v[204:207], v[90:93]
	v_mfma_f32_16x16x32_bf16 v[78:81], v[156:159], v[212:215], v[78:81]
	v_mfma_f32_16x16x32_bf16 v[74:77], v[164:167], v[212:215], v[74:77]
	s_setprio 0
	s_setprio 1
	v_mfma_f32_16x16x32_bf16 v[118:121], v[168:171], v[184:187], v[118:121]
	v_mfma_f32_16x16x32_bf16 v[114:117], v[176:179], v[184:187], v[114:117]
	v_mfma_f32_16x16x32_bf16 v[102:105], v[168:171], v[192:195], v[102:105]
	v_mfma_f32_16x16x32_bf16 v[98:101], v[176:179], v[192:195], v[98:101]
	v_mfma_f32_16x16x32_bf16 v[86:89], v[168:171], v[200:203], v[86:89]
	v_mfma_f32_16x16x32_bf16 v[82:85], v[176:179], v[200:203], v[82:85]
	v_mfma_f32_16x16x32_bf16 v[70:73], v[168:171], v[208:211], v[70:73]
	v_mfma_f32_16x16x32_bf16 v[66:69], v[176:179], v[208:211], v[66:69]
	v_mfma_f32_16x16x32_bf16 v[118:121], v[172:175], v[188:191], v[118:121]
	v_mfma_f32_16x16x32_bf16 v[114:117], v[180:183], v[188:191], v[114:117]
	v_mfma_f32_16x16x32_bf16 v[102:105], v[172:175], v[196:199], v[102:105]
	v_mfma_f32_16x16x32_bf16 v[98:101], v[180:183], v[196:199], v[98:101]
	v_mfma_f32_16x16x32_bf16 v[86:89], v[172:175], v[204:207], v[86:89]
	v_mfma_f32_16x16x32_bf16 v[82:85], v[180:183], v[204:207], v[82:85]
	v_mfma_f32_16x16x32_bf16 v[70:73], v[172:175], v[212:215], v[70:73]
	v_mfma_f32_16x16x32_bf16 v[66:69], v[180:183], v[212:215], v[66:69]
	s_setprio 0
	s_barrier
	s_add_i32 s30, s65, s37
	v_lshl_add_u64 v[216:217], v[216:217], 0, s[20:21]
	s_mov_b32 m0, s30
	ds_read_b128 v[184:187], v154 offset:49152
	ds_read_b128 v[188:191], v154 offset:50176
	ds_read_b128 v[192:195], v154 offset:51200
	ds_read_b128 v[196:199], v154 offset:52224
	ds_read_b128 v[200:203], v154 offset:53248
	ds_read_b128 v[204:207], v154 offset:54272
	ds_read_b128 v[208:211], v154 offset:55296
	ds_read_b128 v[212:215], v154 offset:56320
	global_load_lds_dwordx4 v[216:217], off
	s_add_i32 m0, s30, 0x2000
	s_add_u32 s28, s28, 0x2b0080
	v_lshl_add_u64 v[216:217], v[218:219], 0, s[20:21]
	s_addc_u32 s29, s29, 0
	s_add_i32 s30, s66, s37
	global_load_lds_dwordx4 v[216:217], off
	v_lshl_add_u64 v[216:217], s[28:29], 0, v[132:133]
	s_mov_b32 m0, s30
	s_nop 0
	global_load_lds_dwordx4 v[216:217], off
	v_lshl_add_u64 v[216:217], s[28:29], 0, v[136:137]
	s_add_i32 m0, s30, 0x2000
	s_nop 0
	global_load_lds_dwordx4 v[216:217], off
	v_lshl_add_u64 v[216:217], v[220:221], 0, s[20:21]
	s_mov_b32 m0, s44
	s_nop 0
	global_load_lds_dwordx4 v[216:217], off
	v_lshl_add_u64 v[216:217], v[222:223], 0, s[20:21]
	s_mov_b32 m0, s45
	s_nop 0
	global_load_lds_dwordx4 v[216:217], off
	s_waitcnt vmcnt(8)
	s_waitcnt lgkmcnt(0)
	s_barrier
	s_setprio 1
	s_waitcnt lgkmcnt(0)
	v_mfma_f32_16x16x32_bf16 v[62:65], v[146:149], v[184:187], v[62:65]
	v_mfma_f32_16x16x32_bf16 v[58:61], v[160:163], v[184:187], v[58:61]
	v_mfma_f32_16x16x32_bf16 v[46:49], v[146:149], v[192:195], v[46:49]
	v_mfma_f32_16x16x32_bf16 v[42:45], v[160:163], v[192:195], v[42:45]
	v_mfma_f32_16x16x32_bf16 v[30:33], v[146:149], v[200:203], v[30:33]
	v_mfma_f32_16x16x32_bf16 v[26:29], v[160:163], v[200:203], v[26:29]
	v_mfma_f32_16x16x32_bf16 v[14:17], v[146:149], v[208:211], v[14:17]
	v_mfma_f32_16x16x32_bf16 v[10:13], v[160:163], v[208:211], v[10:13]
	v_mfma_f32_16x16x32_bf16 v[62:65], v[156:159], v[188:191], v[62:65]
	v_mfma_f32_16x16x32_bf16 v[58:61], v[164:167], v[188:191], v[58:61]
	v_mfma_f32_16x16x32_bf16 v[46:49], v[156:159], v[196:199], v[46:49]
	v_mfma_f32_16x16x32_bf16 v[42:45], v[164:167], v[196:199], v[42:45]
	v_mfma_f32_16x16x32_bf16 v[30:33], v[156:159], v[204:207], v[30:33]
	v_mfma_f32_16x16x32_bf16 v[26:29], v[164:167], v[204:207], v[26:29]
	v_mfma_f32_16x16x32_bf16 v[14:17], v[156:159], v[212:215], v[14:17]
	v_mfma_f32_16x16x32_bf16 v[10:13], v[164:167], v[212:215], v[10:13]
	s_setprio 0
	s_setprio 1
	v_mfma_f32_16x16x32_bf16 v[54:57], v[168:171], v[184:187], v[54:57]
	v_mfma_f32_16x16x32_bf16 v[50:53], v[176:179], v[184:187], v[50:53]
	v_mfma_f32_16x16x32_bf16 v[38:41], v[168:171], v[192:195], v[38:41]
	v_mfma_f32_16x16x32_bf16 v[34:37], v[176:179], v[192:195], v[34:37]
	v_mfma_f32_16x16x32_bf16 v[22:25], v[168:171], v[200:203], v[22:25]
	v_mfma_f32_16x16x32_bf16 v[18:21], v[176:179], v[200:203], v[18:21]
	v_mfma_f32_16x16x32_bf16 v[6:9], v[168:171], v[208:211], v[6:9]
	v_mfma_f32_16x16x32_bf16 v[2:5], v[176:179], v[208:211], v[2:5]
	v_mfma_f32_16x16x32_bf16 v[54:57], v[172:175], v[188:191], v[54:57]
	v_mfma_f32_16x16x32_bf16 v[50:53], v[180:183], v[188:191], v[50:53]
	v_mfma_f32_16x16x32_bf16 v[38:41], v[172:175], v[196:199], v[38:41]
	v_mfma_f32_16x16x32_bf16 v[34:37], v[180:183], v[196:199], v[34:37]
	v_mfma_f32_16x16x32_bf16 v[22:25], v[172:175], v[204:207], v[22:25]
	v_mfma_f32_16x16x32_bf16 v[18:21], v[180:183], v[204:207], v[18:21]
	v_mfma_f32_16x16x32_bf16 v[6:9], v[172:175], v[212:215], v[6:9]
	v_mfma_f32_16x16x32_bf16 v[2:5], v[180:183], v[212:215], v[2:5]
	s_setprio 0
	s_barrier
	s_add_i32 s64, s64, 2
	s_add_u32 s62, s62, 0x100
	s_addc_u32 s63, s63, 0
	s_add_u32 s26, s26, 0x100
	s_addc_u32 s27, s27, 0
	s_cmpk_gt_u32 s64, 0xa9
	s_cbranch_scc0 .LBB0_2248
	v_lshl_add_u32 v245, s60, 8, v1
	v_lshl_or_b32 v246, s61, 8, v151
	v_lshlrev_b32_e32 v245, 13, v245
	v_lshl_add_u32 v245, v246, 1, v245
	global_load_dwordx4 v[146:149], v245, s[16:17]
	global_load_dwordx4 v[156:159], v245, s[16:17] offset:256
	s_add_u32 s26, s16, 0x20000
	s_addc_u32 s27, s17, 0
	global_load_dwordx4 v[160:163], v245, s[26:27]
	global_load_dwordx4 v[164:167], v245, s[26:27] offset:256
	s_add_u32 s26, s16, 0x40000
	s_addc_u32 s27, s17, 0
	global_load_dwordx4 v[168:171], v245, s[26:27]
	global_load_dwordx4 v[172:175], v245, s[26:27] offset:256
	s_add_u32 s26, s16, 0x60000
	s_addc_u32 s27, s17, 0
	global_load_dwordx4 v[176:179], v245, s[26:27]
	global_load_dwordx4 v[180:183], v245, s[26:27] offset:256
	s_add_u32 s26, s16, 0x100000
	s_addc_u32 s27, s17, 0
	global_load_dwordx4 v[184:187], v245, s[26:27]
	global_load_dwordx4 v[188:191], v245, s[26:27] offset:256
	s_add_u32 s26, s16, 0x120000
	s_addc_u32 s27, s17, 0
	global_load_dwordx4 v[192:195], v245, s[26:27]
	global_load_dwordx4 v[196:199], v245, s[26:27] offset:256
	s_add_u32 s26, s16, 0x140000
	s_addc_u32 s27, s17, 0
	global_load_dwordx4 v[200:203], v245, s[26:27]
	global_load_dwordx4 v[204:207], v245, s[26:27] offset:256
	s_add_u32 s26, s16, 0x160000
	s_addc_u32 s27, s17, 0
	global_load_dwordx4 v[208:211], v245, s[26:27]
	global_load_dwordx4 v[212:215], v245, s[26:27] offset:256
	s_and_b64 vcc, exec, s[22:23]
	s_cbranch_vccz .LBB0_2251
	s_barrier
.LBB0_2251:
	s_waitcnt vmcnt(15)
	v_lshlrev_b32_e32 v246, 16, v146
	v_and_b32_e32 v247, 0xffff0000, v146
	v_pk_add_f32 v[126:127], v[126:127], v[246:247]
	v_lshlrev_b32_e32 v246, 16, v147
	v_and_b32_e32 v247, 0xffff0000, v147
	v_pk_add_f32 v[128:129], v[128:129], v[246:247]
	v_lshlrev_b32_e32 v246, 16, v148
	v_and_b32_e32 v247, 0xffff0000, v148
	v_pk_add_f32 v[122:123], v[122:123], v[246:247]
	v_lshlrev_b32_e32 v246, 16, v149
	v_and_b32_e32 v247, 0xffff0000, v149
	v_pk_add_f32 v[124:125], v[124:125], v[246:247]
	v_cvt_pk_bf16_f32 v146, v126, v127
	v_cvt_pk_bf16_f32 v147, v128, v129
	v_cvt_pk_bf16_f32 v148, v122, v123
	v_cvt_pk_bf16_f32 v149, v124, v125
	global_store_dwordx4 v245, v[146:149], s[16:17]
	v_mul_f32_e32 v126, v126, v126
	v_fmac_f32_e32 v126, v127, v127
	v_fmac_f32_e32 v126, v128, v128
	v_fmac_f32_e32 v126, v129, v129
	v_fmac_f32_e32 v126, v122, v122
	v_fmac_f32_e32 v126, v123, v123
	v_fmac_f32_e32 v126, v124, v124
	v_fmac_f32_e32 v126, v125, v125
	s_waitcnt vmcnt(15)
	v_lshlrev_b32_e32 v246, 16, v156
	v_and_b32_e32 v247, 0xffff0000, v156
	v_pk_add_f32 v[118:119], v[118:119], v[246:247]
	v_lshlrev_b32_e32 v246, 16, v157
	v_and_b32_e32 v247, 0xffff0000, v157
	v_pk_add_f32 v[120:121], v[120:121], v[246:247]
	v_lshlrev_b32_e32 v246, 16, v158
	v_and_b32_e32 v247, 0xffff0000, v158
	v_pk_add_f32 v[114:115], v[114:115], v[246:247]
	v_lshlrev_b32_e32 v246, 16, v159
	v_and_b32_e32 v247, 0xffff0000, v159
	v_pk_add_f32 v[116:117], v[116:117], v[246:247]
	v_cvt_pk_bf16_f32 v156, v118, v119
	v_cvt_pk_bf16_f32 v157, v120, v121
	v_cvt_pk_bf16_f32 v158, v114, v115
	v_cvt_pk_bf16_f32 v159, v116, v117
	global_store_dwordx4 v245, v[156:159], s[16:17] offset:256
	v_fmac_f32_e32 v126, v118, v118
	v_fmac_f32_e32 v126, v119, v119
	v_fmac_f32_e32 v126, v120, v120
	v_fmac_f32_e32 v126, v121, v121
	v_fmac_f32_e32 v126, v114, v114
	v_fmac_f32_e32 v126, v115, v115
	v_fmac_f32_e32 v126, v116, v116
	v_fmac_f32_e32 v126, v117, v117
	s_add_u32 s26, s16, 0x20000
	s_addc_u32 s27, s17, 0
	s_waitcnt vmcnt(15)
	v_lshlrev_b32_e32 v246, 16, v160
	v_and_b32_e32 v247, 0xffff0000, v160
	v_pk_add_f32 v[110:111], v[110:111], v[246:247]
	v_lshlrev_b32_e32 v246, 16, v161
	v_and_b32_e32 v247, 0xffff0000, v161
	v_pk_add_f32 v[112:113], v[112:113], v[246:247]
	v_lshlrev_b32_e32 v246, 16, v162
	v_and_b32_e32 v247, 0xffff0000, v162
	v_pk_add_f32 v[106:107], v[106:107], v[246:247]
	v_lshlrev_b32_e32 v246, 16, v163
	v_and_b32_e32 v247, 0xffff0000, v163
	v_pk_add_f32 v[108:109], v[108:109], v[246:247]
	v_cvt_pk_bf16_f32 v160, v110, v111
	v_cvt_pk_bf16_f32 v161, v112, v113
	v_cvt_pk_bf16_f32 v162, v106, v107
	v_cvt_pk_bf16_f32 v163, v108, v109
	global_store_dwordx4 v245, v[160:163], s[26:27]
	v_mul_f32_e32 v110, v110, v110
	v_fmac_f32_e32 v110, v111, v111
	v_fmac_f32_e32 v110, v112, v112
	v_fmac_f32_e32 v110, v113, v113
	v_fmac_f32_e32 v110, v106, v106
	v_fmac_f32_e32 v110, v107, v107
	v_fmac_f32_e32 v110, v108, v108
	v_fmac_f32_e32 v110, v109, v109
	s_waitcnt vmcnt(15)
	v_lshlrev_b32_e32 v246, 16, v164
	v_and_b32_e32 v247, 0xffff0000, v164
	v_pk_add_f32 v[102:103], v[102:103], v[246:247]
	v_lshlrev_b32_e32 v246, 16, v165
	v_and_b32_e32 v247, 0xffff0000, v165
	v_pk_add_f32 v[104:105], v[104:105], v[246:247]
	v_lshlrev_b32_e32 v246, 16, v166
	v_and_b32_e32 v247, 0xffff0000, v166
	v_pk_add_f32 v[98:99], v[98:99], v[246:247]
	v_lshlrev_b32_e32 v246, 16, v167
	v_and_b32_e32 v247, 0xffff0000, v167
	v_pk_add_f32 v[100:101], v[100:101], v[246:247]
	v_cvt_pk_bf16_f32 v164, v102, v103
	v_cvt_pk_bf16_f32 v165, v104, v105
	v_cvt_pk_bf16_f32 v166, v98, v99
	v_cvt_pk_bf16_f32 v167, v100, v101
	global_store_dwordx4 v245, v[164:167], s[26:27] offset:256
	v_fmac_f32_e32 v110, v102, v102
	v_fmac_f32_e32 v110, v103, v103
	v_fmac_f32_e32 v110, v104, v104
	v_fmac_f32_e32 v110, v105, v105
	v_fmac_f32_e32 v110, v98, v98
	v_fmac_f32_e32 v110, v99, v99
	v_fmac_f32_e32 v110, v100, v100
	v_fmac_f32_e32 v110, v101, v101
	s_add_u32 s26, s16, 0x40000
	s_addc_u32 s27, s17, 0
	s_waitcnt vmcnt(15)
	v_lshlrev_b32_e32 v246, 16, v168
	v_and_b32_e32 v247, 0xffff0000, v168
	v_pk_add_f32 v[94:95], v[94:95], v[246:247]
	v_lshlrev_b32_e32 v246, 16, v169
	v_and_b32_e32 v247, 0xffff0000, v169
	v_pk_add_f32 v[96:97], v[96:97], v[246:247]
	v_lshlrev_b32_e32 v246, 16, v170
	v_and_b32_e32 v247, 0xffff0000, v170
	v_pk_add_f32 v[90:91], v[90:91], v[246:247]
	v_lshlrev_b32_e32 v246, 16, v171
	v_and_b32_e32 v247, 0xffff0000, v171
	v_pk_add_f32 v[92:93], v[92:93], v[246:247]
	v_cvt_pk_bf16_f32 v168, v94, v95
	v_cvt_pk_bf16_f32 v169, v96, v97
	v_cvt_pk_bf16_f32 v170, v90, v91
	v_cvt_pk_bf16_f32 v171, v92, v93
	global_store_dwordx4 v245, v[168:171], s[26:27]
	v_mul_f32_e32 v94, v94, v94
	v_fmac_f32_e32 v94, v95, v95
	v_fmac_f32_e32 v94, v96, v96
	v_fmac_f32_e32 v94, v97, v97
	v_fmac_f32_e32 v94, v90, v90
	v_fmac_f32_e32 v94, v91, v91
	v_fmac_f32_e32 v94, v92, v92
	v_fmac_f32_e32 v94, v93, v93
	s_waitcnt vmcnt(15)
	v_lshlrev_b32_e32 v246, 16, v172
	v_and_b32_e32 v247, 0xffff0000, v172
	v_pk_add_f32 v[86:87], v[86:87], v[246:247]
	v_lshlrev_b32_e32 v246, 16, v173
	v_and_b32_e32 v247, 0xffff0000, v173
	v_pk_add_f32 v[88:89], v[88:89], v[246:247]
	v_lshlrev_b32_e32 v246, 16, v174
	v_and_b32_e32 v247, 0xffff0000, v174
	v_pk_add_f32 v[82:83], v[82:83], v[246:247]
	v_lshlrev_b32_e32 v246, 16, v175
	v_and_b32_e32 v247, 0xffff0000, v175
	v_pk_add_f32 v[84:85], v[84:85], v[246:247]
	v_cvt_pk_bf16_f32 v172, v86, v87
	v_cvt_pk_bf16_f32 v173, v88, v89
	v_cvt_pk_bf16_f32 v174, v82, v83
	v_cvt_pk_bf16_f32 v175, v84, v85
	global_store_dwordx4 v245, v[172:175], s[26:27] offset:256
	v_fmac_f32_e32 v94, v86, v86
	v_fmac_f32_e32 v94, v87, v87
	v_fmac_f32_e32 v94, v88, v88
	v_fmac_f32_e32 v94, v89, v89
	v_fmac_f32_e32 v94, v82, v82
	v_fmac_f32_e32 v94, v83, v83
	v_fmac_f32_e32 v94, v84, v84
	v_fmac_f32_e32 v94, v85, v85
	s_add_u32 s26, s16, 0x60000
	s_addc_u32 s27, s17, 0
	s_waitcnt vmcnt(15)
	v_lshlrev_b32_e32 v246, 16, v176
	v_and_b32_e32 v247, 0xffff0000, v176
	v_pk_add_f32 v[78:79], v[78:79], v[246:247]
	v_lshlrev_b32_e32 v246, 16, v177
	v_and_b32_e32 v247, 0xffff0000, v177
	v_pk_add_f32 v[80:81], v[80:81], v[246:247]
	v_lshlrev_b32_e32 v246, 16, v178
	v_and_b32_e32 v247, 0xffff0000, v178
	v_pk_add_f32 v[74:75], v[74:75], v[246:247]
	v_lshlrev_b32_e32 v246, 16, v179
	v_and_b32_e32 v247, 0xffff0000, v179
	v_pk_add_f32 v[76:77], v[76:77], v[246:247]
	v_cvt_pk_bf16_f32 v176, v78, v79
	v_cvt_pk_bf16_f32 v177, v80, v81
	v_cvt_pk_bf16_f32 v178, v74, v75
	v_cvt_pk_bf16_f32 v179, v76, v77
	global_store_dwordx4 v245, v[176:179], s[26:27]
	v_mul_f32_e32 v78, v78, v78
	v_fmac_f32_e32 v78, v79, v79
	v_fmac_f32_e32 v78, v80, v80
	v_fmac_f32_e32 v78, v81, v81
	v_fmac_f32_e32 v78, v74, v74
	v_fmac_f32_e32 v78, v75, v75
	v_fmac_f32_e32 v78, v76, v76
	v_fmac_f32_e32 v78, v77, v77
	s_waitcnt vmcnt(15)
	v_lshlrev_b32_e32 v246, 16, v180
	v_and_b32_e32 v247, 0xffff0000, v180
	v_pk_add_f32 v[70:71], v[70:71], v[246:247]
	v_lshlrev_b32_e32 v246, 16, v181
	v_and_b32_e32 v247, 0xffff0000, v181
	v_pk_add_f32 v[72:73], v[72:73], v[246:247]
	v_lshlrev_b32_e32 v246, 16, v182
	v_and_b32_e32 v247, 0xffff0000, v182
	v_pk_add_f32 v[66:67], v[66:67], v[246:247]
	v_lshlrev_b32_e32 v246, 16, v183
	v_and_b32_e32 v247, 0xffff0000, v183
	v_pk_add_f32 v[68:69], v[68:69], v[246:247]
	v_cvt_pk_bf16_f32 v180, v70, v71
	v_cvt_pk_bf16_f32 v181, v72, v73
	v_cvt_pk_bf16_f32 v182, v66, v67
	v_cvt_pk_bf16_f32 v183, v68, v69
	global_store_dwordx4 v245, v[180:183], s[26:27] offset:256
	v_fmac_f32_e32 v78, v70, v70
	v_fmac_f32_e32 v78, v71, v71
	v_fmac_f32_e32 v78, v72, v72
	v_fmac_f32_e32 v78, v73, v73
	v_fmac_f32_e32 v78, v66, v66
	v_fmac_f32_e32 v78, v67, v67
	v_fmac_f32_e32 v78, v68, v68
	v_fmac_f32_e32 v78, v69, v69
	s_add_u32 s26, s16, 0x100000
	s_addc_u32 s27, s17, 0
	s_waitcnt vmcnt(15)
	v_lshlrev_b32_e32 v246, 16, v184
	v_and_b32_e32 v247, 0xffff0000, v184
	v_pk_add_f32 v[62:63], v[62:63], v[246:247]
	v_lshlrev_b32_e32 v246, 16, v185
	v_and_b32_e32 v247, 0xffff0000, v185
	v_pk_add_f32 v[64:65], v[64:65], v[246:247]
	v_lshlrev_b32_e32 v246, 16, v186
	v_and_b32_e32 v247, 0xffff0000, v186
	v_pk_add_f32 v[58:59], v[58:59], v[246:247]
	v_lshlrev_b32_e32 v246, 16, v187
	v_and_b32_e32 v247, 0xffff0000, v187
	v_pk_add_f32 v[60:61], v[60:61], v[246:247]
	v_cvt_pk_bf16_f32 v184, v62, v63
	v_cvt_pk_bf16_f32 v185, v64, v65
	v_cvt_pk_bf16_f32 v186, v58, v59
	v_cvt_pk_bf16_f32 v187, v60, v61
	global_store_dwordx4 v245, v[184:187], s[26:27]
	v_mul_f32_e32 v62, v62, v62
	v_fmac_f32_e32 v62, v63, v63
	v_fmac_f32_e32 v62, v64, v64
	v_fmac_f32_e32 v62, v65, v65
	v_fmac_f32_e32 v62, v58, v58
	v_fmac_f32_e32 v62, v59, v59
	v_fmac_f32_e32 v62, v60, v60
	v_fmac_f32_e32 v62, v61, v61
	s_waitcnt vmcnt(15)
	v_lshlrev_b32_e32 v246, 16, v188
	v_and_b32_e32 v247, 0xffff0000, v188
	v_pk_add_f32 v[54:55], v[54:55], v[246:247]
	v_lshlrev_b32_e32 v246, 16, v189
	v_and_b32_e32 v247, 0xffff0000, v189
	v_pk_add_f32 v[56:57], v[56:57], v[246:247]
	v_lshlrev_b32_e32 v246, 16, v190
	v_and_b32_e32 v247, 0xffff0000, v190
	v_pk_add_f32 v[50:51], v[50:51], v[246:247]
	v_lshlrev_b32_e32 v246, 16, v191
	v_and_b32_e32 v247, 0xffff0000, v191
	v_pk_add_f32 v[52:53], v[52:53], v[246:247]
	v_cvt_pk_bf16_f32 v188, v54, v55
	v_cvt_pk_bf16_f32 v189, v56, v57
	v_cvt_pk_bf16_f32 v190, v50, v51
	v_cvt_pk_bf16_f32 v191, v52, v53
	global_store_dwordx4 v245, v[188:191], s[26:27] offset:256
	v_fmac_f32_e32 v62, v54, v54
	v_fmac_f32_e32 v62, v55, v55
	v_fmac_f32_e32 v62, v56, v56
	v_fmac_f32_e32 v62, v57, v57
	v_fmac_f32_e32 v62, v50, v50
	v_fmac_f32_e32 v62, v51, v51
	v_fmac_f32_e32 v62, v52, v52
	v_fmac_f32_e32 v62, v53, v53
	s_add_u32 s26, s16, 0x120000
	s_addc_u32 s27, s17, 0
	s_waitcnt vmcnt(15)
	v_lshlrev_b32_e32 v246, 16, v192
	v_and_b32_e32 v247, 0xffff0000, v192
	v_pk_add_f32 v[46:47], v[46:47], v[246:247]
	v_lshlrev_b32_e32 v246, 16, v193
	v_and_b32_e32 v247, 0xffff0000, v193
	v_pk_add_f32 v[48:49], v[48:49], v[246:247]
	v_lshlrev_b32_e32 v246, 16, v194
	v_and_b32_e32 v247, 0xffff0000, v194
	v_pk_add_f32 v[42:43], v[42:43], v[246:247]
	v_lshlrev_b32_e32 v246, 16, v195
	v_and_b32_e32 v247, 0xffff0000, v195
	v_pk_add_f32 v[44:45], v[44:45], v[246:247]
	v_cvt_pk_bf16_f32 v192, v46, v47
	v_cvt_pk_bf16_f32 v193, v48, v49
	v_cvt_pk_bf16_f32 v194, v42, v43
	v_cvt_pk_bf16_f32 v195, v44, v45
	global_store_dwordx4 v245, v[192:195], s[26:27]
	v_mul_f32_e32 v46, v46, v46
	v_fmac_f32_e32 v46, v47, v47
	v_fmac_f32_e32 v46, v48, v48
	v_fmac_f32_e32 v46, v49, v49
	v_fmac_f32_e32 v46, v42, v42
	v_fmac_f32_e32 v46, v43, v43
	v_fmac_f32_e32 v46, v44, v44
	v_fmac_f32_e32 v46, v45, v45
	s_waitcnt vmcnt(15)
	v_lshlrev_b32_e32 v246, 16, v196
	v_and_b32_e32 v247, 0xffff0000, v196
	v_pk_add_f32 v[38:39], v[38:39], v[246:247]
	v_lshlrev_b32_e32 v246, 16, v197
	v_and_b32_e32 v247, 0xffff0000, v197
	v_pk_add_f32 v[40:41], v[40:41], v[246:247]
	v_lshlrev_b32_e32 v246, 16, v198
	v_and_b32_e32 v247, 0xffff0000, v198
	v_pk_add_f32 v[34:35], v[34:35], v[246:247]
	v_lshlrev_b32_e32 v246, 16, v199
	v_and_b32_e32 v247, 0xffff0000, v199
	v_pk_add_f32 v[36:37], v[36:37], v[246:247]
	v_cvt_pk_bf16_f32 v196, v38, v39
	v_cvt_pk_bf16_f32 v197, v40, v41
	v_cvt_pk_bf16_f32 v198, v34, v35
	v_cvt_pk_bf16_f32 v199, v36, v37
	global_store_dwordx4 v245, v[196:199], s[26:27] offset:256
	v_fmac_f32_e32 v46, v38, v38
	v_fmac_f32_e32 v46, v39, v39
	v_fmac_f32_e32 v46, v40, v40
	v_fmac_f32_e32 v46, v41, v41
	v_fmac_f32_e32 v46, v34, v34
	v_fmac_f32_e32 v46, v35, v35
	v_fmac_f32_e32 v46, v36, v36
	v_fmac_f32_e32 v46, v37, v37
	s_add_u32 s26, s16, 0x140000
	s_addc_u32 s27, s17, 0
	s_waitcnt vmcnt(15)
	v_lshlrev_b32_e32 v246, 16, v200
	v_and_b32_e32 v247, 0xffff0000, v200
	v_pk_add_f32 v[30:31], v[30:31], v[246:247]
	v_lshlrev_b32_e32 v246, 16, v201
	v_and_b32_e32 v247, 0xffff0000, v201
	v_pk_add_f32 v[32:33], v[32:33], v[246:247]
	v_lshlrev_b32_e32 v246, 16, v202
	v_and_b32_e32 v247, 0xffff0000, v202
	v_pk_add_f32 v[26:27], v[26:27], v[246:247]
	v_lshlrev_b32_e32 v246, 16, v203
	v_and_b32_e32 v247, 0xffff0000, v203
	v_pk_add_f32 v[28:29], v[28:29], v[246:247]
	v_cvt_pk_bf16_f32 v200, v30, v31
	v_cvt_pk_bf16_f32 v201, v32, v33
	v_cvt_pk_bf16_f32 v202, v26, v27
	v_cvt_pk_bf16_f32 v203, v28, v29
	global_store_dwordx4 v245, v[200:203], s[26:27]
	v_mul_f32_e32 v30, v30, v30
	v_fmac_f32_e32 v30, v31, v31
	v_fmac_f32_e32 v30, v32, v32
	v_fmac_f32_e32 v30, v33, v33
	v_fmac_f32_e32 v30, v26, v26
	v_fmac_f32_e32 v30, v27, v27
	v_fmac_f32_e32 v30, v28, v28
	v_fmac_f32_e32 v30, v29, v29
	s_waitcnt vmcnt(15)
	v_lshlrev_b32_e32 v246, 16, v204
	v_and_b32_e32 v247, 0xffff0000, v204
	v_pk_add_f32 v[22:23], v[22:23], v[246:247]
	v_lshlrev_b32_e32 v246, 16, v205
	v_and_b32_e32 v247, 0xffff0000, v205
	v_pk_add_f32 v[24:25], v[24:25], v[246:247]
	v_lshlrev_b32_e32 v246, 16, v206
	v_and_b32_e32 v247, 0xffff0000, v206
	v_pk_add_f32 v[18:19], v[18:19], v[246:247]
	v_lshlrev_b32_e32 v246, 16, v207
	v_and_b32_e32 v247, 0xffff0000, v207
	v_pk_add_f32 v[20:21], v[20:21], v[246:247]
	v_cvt_pk_bf16_f32 v204, v22, v23
	v_cvt_pk_bf16_f32 v205, v24, v25
	v_cvt_pk_bf16_f32 v206, v18, v19
	v_cvt_pk_bf16_f32 v207, v20, v21
	global_store_dwordx4 v245, v[204:207], s[26:27] offset:256
	v_fmac_f32_e32 v30, v22, v22
	v_fmac_f32_e32 v30, v23, v23
	v_fmac_f32_e32 v30, v24, v24
	v_fmac_f32_e32 v30, v25, v25
	v_fmac_f32_e32 v30, v18, v18
	v_fmac_f32_e32 v30, v19, v19
	v_fmac_f32_e32 v30, v20, v20
	v_fmac_f32_e32 v30, v21, v21
	s_add_u32 s26, s16, 0x160000
	s_addc_u32 s27, s17, 0
	s_waitcnt vmcnt(15)
	v_lshlrev_b32_e32 v246, 16, v208
	v_and_b32_e32 v247, 0xffff0000, v208
	v_pk_add_f32 v[14:15], v[14:15], v[246:247]
	v_lshlrev_b32_e32 v246, 16, v209
	v_and_b32_e32 v247, 0xffff0000, v209
	v_pk_add_f32 v[16:17], v[16:17], v[246:247]
	v_lshlrev_b32_e32 v246, 16, v210
	v_and_b32_e32 v247, 0xffff0000, v210
	v_pk_add_f32 v[10:11], v[10:11], v[246:247]
	v_lshlrev_b32_e32 v246, 16, v211
	v_and_b32_e32 v247, 0xffff0000, v211
	v_pk_add_f32 v[12:13], v[12:13], v[246:247]
	v_cvt_pk_bf16_f32 v208, v14, v15
	v_cvt_pk_bf16_f32 v209, v16, v17
	v_cvt_pk_bf16_f32 v210, v10, v11
	v_cvt_pk_bf16_f32 v211, v12, v13
	global_store_dwordx4 v245, v[208:211], s[26:27]
	v_mul_f32_e32 v14, v14, v14
	v_fmac_f32_e32 v14, v15, v15
	v_fmac_f32_e32 v14, v16, v16
	v_fmac_f32_e32 v14, v17, v17
	v_fmac_f32_e32 v14, v10, v10
	v_fmac_f32_e32 v14, v11, v11
	v_fmac_f32_e32 v14, v12, v12
	v_fmac_f32_e32 v14, v13, v13
	s_waitcnt vmcnt(15)
	v_lshlrev_b32_e32 v246, 16, v212
	v_and_b32_e32 v247, 0xffff0000, v212
	v_pk_add_f32 v[6:7], v[6:7], v[246:247]
	v_lshlrev_b32_e32 v246, 16, v213
	v_and_b32_e32 v247, 0xffff0000, v213
	v_pk_add_f32 v[8:9], v[8:9], v[246:247]
	v_lshlrev_b32_e32 v246, 16, v214
	v_and_b32_e32 v247, 0xffff0000, v214
	v_pk_add_f32 v[2:3], v[2:3], v[246:247]
	v_lshlrev_b32_e32 v246, 16, v215
	v_and_b32_e32 v247, 0xffff0000, v215
	v_pk_add_f32 v[4:5], v[4:5], v[246:247]
	v_cvt_pk_bf16_f32 v212, v6, v7
	v_cvt_pk_bf16_f32 v213, v8, v9
	v_cvt_pk_bf16_f32 v214, v2, v3
	v_cvt_pk_bf16_f32 v215, v4, v5
	global_store_dwordx4 v245, v[212:215], s[26:27] offset:256
	v_fmac_f32_e32 v14, v6, v6
	v_fmac_f32_e32 v14, v7, v7
	v_fmac_f32_e32 v14, v8, v8
	v_fmac_f32_e32 v14, v9, v9
	v_fmac_f32_e32 v14, v2, v2
	v_fmac_f32_e32 v14, v3, v3
	v_fmac_f32_e32 v14, v4, v4
	v_fmac_f32_e32 v14, v5, v5
	v_mbcnt_lo_u32_b32 v246, -1, 0
	v_mbcnt_hi_u32_b32 v246, -1, v246
	v_xor_b32_e32 v247, 32, v246
	v_xor_b32_e32 v246, 16, v246
	v_lshlrev_b32_e32 v246, 2, v246
	v_lshlrev_b32_e32 v247, 2, v247
	ds_bpermute_b32 v127, v246, v126
	ds_bpermute_b32 v111, v246, v110
	ds_bpermute_b32 v95, v246, v94
	ds_bpermute_b32 v79, v246, v78
	ds_bpermute_b32 v63, v246, v62
	ds_bpermute_b32 v47, v246, v46
	ds_bpermute_b32 v31, v246, v30
	ds_bpermute_b32 v15, v246, v14
	s_waitcnt lgkmcnt(0)
	v_add_f32_e32 v126, v126, v127
	v_add_f32_e32 v110, v110, v111
	v_add_f32_e32 v94, v94, v95
	v_add_f32_e32 v78, v78, v79
	v_add_f32_e32 v62, v62, v63
	v_add_f32_e32 v46, v46, v47
	v_add_f32_e32 v30, v30, v31
	v_add_f32_e32 v14, v14, v15
	ds_bpermute_b32 v127, v247, v126
	ds_bpermute_b32 v111, v247, v110
	ds_bpermute_b32 v95, v247, v94
	ds_bpermute_b32 v79, v247, v78
	ds_bpermute_b32 v63, v247, v62
	ds_bpermute_b32 v47, v247, v46
	ds_bpermute_b32 v31, v247, v30
	ds_bpermute_b32 v15, v247, v14
	s_waitcnt lgkmcnt(0)
	v_add_f32_e32 v126, v126, v127
	v_add_f32_e32 v110, v110, v111
	v_add_f32_e32 v94, v94, v95
	v_add_f32_e32 v78, v78, v79
	v_add_f32_e32 v62, v62, v63
	v_add_f32_e32 v46, v46, v47
	v_add_f32_e32 v30, v30, v31
	v_add_f32_e32 v14, v14, v15
	v_lshl_add_u32 v246, s60, 8, v1
	v_lshlrev_b32_e32 v246, 2, v246
	s_and_saveexec_b64 s[26:27], s[6:7]
	global_atomic_add_f32 v246, v126, s[18:19]
	global_atomic_add_f32 v246, v110, s[18:19] offset:64
	global_atomic_add_f32 v246, v94, s[18:19] offset:128
	global_atomic_add_f32 v246, v78, s[18:19] offset:192
	global_atomic_add_f32 v246, v62, s[18:19] offset:512
	global_atomic_add_f32 v246, v46, s[18:19] offset:576
	global_atomic_add_f32 v246, v30, s[18:19] offset:640
	global_atomic_add_f32 v246, v14, s[18:19] offset:704
	s_mov_b64 exec, s[26:27]
	s_and_b64 vcc, exec, s[8:9]
	s_mov_b64 s[8:9], -1
	s_cbranch_vccnz .LBB0_2236
	s_andn2_b64 vcc, exec, s[14:15]
	s_cbranch_vccnz .LBB0_2235
	s_barrier
	s_branch .LBB0_2235

	.amdhsa_kernel _Z6mk_fwd4Args
		.amdhsa_group_segment_fixed_size 0
		.amdhsa_private_segment_fixed_size 0
		.amdhsa_kernarg_size 488
		.amdhsa_user_sgpr_count 2
		.amdhsa_user_sgpr_dispatch_ptr 0
		.amdhsa_user_sgpr_queue_ptr 0
		.amdhsa_user_sgpr_kernarg_segment_ptr 1
		.amdhsa_user_sgpr_dispatch_id 0
		.amdhsa_user_sgpr_kernarg_preload_length 0
		.amdhsa_user_sgpr_kernarg_preload_offset 0
		.amdhsa_user_sgpr_private_segment_size 0
		.amdhsa_uses_dynamic_stack 0
		.amdhsa_enable_private_segment 0
		.amdhsa_system_sgpr_workgroup_id_x 1
		.amdhsa_system_sgpr_workgroup_id_y 0
		.amdhsa_system_sgpr_workgroup_id_z 0
		.amdhsa_system_sgpr_workgroup_info 0
		.amdhsa_system_vgpr_workitem_id 0
		.amdhsa_next_free_vgpr 248
		.amdhsa_next_free_sgpr 98
		.amdhsa_accum_offset 248
		.amdhsa_reserve_vcc 1
		.amdhsa_float_round_mode_32 0
		.amdhsa_float_round_mode_16_64 0
		.amdhsa_float_denorm_mode_32 3
		.amdhsa_float_denorm_mode_16_64 3
		.amdhsa_dx10_clamp 1
		.amdhsa_ieee_mode 1
		.amdhsa_fp16_overflow 0
		.amdhsa_tg_split 0
		.amdhsa_exception_fp_ieee_invalid_op 0
		.amdhsa_exception_fp_denorm_src 0
		.amdhsa_exception_fp_ieee_div_zero 0
		.amdhsa_exception_fp_ieee_overflow 0
		.amdhsa_exception_fp_ieee_underflow 0
		.amdhsa_exception_fp_ieee_inexact 0
		.amdhsa_exception_int_div_zero 0
	.end_amdhsa_kernel

amdhsa.kernels:
  - .agpr_count:     0
    .args:
      - .offset:         0
        .size:           232
        .value_kind:     by_value
      - .offset:         232
        .size:           4
        .value_kind:     hidden_block_count_x
      - .offset:         236
        .size:           4
        .value_kind:     hidden_block_count_y
      - .offset:         240
        .size:           4
        .value_kind:     hidden_block_count_z
      - .offset:         244
        .size:           2
        .value_kind:     hidden_group_size_x
      - .offset:         246
        .size:           2
        .value_kind:     hidden_group_size_y
      - .offset:         248
        .size:           2
        .value_kind:     hidden_group_size_z
      - .offset:         250
        .size:           2
        .value_kind:     hidden_remainder_x
      - .offset:         252
        .size:           2
        .value_kind:     hidden_remainder_y
      - .offset:         254
        .size:           2
        .value_kind:     hidden_remainder_z
      - .offset:         272
        .size:           8
        .value_kind:     hidden_global_offset_x
      - .offset:         280
        .size:           8
        .value_kind:     hidden_global_offset_y
      - .offset:         288
        .size:           8
        .value_kind:     hidden_global_offset_z
      - .offset:         296
        .size:           2
        .value_kind:     hidden_grid_dims
      - .offset:         352
        .size:           4
        .value_kind:     hidden_dynamic_lds_size
    .group_segment_fixed_size: 0
    .kernarg_segment_align: 8
    .kernarg_segment_size: 488
    .language:       OpenCL C
    .language_version:
      - 2
      - 0
    .max_flat_workgroup_size: 512
    .name:           _Z6mk_fwd4Args
    .private_segment_fixed_size: 0
    .sgpr_count:     104
    .sgpr_spill_count: 21
    .symbol:         _Z6mk_fwd4Args.kd
    .uniform_work_group_size: 1
    .uses_dynamic_stack: false
    .vgpr_count:     248
    .vgpr_spill_count: 0
    .wavefront_size: 64
